# GEMM K-loops: MFMA clusters run at s_setprio 3 (was 1) and the mid-cluster priority drop/raise pair is removed
# baseline (speedup 1.0000x reference)
.LBB0_675:
	s_ashr_i32 s21, s20, 31
	s_lshl_b64 s[8:9], s[20:21], 19
	s_add_u32 s26, s36, s8
	s_addc_u32 s27, s37, s9
	s_and_b64 s[8:9], s[6:7], exec
	s_cselect_b32 s21, s27, s69
	s_cselect_b32 s31, s26, s68
	s_ashr_i32 s11, s10, 31
	s_lshl_b64 s[8:9], s[10:11], 19
	s_add_u32 s52, s40, s8
	s_addc_u32 s53, s60, s9
	s_and_b64 s[8:9], s[6:7], exec
	s_cselect_b32 s11, s53, s57
	s_cselect_b32 s82, s52, s56
	s_add_u32 s8, s68, 0x40080
	s_addc_u32 s9, s69, 0
	s_add_u32 s83, s56, 0x100
	s_addc_u32 s84, s57, 0
	s_mov_b32 s85, -2
	s_add_u32 s56, s8, 0xfffc0080
	s_addc_u32 s57, s9, -1
	s_add_i32 s64, 0, 0x10000
	s_cmp_eq_u32 s85, 12
	s_cselect_b32 s69, s21, s57
	s_cselect_b32 s68, s31, s56
	v_add_u32_e32 v160, s64, v163
	s_cselect_b32 s57, s11, s84
	s_cselect_b32 s56, s82, s83
	s_add_i32 s86, 0, 0x14000
	ds_read_b128 v[148:151], v160
	ds_read_b128 v[152:155], v160 offset:1024
	ds_read_b128 v[156:159], v160 offset:2048
	ds_read_b128 v[166:169], v160 offset:3072
	v_add_u32_e32 v160, s86, v163
	ds_read_b128 v[170:173], v160
	ds_read_b128 v[174:177], v160 offset:1024
	ds_read_b128 v[178:181], v160 offset:2048
	ds_read_b128 v[182:185], v160 offset:3072
	v_lshl_add_u64 v[160:161], s[8:9], 0, v[144:145]
	s_add_i32 m0, s72, 0xc000
	ds_read_b128 v[186:189], v165
	ds_read_b128 v[190:193], v165 offset:1024
	ds_read_b128 v[194:197], v165 offset:2048
	ds_read_b128 v[198:201], v165 offset:3072
	ds_read_b128 v[202:205], v165 offset:4096
	ds_read_b128 v[206:209], v165 offset:5120
	ds_read_b128 v[222:225], v165 offset:6144
	ds_read_b128 v[226:229], v165 offset:7168
	global_load_lds_dwordx4 v[160:161], off
	v_lshl_add_u64 v[160:161], s[8:9], 0, v[146:147]
	s_add_i32 m0, s72, 0xe000
	s_nop 0
	global_load_lds_dwordx4 v[160:161], off
	s_waitcnt vmcnt(8)
	s_waitcnt lgkmcnt(0)
	s_barrier
	s_setprio 3
	s_waitcnt lgkmcnt(0)
	v_mfma_f32_16x16x32_bf16 v[70:73], v[148:151], v[186:189], 0
	v_mfma_f32_16x16x32_bf16 v[66:69], v[156:159], v[186:189], 0
	v_mfma_f32_16x16x32_bf16 v[54:57], v[148:151], v[194:197], 0
	v_mfma_f32_16x16x32_bf16 v[50:53], v[156:159], v[194:197], 0
	v_mfma_f32_16x16x32_bf16 v[46:49], v[148:151], v[202:205], 0
	v_mfma_f32_16x16x32_bf16 v[42:45], v[156:159], v[202:205], 0
	v_mfma_f32_16x16x32_bf16 v[38:41], v[148:151], v[222:225], 0
	v_mfma_f32_16x16x32_bf16 v[34:37], v[156:159], v[222:225], 0
	v_mfma_f32_16x16x32_bf16 v[70:73], v[152:155], v[190:193], v[70:73]
	v_mfma_f32_16x16x32_bf16 v[66:69], v[166:169], v[190:193], v[66:69]
	v_mfma_f32_16x16x32_bf16 v[54:57], v[152:155], v[198:201], v[54:57]
	v_mfma_f32_16x16x32_bf16 v[50:53], v[166:169], v[198:201], v[50:53]
	v_mfma_f32_16x16x32_bf16 v[46:49], v[152:155], v[206:209], v[46:49]
	v_mfma_f32_16x16x32_bf16 v[42:45], v[166:169], v[206:209], v[42:45]
	v_mfma_f32_16x16x32_bf16 v[38:41], v[152:155], v[226:229], v[38:41]
	v_mfma_f32_16x16x32_bf16 v[34:37], v[166:169], v[226:229], v[34:37]
	v_mfma_f32_16x16x32_bf16 v[126:129], v[170:173], v[186:189], 0
	v_mfma_f32_16x16x32_bf16 v[122:125], v[178:181], v[186:189], 0
	v_mfma_f32_16x16x32_bf16 v[118:121], v[170:173], v[194:197], 0
	v_mfma_f32_16x16x32_bf16 v[114:117], v[178:181], v[194:197], 0
	v_mfma_f32_16x16x32_bf16 v[110:113], v[170:173], v[202:205], 0
	v_mfma_f32_16x16x32_bf16 v[106:109], v[178:181], v[202:205], 0
	v_mfma_f32_16x16x32_bf16 v[102:105], v[170:173], v[222:225], 0
	v_mfma_f32_16x16x32_bf16 v[98:101], v[178:181], v[222:225], 0
	v_mfma_f32_16x16x32_bf16 v[126:129], v[174:177], v[190:193], v[126:129]
	v_mfma_f32_16x16x32_bf16 v[122:125], v[182:185], v[190:193], v[122:125]
	v_mfma_f32_16x16x32_bf16 v[118:121], v[174:177], v[198:201], v[118:121]
	v_mfma_f32_16x16x32_bf16 v[114:117], v[182:185], v[198:201], v[114:117]
	v_mfma_f32_16x16x32_bf16 v[110:113], v[174:177], v[206:209], v[110:113]
	v_mfma_f32_16x16x32_bf16 v[106:109], v[182:185], v[206:209], v[106:109]
	v_mfma_f32_16x16x32_bf16 v[102:105], v[174:177], v[226:229], v[102:105]
	v_mfma_f32_16x16x32_bf16 v[98:101], v[182:185], v[226:229], v[98:101]
	s_setprio 0
	s_barrier
	s_add_i32 s64, s64, s63
	v_lshl_add_u64 v[160:161], s[56:57], 0, v[0:1]
	s_mov_b32 m0, s64
	ds_read_b128 v[186:189], v165 offset:16384
	ds_read_b128 v[190:193], v165 offset:17408
	ds_read_b128 v[194:197], v165 offset:18432
	ds_read_b128 v[198:201], v165 offset:19456
	ds_read_b128 v[202:205], v165 offset:20480
	ds_read_b128 v[206:209], v165 offset:21504
	ds_read_b128 v[222:225], v165 offset:22528
	ds_read_b128 v[226:229], v165 offset:23552
	global_load_lds_dwordx4 v[160:161], off
	s_add_i32 m0, s64, 0x2000
	s_add_u32 s64, s56, 0x40000
	v_lshl_add_u64 v[210:211], s[56:57], 0, v[134:135]
	s_addc_u32 s65, s57, 0
	s_add_i32 s86, s86, s63
	global_load_lds_dwordx4 v[210:211], off
	v_lshl_add_u64 v[230:231], s[64:65], 0, v[0:1]
	s_mov_b32 m0, s86
	v_lshl_add_u64 v[232:233], s[68:69], 0, v[136:137]
	global_load_lds_dwordx4 v[230:231], off
	v_lshl_add_u64 v[230:231], s[64:65], 0, v[134:135]
	s_add_i32 m0, s86, 0x2000
	s_nop 0
	global_load_lds_dwordx4 v[230:231], off
	v_lshl_add_u64 v[230:231], s[68:69], 0, v[138:139]
	s_mov_b32 m0, s72
	s_nop 0
	global_load_lds_dwordx4 v[230:231], off
	s_mov_b32 m0, s73
	s_nop 0
	global_load_lds_dwordx4 v[232:233], off
	s_waitcnt vmcnt(8)
	s_waitcnt lgkmcnt(0)
	s_barrier
	s_setprio 3
	s_waitcnt lgkmcnt(0)
	v_mfma_f32_16x16x32_bf16 v[30:33], v[148:151], v[186:189], 0
	v_mfma_f32_16x16x32_bf16 v[26:29], v[156:159], v[186:189], 0
	v_mfma_f32_16x16x32_bf16 v[22:25], v[148:151], v[194:197], 0
	v_mfma_f32_16x16x32_bf16 v[18:21], v[156:159], v[194:197], 0
	v_mfma_f32_16x16x32_bf16 v[14:17], v[148:151], v[202:205], 0
	v_mfma_f32_16x16x32_bf16 v[10:13], v[156:159], v[202:205], 0
	v_mfma_f32_16x16x32_bf16 v[6:9], v[148:151], v[222:225], 0
	v_mfma_f32_16x16x32_bf16 v[2:5], v[156:159], v[222:225], 0
	v_mfma_f32_16x16x32_bf16 v[30:33], v[152:155], v[190:193], v[30:33]
	v_mfma_f32_16x16x32_bf16 v[26:29], v[166:169], v[190:193], v[26:29]
	v_mfma_f32_16x16x32_bf16 v[22:25], v[152:155], v[198:201], v[22:25]
	v_mfma_f32_16x16x32_bf16 v[18:21], v[166:169], v[198:201], v[18:21]
	v_mfma_f32_16x16x32_bf16 v[14:17], v[152:155], v[206:209], v[14:17]
	v_mfma_f32_16x16x32_bf16 v[10:13], v[166:169], v[206:209], v[10:13]
	v_mfma_f32_16x16x32_bf16 v[6:9], v[152:155], v[226:229], v[6:9]
	v_mfma_f32_16x16x32_bf16 v[2:5], v[166:169], v[226:229], v[2:5]
	v_mfma_f32_16x16x32_bf16 v[94:97], v[170:173], v[186:189], 0
	v_mfma_f32_16x16x32_bf16 v[90:93], v[178:181], v[186:189], 0
	v_mfma_f32_16x16x32_bf16 v[86:89], v[170:173], v[194:197], 0
	v_mfma_f32_16x16x32_bf16 v[82:85], v[178:181], v[194:197], 0
	v_mfma_f32_16x16x32_bf16 v[78:81], v[170:173], v[202:205], 0
	v_mfma_f32_16x16x32_bf16 v[74:77], v[178:181], v[202:205], 0
	v_mfma_f32_16x16x32_bf16 v[62:65], v[170:173], v[222:225], 0
	v_mfma_f32_16x16x32_bf16 v[58:61], v[178:181], v[222:225], 0
	v_mfma_f32_16x16x32_bf16 v[94:97], v[174:177], v[190:193], v[94:97]
	v_mfma_f32_16x16x32_bf16 v[90:93], v[182:185], v[190:193], v[90:93]
	v_mfma_f32_16x16x32_bf16 v[86:89], v[174:177], v[198:201], v[86:89]
	v_mfma_f32_16x16x32_bf16 v[82:85], v[182:185], v[198:201], v[82:85]
	v_mfma_f32_16x16x32_bf16 v[78:81], v[174:177], v[206:209], v[78:81]
	v_mfma_f32_16x16x32_bf16 v[74:77], v[182:185], v[206:209], v[74:77]
	v_mfma_f32_16x16x32_bf16 v[62:65], v[174:177], v[226:229], v[62:65]
	v_mfma_f32_16x16x32_bf16 v[58:61], v[182:185], v[226:229], v[58:61]
	s_setprio 0
	s_barrier
	s_add_i32 s86, 0, 0x18000
	s_add_i32 s87, 0, 0x1c000
	v_add_u32_e32 v166, s86, v163
	v_add_u32_e32 v182, s87, v163
	ds_read_b128 v[148:151], v166
	ds_read_b128 v[152:155], v166 offset:1024
	ds_read_b128 v[156:159], v166 offset:2048
	ds_read_b128 v[166:169], v166 offset:3072
	ds_read_b128 v[170:173], v182
	ds_read_b128 v[174:177], v182 offset:1024
	ds_read_b128 v[178:181], v182 offset:2048
	ds_read_b128 v[182:185], v182 offset:3072
	s_add_u32 s64, s68, 0x40000
	s_addc_u32 s65, s69, 0
	s_mov_b32 m0, s74
	v_lshl_add_u64 v[234:235], s[64:65], 0, v[138:139]
	ds_read_b128 v[186:189], v165 offset:32768
	ds_read_b128 v[190:193], v165 offset:33792
	ds_read_b128 v[194:197], v165 offset:34816
	ds_read_b128 v[198:201], v165 offset:35840
	ds_read_b128 v[202:205], v165 offset:36864
	ds_read_b128 v[206:209], v165 offset:37888
	ds_read_b128 v[222:225], v165 offset:38912
	ds_read_b128 v[226:229], v165 offset:39936
	global_load_lds_dwordx4 v[234:235], off
	v_lshl_add_u64 v[234:235], s[64:65], 0, v[136:137]
	s_mov_b32 m0, s75
	s_nop 0
	global_load_lds_dwordx4 v[234:235], off
	s_waitcnt vmcnt(8)
	s_waitcnt lgkmcnt(0)
	s_barrier
	s_setprio 3
	s_waitcnt lgkmcnt(0)
	v_mfma_f32_16x16x32_bf16 v[70:73], v[148:151], v[186:189], v[70:73]
	v_mfma_f32_16x16x32_bf16 v[66:69], v[156:159], v[186:189], v[66:69]
	v_mfma_f32_16x16x32_bf16 v[54:57], v[148:151], v[194:197], v[54:57]
	v_mfma_f32_16x16x32_bf16 v[50:53], v[156:159], v[194:197], v[50:53]
	v_mfma_f32_16x16x32_bf16 v[46:49], v[148:151], v[202:205], v[46:49]
	v_mfma_f32_16x16x32_bf16 v[42:45], v[156:159], v[202:205], v[42:45]
	v_mfma_f32_16x16x32_bf16 v[38:41], v[148:151], v[222:225], v[38:41]
	v_mfma_f32_16x16x32_bf16 v[34:37], v[156:159], v[222:225], v[34:37]
	v_mfma_f32_16x16x32_bf16 v[70:73], v[152:155], v[190:193], v[70:73]
	v_mfma_f32_16x16x32_bf16 v[66:69], v[166:169], v[190:193], v[66:69]
	v_mfma_f32_16x16x32_bf16 v[54:57], v[152:155], v[198:201], v[54:57]
	v_mfma_f32_16x16x32_bf16 v[50:53], v[166:169], v[198:201], v[50:53]
	v_mfma_f32_16x16x32_bf16 v[46:49], v[152:155], v[206:209], v[46:49]
	v_mfma_f32_16x16x32_bf16 v[42:45], v[166:169], v[206:209], v[42:45]
	v_mfma_f32_16x16x32_bf16 v[38:41], v[152:155], v[226:229], v[38:41]
	v_mfma_f32_16x16x32_bf16 v[34:37], v[166:169], v[226:229], v[34:37]
	v_mfma_f32_16x16x32_bf16 v[126:129], v[170:173], v[186:189], v[126:129]
	v_mfma_f32_16x16x32_bf16 v[122:125], v[178:181], v[186:189], v[122:125]
	v_mfma_f32_16x16x32_bf16 v[118:121], v[170:173], v[194:197], v[118:121]
	v_mfma_f32_16x16x32_bf16 v[114:117], v[178:181], v[194:197], v[114:117]
	v_mfma_f32_16x16x32_bf16 v[110:113], v[170:173], v[202:205], v[110:113]
	v_mfma_f32_16x16x32_bf16 v[106:109], v[178:181], v[202:205], v[106:109]
	v_mfma_f32_16x16x32_bf16 v[102:105], v[170:173], v[222:225], v[102:105]
	v_mfma_f32_16x16x32_bf16 v[98:101], v[178:181], v[222:225], v[98:101]
	v_mfma_f32_16x16x32_bf16 v[126:129], v[174:177], v[190:193], v[126:129]
	v_mfma_f32_16x16x32_bf16 v[122:125], v[182:185], v[190:193], v[122:125]
	v_mfma_f32_16x16x32_bf16 v[118:121], v[174:177], v[198:201], v[118:121]
	v_mfma_f32_16x16x32_bf16 v[114:117], v[182:185], v[198:201], v[114:117]
	v_mfma_f32_16x16x32_bf16 v[110:113], v[174:177], v[206:209], v[110:113]
	v_mfma_f32_16x16x32_bf16 v[106:109], v[182:185], v[206:209], v[106:109]
	v_mfma_f32_16x16x32_bf16 v[102:105], v[174:177], v[226:229], v[102:105]
	v_mfma_f32_16x16x32_bf16 v[98:101], v[182:185], v[226:229], v[98:101]
	s_setprio 0
	s_barrier
	s_add_i32 s64, s86, s63
	v_lshl_add_u64 v[160:161], v[160:161], 0, s[48:49]
	s_mov_b32 m0, s64
	ds_read_b128 v[186:189], v165 offset:49152
	ds_read_b128 v[190:193], v165 offset:50176
	ds_read_b128 v[194:197], v165 offset:51200
	ds_read_b128 v[198:201], v165 offset:52224
	ds_read_b128 v[202:205], v165 offset:53248
	ds_read_b128 v[206:209], v165 offset:54272
	ds_read_b128 v[222:225], v165 offset:55296
	ds_read_b128 v[226:229], v165 offset:56320
	global_load_lds_dwordx4 v[160:161], off
	s_add_i32 m0, s64, 0x2000
	s_add_u32 s56, s56, 0x40080
	v_lshl_add_u64 v[160:161], v[210:211], 0, s[48:49]
	s_addc_u32 s57, s57, 0
	s_add_i32 s64, s87, s63
	global_load_lds_dwordx4 v[160:161], off
	v_lshl_add_u64 v[160:161], s[56:57], 0, v[0:1]
	s_mov_b32 m0, s64
	s_nop 0
	global_load_lds_dwordx4 v[160:161], off
	v_lshl_add_u64 v[160:161], s[56:57], 0, v[134:135]
	s_add_i32 m0, s64, 0x2000
	s_nop 0
	global_load_lds_dwordx4 v[160:161], off
	v_lshl_add_u64 v[160:161], v[230:231], 0, s[48:49]
	s_mov_b32 m0, s78
	s_nop 0
	global_load_lds_dwordx4 v[160:161], off
	v_lshl_add_u64 v[160:161], v[232:233], 0, s[48:49]
	s_mov_b32 m0, s79
	s_nop 0
	global_load_lds_dwordx4 v[160:161], off
	s_waitcnt vmcnt(8)
	s_waitcnt lgkmcnt(0)
	s_barrier
	s_setprio 3
	s_waitcnt lgkmcnt(0)
	v_mfma_f32_16x16x32_bf16 v[30:33], v[148:151], v[186:189], v[30:33]
	v_mfma_f32_16x16x32_bf16 v[26:29], v[156:159], v[186:189], v[26:29]
	v_mfma_f32_16x16x32_bf16 v[22:25], v[148:151], v[194:197], v[22:25]
	v_mfma_f32_16x16x32_bf16 v[18:21], v[156:159], v[194:197], v[18:21]
	v_mfma_f32_16x16x32_bf16 v[14:17], v[148:151], v[202:205], v[14:17]
	v_mfma_f32_16x16x32_bf16 v[10:13], v[156:159], v[202:205], v[10:13]
	v_mfma_f32_16x16x32_bf16 v[6:9], v[148:151], v[222:225], v[6:9]
	v_mfma_f32_16x16x32_bf16 v[2:5], v[156:159], v[222:225], v[2:5]
	v_mfma_f32_16x16x32_bf16 v[30:33], v[152:155], v[190:193], v[30:33]
	v_mfma_f32_16x16x32_bf16 v[26:29], v[166:169], v[190:193], v[26:29]
	v_mfma_f32_16x16x32_bf16 v[22:25], v[152:155], v[198:201], v[22:25]
	v_mfma_f32_16x16x32_bf16 v[18:21], v[166:169], v[198:201], v[18:21]
	v_mfma_f32_16x16x32_bf16 v[14:17], v[152:155], v[206:209], v[14:17]
	v_mfma_f32_16x16x32_bf16 v[10:13], v[166:169], v[206:209], v[10:13]
	v_mfma_f32_16x16x32_bf16 v[6:9], v[152:155], v[226:229], v[6:9]
	v_mfma_f32_16x16x32_bf16 v[2:5], v[166:169], v[226:229], v[2:5]
	v_mfma_f32_16x16x32_bf16 v[94:97], v[170:173], v[186:189], v[94:97]
	v_mfma_f32_16x16x32_bf16 v[90:93], v[178:181], v[186:189], v[90:93]
	v_mfma_f32_16x16x32_bf16 v[86:89], v[170:173], v[194:197], v[86:89]
	v_mfma_f32_16x16x32_bf16 v[82:85], v[178:181], v[194:197], v[82:85]
	v_mfma_f32_16x16x32_bf16 v[78:81], v[170:173], v[202:205], v[78:81]
	v_mfma_f32_16x16x32_bf16 v[74:77], v[178:181], v[202:205], v[74:77]
	v_mfma_f32_16x16x32_bf16 v[62:65], v[170:173], v[222:225], v[62:65]
	v_mfma_f32_16x16x32_bf16 v[58:61], v[178:181], v[222:225], v[58:61]
	v_mfma_f32_16x16x32_bf16 v[94:97], v[174:177], v[190:193], v[94:97]
	v_mfma_f32_16x16x32_bf16 v[90:93], v[182:185], v[190:193], v[90:93]
	v_mfma_f32_16x16x32_bf16 v[86:89], v[174:177], v[198:201], v[86:89]
	v_mfma_f32_16x16x32_bf16 v[82:85], v[182:185], v[198:201], v[82:85]
	v_mfma_f32_16x16x32_bf16 v[78:81], v[174:177], v[206:209], v[78:81]
	v_mfma_f32_16x16x32_bf16 v[74:77], v[182:185], v[206:209], v[74:77]
	v_mfma_f32_16x16x32_bf16 v[62:65], v[174:177], v[226:229], v[62:65]
	v_mfma_f32_16x16x32_bf16 v[58:61], v[182:185], v[226:229], v[58:61]
	s_setprio 0
	s_barrier
	s_add_i32 s85, s85, 2
	s_add_u32 s8, s8, 0x100
	s_addc_u32 s9, s9, 0
	s_add_u32 s83, s83, 0x100
	s_addc_u32 s84, s84, 0
.LBB0_676:
	s_add_u32 s56, s8, 0xfffc0080
	s_addc_u32 s57, s9, -1
	s_add_i32 s64, 0, 0x10000
	s_cmp_eq_u32 s85, 12
	s_cselect_b32 s69, s21, s57
	s_cselect_b32 s68, s31, s56
	v_add_u32_e32 v160, s64, v163
	s_cselect_b32 s57, s11, s84
	s_cselect_b32 s56, s82, s83
	s_add_i32 s86, 0, 0x14000
	ds_read_b128 v[148:151], v160
	ds_read_b128 v[152:155], v160 offset:1024
	ds_read_b128 v[156:159], v160 offset:2048
	ds_read_b128 v[166:169], v160 offset:3072
	v_add_u32_e32 v160, s86, v163
	ds_read_b128 v[170:173], v160
	ds_read_b128 v[174:177], v160 offset:1024
	ds_read_b128 v[178:181], v160 offset:2048
	ds_read_b128 v[182:185], v160 offset:3072
	v_lshl_add_u64 v[160:161], s[8:9], 0, v[144:145]
	s_add_i32 m0, s72, 0xc000
	ds_read_b128 v[186:189], v165
	ds_read_b128 v[190:193], v165 offset:1024
	ds_read_b128 v[194:197], v165 offset:2048
	ds_read_b128 v[198:201], v165 offset:3072
	ds_read_b128 v[202:205], v165 offset:4096
	ds_read_b128 v[206:209], v165 offset:5120
	ds_read_b128 v[222:225], v165 offset:6144
	ds_read_b128 v[226:229], v165 offset:7168
	global_load_lds_dwordx4 v[160:161], off
	v_lshl_add_u64 v[160:161], s[8:9], 0, v[146:147]
	s_add_i32 m0, s72, 0xe000
	s_nop 0
	global_load_lds_dwordx4 v[160:161], off
	s_waitcnt vmcnt(8)
	s_waitcnt lgkmcnt(0)
	s_barrier
	s_setprio 3
	s_waitcnt lgkmcnt(0)
	v_mfma_f32_16x16x32_bf16 v[70:73], v[148:151], v[186:189], v[70:73]
	v_mfma_f32_16x16x32_bf16 v[66:69], v[156:159], v[186:189], v[66:69]
	v_mfma_f32_16x16x32_bf16 v[54:57], v[148:151], v[194:197], v[54:57]
	v_mfma_f32_16x16x32_bf16 v[50:53], v[156:159], v[194:197], v[50:53]
	v_mfma_f32_16x16x32_bf16 v[46:49], v[148:151], v[202:205], v[46:49]
	v_mfma_f32_16x16x32_bf16 v[42:45], v[156:159], v[202:205], v[42:45]
	v_mfma_f32_16x16x32_bf16 v[38:41], v[148:151], v[222:225], v[38:41]
	v_mfma_f32_16x16x32_bf16 v[34:37], v[156:159], v[222:225], v[34:37]
	v_mfma_f32_16x16x32_bf16 v[70:73], v[152:155], v[190:193], v[70:73]
	v_mfma_f32_16x16x32_bf16 v[66:69], v[166:169], v[190:193], v[66:69]
	v_mfma_f32_16x16x32_bf16 v[54:57], v[152:155], v[198:201], v[54:57]
	v_mfma_f32_16x16x32_bf16 v[50:53], v[166:169], v[198:201], v[50:53]
	v_mfma_f32_16x16x32_bf16 v[46:49], v[152:155], v[206:209], v[46:49]
	v_mfma_f32_16x16x32_bf16 v[42:45], v[166:169], v[206:209], v[42:45]
	v_mfma_f32_16x16x32_bf16 v[38:41], v[152:155], v[226:229], v[38:41]
	v_mfma_f32_16x16x32_bf16 v[34:37], v[166:169], v[226:229], v[34:37]
	v_mfma_f32_16x16x32_bf16 v[126:129], v[170:173], v[186:189], v[126:129]
	v_mfma_f32_16x16x32_bf16 v[122:125], v[178:181], v[186:189], v[122:125]
	v_mfma_f32_16x16x32_bf16 v[118:121], v[170:173], v[194:197], v[118:121]
	v_mfma_f32_16x16x32_bf16 v[114:117], v[178:181], v[194:197], v[114:117]
	v_mfma_f32_16x16x32_bf16 v[110:113], v[170:173], v[202:205], v[110:113]
	v_mfma_f32_16x16x32_bf16 v[106:109], v[178:181], v[202:205], v[106:109]
	v_mfma_f32_16x16x32_bf16 v[102:105], v[170:173], v[222:225], v[102:105]
	v_mfma_f32_16x16x32_bf16 v[98:101], v[178:181], v[222:225], v[98:101]
	v_mfma_f32_16x16x32_bf16 v[126:129], v[174:177], v[190:193], v[126:129]
	v_mfma_f32_16x16x32_bf16 v[122:125], v[182:185], v[190:193], v[122:125]
	v_mfma_f32_16x16x32_bf16 v[118:121], v[174:177], v[198:201], v[118:121]
	v_mfma_f32_16x16x32_bf16 v[114:117], v[182:185], v[198:201], v[114:117]
	v_mfma_f32_16x16x32_bf16 v[110:113], v[174:177], v[206:209], v[110:113]
	v_mfma_f32_16x16x32_bf16 v[106:109], v[182:185], v[206:209], v[106:109]
	v_mfma_f32_16x16x32_bf16 v[102:105], v[174:177], v[226:229], v[102:105]
	v_mfma_f32_16x16x32_bf16 v[98:101], v[182:185], v[226:229], v[98:101]
	s_setprio 0
	s_barrier
	s_add_i32 s64, s64, s63
	v_lshl_add_u64 v[160:161], s[56:57], 0, v[0:1]
	s_mov_b32 m0, s64
	ds_read_b128 v[186:189], v165 offset:16384
	ds_read_b128 v[190:193], v165 offset:17408
	ds_read_b128 v[194:197], v165 offset:18432
	ds_read_b128 v[198:201], v165 offset:19456
	ds_read_b128 v[202:205], v165 offset:20480
	ds_read_b128 v[206:209], v165 offset:21504
	ds_read_b128 v[222:225], v165 offset:22528
	ds_read_b128 v[226:229], v165 offset:23552
	global_load_lds_dwordx4 v[160:161], off
	s_add_i32 m0, s64, 0x2000
	s_add_u32 s64, s56, 0x40000
	v_lshl_add_u64 v[210:211], s[56:57], 0, v[134:135]
	s_addc_u32 s65, s57, 0
	s_add_i32 s86, s86, s63
	global_load_lds_dwordx4 v[210:211], off
	v_lshl_add_u64 v[230:231], s[64:65], 0, v[0:1]
	s_mov_b32 m0, s86
	v_lshl_add_u64 v[232:233], s[68:69], 0, v[136:137]
	global_load_lds_dwordx4 v[230:231], off
	v_lshl_add_u64 v[230:231], s[64:65], 0, v[134:135]
	s_add_i32 m0, s86, 0x2000
	s_nop 0
	global_load_lds_dwordx4 v[230:231], off
	v_lshl_add_u64 v[230:231], s[68:69], 0, v[138:139]
	s_mov_b32 m0, s72
	s_nop 0
	global_load_lds_dwordx4 v[230:231], off
	s_mov_b32 m0, s73
	s_nop 0
	global_load_lds_dwordx4 v[232:233], off
	s_waitcnt vmcnt(8)
	s_waitcnt lgkmcnt(0)
	s_barrier
	s_setprio 3
	s_waitcnt lgkmcnt(0)
	v_mfma_f32_16x16x32_bf16 v[30:33], v[148:151], v[186:189], v[30:33]
	v_mfma_f32_16x16x32_bf16 v[26:29], v[156:159], v[186:189], v[26:29]
	v_mfma_f32_16x16x32_bf16 v[22:25], v[148:151], v[194:197], v[22:25]
	v_mfma_f32_16x16x32_bf16 v[18:21], v[156:159], v[194:197], v[18:21]
	v_mfma_f32_16x16x32_bf16 v[14:17], v[148:151], v[202:205], v[14:17]
	v_mfma_f32_16x16x32_bf16 v[10:13], v[156:159], v[202:205], v[10:13]
	v_mfma_f32_16x16x32_bf16 v[6:9], v[148:151], v[222:225], v[6:9]
	v_mfma_f32_16x16x32_bf16 v[2:5], v[156:159], v[222:225], v[2:5]
	v_mfma_f32_16x16x32_bf16 v[30:33], v[152:155], v[190:193], v[30:33]
	v_mfma_f32_16x16x32_bf16 v[26:29], v[166:169], v[190:193], v[26:29]
	v_mfma_f32_16x16x32_bf16 v[22:25], v[152:155], v[198:201], v[22:25]
	v_mfma_f32_16x16x32_bf16 v[18:21], v[166:169], v[198:201], v[18:21]
	v_mfma_f32_16x16x32_bf16 v[14:17], v[152:155], v[206:209], v[14:17]
	v_mfma_f32_16x16x32_bf16 v[10:13], v[166:169], v[206:209], v[10:13]
	v_mfma_f32_16x16x32_bf16 v[6:9], v[152:155], v[226:229], v[6:9]
	v_mfma_f32_16x16x32_bf16 v[2:5], v[166:169], v[226:229], v[2:5]
	v_mfma_f32_16x16x32_bf16 v[94:97], v[170:173], v[186:189], v[94:97]
	v_mfma_f32_16x16x32_bf16 v[90:93], v[178:181], v[186:189], v[90:93]
	v_mfma_f32_16x16x32_bf16 v[86:89], v[170:173], v[194:197], v[86:89]
	v_mfma_f32_16x16x32_bf16 v[82:85], v[178:181], v[194:197], v[82:85]
	v_mfma_f32_16x16x32_bf16 v[78:81], v[170:173], v[202:205], v[78:81]
	v_mfma_f32_16x16x32_bf16 v[74:77], v[178:181], v[202:205], v[74:77]
	v_mfma_f32_16x16x32_bf16 v[62:65], v[170:173], v[222:225], v[62:65]
	v_mfma_f32_16x16x32_bf16 v[58:61], v[178:181], v[222:225], v[58:61]
	v_mfma_f32_16x16x32_bf16 v[94:97], v[174:177], v[190:193], v[94:97]
	v_mfma_f32_16x16x32_bf16 v[90:93], v[182:185], v[190:193], v[90:93]
	v_mfma_f32_16x16x32_bf16 v[86:89], v[174:177], v[198:201], v[86:89]
	v_mfma_f32_16x16x32_bf16 v[82:85], v[182:185], v[198:201], v[82:85]
	v_mfma_f32_16x16x32_bf16 v[78:81], v[174:177], v[206:209], v[78:81]
	v_mfma_f32_16x16x32_bf16 v[74:77], v[182:185], v[206:209], v[74:77]
	v_mfma_f32_16x16x32_bf16 v[62:65], v[174:177], v[226:229], v[62:65]
	v_mfma_f32_16x16x32_bf16 v[58:61], v[182:185], v[226:229], v[58:61]
	s_setprio 0
	s_barrier
	s_add_i32 s86, 0, 0x18000
	s_add_i32 s87, 0, 0x1c000
	v_add_u32_e32 v166, s86, v163
	v_add_u32_e32 v182, s87, v163
	ds_read_b128 v[148:151], v166
	ds_read_b128 v[152:155], v166 offset:1024
	ds_read_b128 v[156:159], v166 offset:2048
	ds_read_b128 v[166:169], v166 offset:3072
	ds_read_b128 v[170:173], v182
	ds_read_b128 v[174:177], v182 offset:1024
	ds_read_b128 v[178:181], v182 offset:2048
	ds_read_b128 v[182:185], v182 offset:3072
	s_add_u32 s64, s68, 0x40000
	s_addc_u32 s65, s69, 0
	s_mov_b32 m0, s74
	v_lshl_add_u64 v[234:235], s[64:65], 0, v[138:139]
	ds_read_b128 v[186:189], v165 offset:32768
	ds_read_b128 v[190:193], v165 offset:33792
	ds_read_b128 v[194:197], v165 offset:34816
	ds_read_b128 v[198:201], v165 offset:35840
	ds_read_b128 v[202:205], v165 offset:36864
	ds_read_b128 v[206:209], v165 offset:37888
	ds_read_b128 v[222:225], v165 offset:38912
	ds_read_b128 v[226:229], v165 offset:39936
	global_load_lds_dwordx4 v[234:235], off
	v_lshl_add_u64 v[234:235], s[64:65], 0, v[136:137]
	s_mov_b32 m0, s75
	s_nop 0
	global_load_lds_dwordx4 v[234:235], off
	s_waitcnt vmcnt(8)
	s_waitcnt lgkmcnt(0)
	s_barrier
	s_setprio 3
	s_waitcnt lgkmcnt(0)
	v_mfma_f32_16x16x32_bf16 v[70:73], v[148:151], v[186:189], v[70:73]
	v_mfma_f32_16x16x32_bf16 v[66:69], v[156:159], v[186:189], v[66:69]
	v_mfma_f32_16x16x32_bf16 v[54:57], v[148:151], v[194:197], v[54:57]
	v_mfma_f32_16x16x32_bf16 v[50:53], v[156:159], v[194:197], v[50:53]
	v_mfma_f32_16x16x32_bf16 v[46:49], v[148:151], v[202:205], v[46:49]
	v_mfma_f32_16x16x32_bf16 v[42:45], v[156:159], v[202:205], v[42:45]
	v_mfma_f32_16x16x32_bf16 v[38:41], v[148:151], v[222:225], v[38:41]
	v_mfma_f32_16x16x32_bf16 v[34:37], v[156:159], v[222:225], v[34:37]
	v_mfma_f32_16x16x32_bf16 v[70:73], v[152:155], v[190:193], v[70:73]
	v_mfma_f32_16x16x32_bf16 v[66:69], v[166:169], v[190:193], v[66:69]
	v_mfma_f32_16x16x32_bf16 v[54:57], v[152:155], v[198:201], v[54:57]
	v_mfma_f32_16x16x32_bf16 v[50:53], v[166:169], v[198:201], v[50:53]
	v_mfma_f32_16x16x32_bf16 v[46:49], v[152:155], v[206:209], v[46:49]
	v_mfma_f32_16x16x32_bf16 v[42:45], v[166:169], v[206:209], v[42:45]
	v_mfma_f32_16x16x32_bf16 v[38:41], v[152:155], v[226:229], v[38:41]
	v_mfma_f32_16x16x32_bf16 v[34:37], v[166:169], v[226:229], v[34:37]
	v_mfma_f32_16x16x32_bf16 v[126:129], v[170:173], v[186:189], v[126:129]
	v_mfma_f32_16x16x32_bf16 v[122:125], v[178:181], v[186:189], v[122:125]
	v_mfma_f32_16x16x32_bf16 v[118:121], v[170:173], v[194:197], v[118:121]
	v_mfma_f32_16x16x32_bf16 v[114:117], v[178:181], v[194:197], v[114:117]
	v_mfma_f32_16x16x32_bf16 v[110:113], v[170:173], v[202:205], v[110:113]
	v_mfma_f32_16x16x32_bf16 v[106:109], v[178:181], v[202:205], v[106:109]
	v_mfma_f32_16x16x32_bf16 v[102:105], v[170:173], v[222:225], v[102:105]
	v_mfma_f32_16x16x32_bf16 v[98:101], v[178:181], v[222:225], v[98:101]
	v_mfma_f32_16x16x32_bf16 v[126:129], v[174:177], v[190:193], v[126:129]
	v_mfma_f32_16x16x32_bf16 v[122:125], v[182:185], v[190:193], v[122:125]
	v_mfma_f32_16x16x32_bf16 v[118:121], v[174:177], v[198:201], v[118:121]
	v_mfma_f32_16x16x32_bf16 v[114:117], v[182:185], v[198:201], v[114:117]
	v_mfma_f32_16x16x32_bf16 v[110:113], v[174:177], v[206:209], v[110:113]
	v_mfma_f32_16x16x32_bf16 v[106:109], v[182:185], v[206:209], v[106:109]
	v_mfma_f32_16x16x32_bf16 v[102:105], v[174:177], v[226:229], v[102:105]
	v_mfma_f32_16x16x32_bf16 v[98:101], v[182:185], v[226:229], v[98:101]
	s_setprio 0
	s_barrier
	s_add_i32 s64, s86, s63
	v_lshl_add_u64 v[160:161], v[160:161], 0, s[48:49]
	s_mov_b32 m0, s64
	ds_read_b128 v[186:189], v165 offset:49152
	ds_read_b128 v[190:193], v165 offset:50176
	ds_read_b128 v[194:197], v165 offset:51200
	ds_read_b128 v[198:201], v165 offset:52224
	ds_read_b128 v[202:205], v165 offset:53248
	ds_read_b128 v[206:209], v165 offset:54272
	ds_read_b128 v[222:225], v165 offset:55296
	ds_read_b128 v[226:229], v165 offset:56320
	global_load_lds_dwordx4 v[160:161], off
	s_add_i32 m0, s64, 0x2000
	s_add_u32 s56, s56, 0x40080
	v_lshl_add_u64 v[160:161], v[210:211], 0, s[48:49]
	s_addc_u32 s57, s57, 0
	s_add_i32 s64, s87, s63
	global_load_lds_dwordx4 v[160:161], off
	v_lshl_add_u64 v[160:161], s[56:57], 0, v[0:1]
	s_mov_b32 m0, s64
	s_nop 0
	global_load_lds_dwordx4 v[160:161], off
	v_lshl_add_u64 v[160:161], s[56:57], 0, v[134:135]
	s_add_i32 m0, s64, 0x2000
	s_nop 0
	global_load_lds_dwordx4 v[160:161], off
	v_lshl_add_u64 v[160:161], v[230:231], 0, s[48:49]
	s_mov_b32 m0, s78
	s_nop 0
	global_load_lds_dwordx4 v[160:161], off
	v_lshl_add_u64 v[160:161], v[232:233], 0, s[48:49]
	s_mov_b32 m0, s79
	s_nop 0
	global_load_lds_dwordx4 v[160:161], off
	s_waitcnt vmcnt(8)
	s_waitcnt lgkmcnt(0)
	s_barrier
	s_setprio 3
	s_waitcnt lgkmcnt(0)
	v_mfma_f32_16x16x32_bf16 v[30:33], v[148:151], v[186:189], v[30:33]
	v_mfma_f32_16x16x32_bf16 v[26:29], v[156:159], v[186:189], v[26:29]
	v_mfma_f32_16x16x32_bf16 v[22:25], v[148:151], v[194:197], v[22:25]
	v_mfma_f32_16x16x32_bf16 v[18:21], v[156:159], v[194:197], v[18:21]
	v_mfma_f32_16x16x32_bf16 v[14:17], v[148:151], v[202:205], v[14:17]
	v_mfma_f32_16x16x32_bf16 v[10:13], v[156:159], v[202:205], v[10:13]
	v_mfma_f32_16x16x32_bf16 v[6:9], v[148:151], v[222:225], v[6:9]
	v_mfma_f32_16x16x32_bf16 v[2:5], v[156:159], v[222:225], v[2:5]
	v_mfma_f32_16x16x32_bf16 v[30:33], v[152:155], v[190:193], v[30:33]
	v_mfma_f32_16x16x32_bf16 v[26:29], v[166:169], v[190:193], v[26:29]
	v_mfma_f32_16x16x32_bf16 v[22:25], v[152:155], v[198:201], v[22:25]
	v_mfma_f32_16x16x32_bf16 v[18:21], v[166:169], v[198:201], v[18:21]
	v_mfma_f32_16x16x32_bf16 v[14:17], v[152:155], v[206:209], v[14:17]
	v_mfma_f32_16x16x32_bf16 v[10:13], v[166:169], v[206:209], v[10:13]
	v_mfma_f32_16x16x32_bf16 v[6:9], v[152:155], v[226:229], v[6:9]
	v_mfma_f32_16x16x32_bf16 v[2:5], v[166:169], v[226:229], v[2:5]
	v_mfma_f32_16x16x32_bf16 v[94:97], v[170:173], v[186:189], v[94:97]
	v_mfma_f32_16x16x32_bf16 v[90:93], v[178:181], v[186:189], v[90:93]
	v_mfma_f32_16x16x32_bf16 v[86:89], v[170:173], v[194:197], v[86:89]
	v_mfma_f32_16x16x32_bf16 v[82:85], v[178:181], v[194:197], v[82:85]
	v_mfma_f32_16x16x32_bf16 v[78:81], v[170:173], v[202:205], v[78:81]
	v_mfma_f32_16x16x32_bf16 v[74:77], v[178:181], v[202:205], v[74:77]
	v_mfma_f32_16x16x32_bf16 v[62:65], v[170:173], v[222:225], v[62:65]
	v_mfma_f32_16x16x32_bf16 v[58:61], v[178:181], v[222:225], v[58:61]
	v_mfma_f32_16x16x32_bf16 v[94:97], v[174:177], v[190:193], v[94:97]
	v_mfma_f32_16x16x32_bf16 v[90:93], v[182:185], v[190:193], v[90:93]
	v_mfma_f32_16x16x32_bf16 v[86:89], v[174:177], v[198:201], v[86:89]
	v_mfma_f32_16x16x32_bf16 v[82:85], v[182:185], v[198:201], v[82:85]
	v_mfma_f32_16x16x32_bf16 v[78:81], v[174:177], v[206:209], v[78:81]
	v_mfma_f32_16x16x32_bf16 v[74:77], v[182:185], v[206:209], v[74:77]
	v_mfma_f32_16x16x32_bf16 v[62:65], v[174:177], v[226:229], v[62:65]
	v_mfma_f32_16x16x32_bf16 v[58:61], v[182:185], v[226:229], v[58:61]
	s_setprio 0
	s_barrier
	s_add_i32 s85, s85, 2
	s_add_u32 s8, s8, 0x100
	s_addc_u32 s9, s9, 0
	s_add_u32 s83, s83, 0x100
	s_addc_u32 s84, s84, 0
	s_cmp_gt_u32 s85, 13
	s_cbranch_scc0 .LBB0_676
	s_and_b64 vcc, exec, s[16:17]
	s_cbranch_vccnz .LBB0_681
	s_cmp_lt_i32 s30, 16
	s_mov_b64 s[8:9], -1
	s_cbranch_scc1 .LBB0_682

.LBB0_1458:
	s_ashr_i32 s11, s12, 3
	s_add_i32 s11, s12, s11
	s_and_b64 s[16:17], s[66:67], s[4:5]
	s_add_i32 s11, s11, 1
	s_and_b64 s[16:17], s[16:17], exec
	s_cselect_b32 s12, s11, s12
	s_ashr_i32 s13, s12, 31
	s_lshl_b64 s[16:17], s[12:13], 19
	s_add_u32 s16, s37, s16
	s_addc_u32 s17, s60, s17
	s_and_b64 s[18:19], s[4:5], exec
	s_cselect_b32 s13, s17, s53
	s_cselect_b32 s27, s16, s52
	s_ashr_i32 s11, s10, 31
	s_lshl_b64 s[18:19], s[10:11], 19
	s_add_u32 s18, s63, s18
	s_addc_u32 s19, s70, s19
	s_and_b64 s[30:31], s[4:5], exec
	s_cselect_b32 s11, s19, s57
	s_cselect_b32 s30, s18, s56
	s_add_u32 s52, s52, 0x40080
	s_addc_u32 s53, s53, 0
	s_add_u32 s31, s56, 0x100
	s_addc_u32 s84, s57, 0
	s_mov_b32 s85, -2
	s_add_u32 s56, s52, 0xfffc0080
	s_addc_u32 s57, s53, -1
	s_add_i32 s64, 0, 0x10000
	s_cmp_eq_u32 s85, 12
	s_cselect_b32 s69, s13, s57
	s_cselect_b32 s68, s27, s56
	v_add_u32_e32 v0, s64, v167
	s_cselect_b32 s57, s11, s84
	s_cselect_b32 s56, s30, s31
	s_add_i32 s86, 0, 0x14000
	ds_read_b128 v[134:137], v0
	ds_read_b128 v[150:153], v0 offset:1024
	ds_read_b128 v[154:157], v0 offset:2048
	ds_read_b128 v[158:161], v0 offset:3072
	v_add_u32_e32 v0, s86, v167
	ds_read_b128 v[162:165], v0
	ds_read_b128 v[170:173], v0 offset:1024
	ds_read_b128 v[174:177], v0 offset:2048
	ds_read_b128 v[178:181], v0 offset:3072
	v_lshl_add_u64 v[210:211], s[52:53], 0, v[146:147]
	s_add_i32 m0, s21, 0xc000
	ds_read_b128 v[182:185], v169
	ds_read_b128 v[186:189], v169 offset:1024
	ds_read_b128 v[190:193], v169 offset:2048
	ds_read_b128 v[194:197], v169 offset:3072
	ds_read_b128 v[198:201], v169 offset:4096
	ds_read_b128 v[202:205], v169 offset:5120
	ds_read_b128 v[206:209], v169 offset:6144
	ds_read_b128 v[224:227], v169 offset:7168
	global_load_lds_dwordx4 v[210:211], off
	v_lshl_add_u64 v[210:211], s[52:53], 0, v[148:149]
	s_add_i32 m0, s21, 0xe000
	s_nop 0
	global_load_lds_dwordx4 v[210:211], off
	s_waitcnt vmcnt(8)
	s_waitcnt lgkmcnt(0)
	s_barrier
	s_setprio 3
	s_waitcnt lgkmcnt(0)
	v_mfma_f32_16x16x32_bf16 v[126:129], v[134:137], v[182:185], 0
	v_mfma_f32_16x16x32_bf16 v[122:125], v[154:157], v[182:185], 0
	v_mfma_f32_16x16x32_bf16 v[110:113], v[134:137], v[190:193], 0
	v_mfma_f32_16x16x32_bf16 v[106:109], v[154:157], v[190:193], 0
	v_mfma_f32_16x16x32_bf16 v[94:97], v[134:137], v[198:201], 0
	v_mfma_f32_16x16x32_bf16 v[90:93], v[154:157], v[198:201], 0
	v_mfma_f32_16x16x32_bf16 v[78:81], v[134:137], v[206:209], 0
	v_mfma_f32_16x16x32_bf16 v[74:77], v[154:157], v[206:209], 0
	v_mfma_f32_16x16x32_bf16 v[126:129], v[150:153], v[186:189], v[126:129]
	v_mfma_f32_16x16x32_bf16 v[122:125], v[158:161], v[186:189], v[122:125]
	v_mfma_f32_16x16x32_bf16 v[110:113], v[150:153], v[194:197], v[110:113]
	v_mfma_f32_16x16x32_bf16 v[106:109], v[158:161], v[194:197], v[106:109]
	v_mfma_f32_16x16x32_bf16 v[94:97], v[150:153], v[202:205], v[94:97]
	v_mfma_f32_16x16x32_bf16 v[90:93], v[158:161], v[202:205], v[90:93]
	v_mfma_f32_16x16x32_bf16 v[78:81], v[150:153], v[224:227], v[78:81]
	v_mfma_f32_16x16x32_bf16 v[74:77], v[158:161], v[224:227], v[74:77]
	v_mfma_f32_16x16x32_bf16 v[118:121], v[162:165], v[182:185], 0
	v_mfma_f32_16x16x32_bf16 v[114:117], v[174:177], v[182:185], 0
	v_mfma_f32_16x16x32_bf16 v[102:105], v[162:165], v[190:193], 0
	v_mfma_f32_16x16x32_bf16 v[98:101], v[174:177], v[190:193], 0
	v_mfma_f32_16x16x32_bf16 v[86:89], v[162:165], v[198:201], 0
	v_mfma_f32_16x16x32_bf16 v[82:85], v[174:177], v[198:201], 0
	v_mfma_f32_16x16x32_bf16 v[70:73], v[162:165], v[206:209], 0
	v_mfma_f32_16x16x32_bf16 v[66:69], v[174:177], v[206:209], 0
	v_mfma_f32_16x16x32_bf16 v[118:121], v[170:173], v[186:189], v[118:121]
	v_mfma_f32_16x16x32_bf16 v[114:117], v[178:181], v[186:189], v[114:117]
	v_mfma_f32_16x16x32_bf16 v[102:105], v[170:173], v[194:197], v[102:105]
	v_mfma_f32_16x16x32_bf16 v[98:101], v[178:181], v[194:197], v[98:101]
	v_mfma_f32_16x16x32_bf16 v[86:89], v[170:173], v[202:205], v[86:89]
	v_mfma_f32_16x16x32_bf16 v[82:85], v[178:181], v[202:205], v[82:85]
	v_mfma_f32_16x16x32_bf16 v[70:73], v[170:173], v[224:227], v[70:73]
	v_mfma_f32_16x16x32_bf16 v[66:69], v[178:181], v[224:227], v[66:69]
	s_setprio 0
	s_barrier
	s_add_i32 s64, s64, s71
	v_lshl_add_u64 v[210:211], s[56:57], 0, v[142:143]
	s_mov_b32 m0, s64
	ds_read_b128 v[182:185], v169 offset:16384
	ds_read_b128 v[186:189], v169 offset:17408
	ds_read_b128 v[190:193], v169 offset:18432
	ds_read_b128 v[194:197], v169 offset:19456
	ds_read_b128 v[198:201], v169 offset:20480
	ds_read_b128 v[202:205], v169 offset:21504
	ds_read_b128 v[206:209], v169 offset:22528
	ds_read_b128 v[224:227], v169 offset:23552
	global_load_lds_dwordx4 v[210:211], off
	s_add_i32 m0, s64, 0x2000
	s_add_u32 s64, s56, 0x40000
	v_lshl_add_u64 v[228:229], s[56:57], 0, v[138:139]
	s_addc_u32 s65, s57, 0
	s_add_i32 s86, s86, s71
	global_load_lds_dwordx4 v[228:229], off
	v_lshl_add_u64 v[230:231], s[64:65], 0, v[142:143]
	s_mov_b32 m0, s86
	v_lshl_add_u64 v[232:233], s[68:69], 0, v[140:141]
	global_load_lds_dwordx4 v[230:231], off
	v_lshl_add_u64 v[230:231], s[64:65], 0, v[138:139]
	s_add_i32 m0, s86, 0x2000
	s_nop 0
	global_load_lds_dwordx4 v[230:231], off
	v_lshl_add_u64 v[230:231], s[68:69], 0, v[144:145]
	s_mov_b32 m0, s21
	s_nop 0
	global_load_lds_dwordx4 v[230:231], off
	s_mov_b32 m0, s73
	s_nop 0
	global_load_lds_dwordx4 v[232:233], off
	s_waitcnt vmcnt(8)
	s_waitcnt lgkmcnt(0)
	s_barrier
	s_setprio 3
	s_waitcnt lgkmcnt(0)
	v_mfma_f32_16x16x32_bf16 v[62:65], v[134:137], v[182:185], 0
	v_mfma_f32_16x16x32_bf16 v[58:61], v[154:157], v[182:185], 0
	v_mfma_f32_16x16x32_bf16 v[46:49], v[134:137], v[190:193], 0
	v_mfma_f32_16x16x32_bf16 v[42:45], v[154:157], v[190:193], 0
	v_mfma_f32_16x16x32_bf16 v[30:33], v[134:137], v[198:201], 0
	v_mfma_f32_16x16x32_bf16 v[26:29], v[154:157], v[198:201], 0
	v_mfma_f32_16x16x32_bf16 v[14:17], v[134:137], v[206:209], 0
	v_mfma_f32_16x16x32_bf16 v[10:13], v[154:157], v[206:209], 0
	v_mfma_f32_16x16x32_bf16 v[62:65], v[150:153], v[186:189], v[62:65]
	v_mfma_f32_16x16x32_bf16 v[58:61], v[158:161], v[186:189], v[58:61]
	v_mfma_f32_16x16x32_bf16 v[46:49], v[150:153], v[194:197], v[46:49]
	v_mfma_f32_16x16x32_bf16 v[42:45], v[158:161], v[194:197], v[42:45]
	v_mfma_f32_16x16x32_bf16 v[30:33], v[150:153], v[202:205], v[30:33]
	v_mfma_f32_16x16x32_bf16 v[26:29], v[158:161], v[202:205], v[26:29]
	v_mfma_f32_16x16x32_bf16 v[14:17], v[150:153], v[224:227], v[14:17]
	v_mfma_f32_16x16x32_bf16 v[10:13], v[158:161], v[224:227], v[10:13]
	v_mfma_f32_16x16x32_bf16 v[54:57], v[162:165], v[182:185], 0
	v_mfma_f32_16x16x32_bf16 v[50:53], v[174:177], v[182:185], 0
	v_mfma_f32_16x16x32_bf16 v[38:41], v[162:165], v[190:193], 0
	v_mfma_f32_16x16x32_bf16 v[34:37], v[174:177], v[190:193], 0
	v_mfma_f32_16x16x32_bf16 v[22:25], v[162:165], v[198:201], 0
	v_mfma_f32_16x16x32_bf16 v[18:21], v[174:177], v[198:201], 0
	v_mfma_f32_16x16x32_bf16 v[6:9], v[162:165], v[206:209], 0
	v_mfma_f32_16x16x32_bf16 v[2:5], v[174:177], v[206:209], 0
	v_mfma_f32_16x16x32_bf16 v[54:57], v[170:173], v[186:189], v[54:57]
	v_mfma_f32_16x16x32_bf16 v[50:53], v[178:181], v[186:189], v[50:53]
	v_mfma_f32_16x16x32_bf16 v[38:41], v[170:173], v[194:197], v[38:41]
	v_mfma_f32_16x16x32_bf16 v[34:37], v[178:181], v[194:197], v[34:37]
	v_mfma_f32_16x16x32_bf16 v[22:25], v[170:173], v[202:205], v[22:25]
	v_mfma_f32_16x16x32_bf16 v[18:21], v[178:181], v[202:205], v[18:21]
	v_mfma_f32_16x16x32_bf16 v[6:9], v[170:173], v[224:227], v[6:9]
	v_mfma_f32_16x16x32_bf16 v[2:5], v[178:181], v[224:227], v[2:5]
	s_setprio 0
	s_barrier
	s_add_i32 s86, 0, 0x18000
	v_add_u32_e32 v0, s86, v167
	s_add_i32 s87, 0, 0x1c000
	ds_read_b128 v[134:137], v0
	ds_read_b128 v[150:153], v0 offset:1024
	ds_read_b128 v[154:157], v0 offset:2048
	ds_read_b128 v[158:161], v0 offset:3072
	v_add_u32_e32 v0, s87, v167
	ds_read_b128 v[162:165], v0
	ds_read_b128 v[170:173], v0 offset:1024
	ds_read_b128 v[174:177], v0 offset:2048
	ds_read_b128 v[178:181], v0 offset:3072
	s_add_u32 s64, s68, 0x40000
	s_addc_u32 s65, s69, 0
	s_mov_b32 m0, s74
	v_lshl_add_u64 v[234:235], s[64:65], 0, v[144:145]
	ds_read_b128 v[182:185], v169 offset:32768
	ds_read_b128 v[186:189], v169 offset:33792
	ds_read_b128 v[190:193], v169 offset:34816
	ds_read_b128 v[194:197], v169 offset:35840
	ds_read_b128 v[198:201], v169 offset:36864
	ds_read_b128 v[202:205], v169 offset:37888
	ds_read_b128 v[206:209], v169 offset:38912
	ds_read_b128 v[224:227], v169 offset:39936
	global_load_lds_dwordx4 v[234:235], off
	v_lshl_add_u64 v[234:235], s[64:65], 0, v[140:141]
	s_mov_b32 m0, s75
	s_nop 0
	global_load_lds_dwordx4 v[234:235], off
	s_waitcnt vmcnt(8)
	s_waitcnt lgkmcnt(0)
	s_barrier
	s_setprio 3
	s_waitcnt lgkmcnt(0)
	v_mfma_f32_16x16x32_bf16 v[126:129], v[134:137], v[182:185], v[126:129]
	v_mfma_f32_16x16x32_bf16 v[122:125], v[154:157], v[182:185], v[122:125]
	v_mfma_f32_16x16x32_bf16 v[110:113], v[134:137], v[190:193], v[110:113]
	v_mfma_f32_16x16x32_bf16 v[106:109], v[154:157], v[190:193], v[106:109]
	v_mfma_f32_16x16x32_bf16 v[94:97], v[134:137], v[198:201], v[94:97]
	v_mfma_f32_16x16x32_bf16 v[90:93], v[154:157], v[198:201], v[90:93]
	v_mfma_f32_16x16x32_bf16 v[78:81], v[134:137], v[206:209], v[78:81]
	v_mfma_f32_16x16x32_bf16 v[74:77], v[154:157], v[206:209], v[74:77]
	v_mfma_f32_16x16x32_bf16 v[126:129], v[150:153], v[186:189], v[126:129]
	v_mfma_f32_16x16x32_bf16 v[122:125], v[158:161], v[186:189], v[122:125]
	v_mfma_f32_16x16x32_bf16 v[110:113], v[150:153], v[194:197], v[110:113]
	v_mfma_f32_16x16x32_bf16 v[106:109], v[158:161], v[194:197], v[106:109]
	v_mfma_f32_16x16x32_bf16 v[94:97], v[150:153], v[202:205], v[94:97]
	v_mfma_f32_16x16x32_bf16 v[90:93], v[158:161], v[202:205], v[90:93]
	v_mfma_f32_16x16x32_bf16 v[78:81], v[150:153], v[224:227], v[78:81]
	v_mfma_f32_16x16x32_bf16 v[74:77], v[158:161], v[224:227], v[74:77]
	v_mfma_f32_16x16x32_bf16 v[118:121], v[162:165], v[182:185], v[118:121]
	v_mfma_f32_16x16x32_bf16 v[114:117], v[174:177], v[182:185], v[114:117]
	v_mfma_f32_16x16x32_bf16 v[102:105], v[162:165], v[190:193], v[102:105]
	v_mfma_f32_16x16x32_bf16 v[98:101], v[174:177], v[190:193], v[98:101]
	v_mfma_f32_16x16x32_bf16 v[86:89], v[162:165], v[198:201], v[86:89]
	v_mfma_f32_16x16x32_bf16 v[82:85], v[174:177], v[198:201], v[82:85]
	v_mfma_f32_16x16x32_bf16 v[70:73], v[162:165], v[206:209], v[70:73]
	v_mfma_f32_16x16x32_bf16 v[66:69], v[174:177], v[206:209], v[66:69]
	v_mfma_f32_16x16x32_bf16 v[118:121], v[170:173], v[186:189], v[118:121]
	v_mfma_f32_16x16x32_bf16 v[114:117], v[178:181], v[186:189], v[114:117]
	v_mfma_f32_16x16x32_bf16 v[102:105], v[170:173], v[194:197], v[102:105]
	v_mfma_f32_16x16x32_bf16 v[98:101], v[178:181], v[194:197], v[98:101]
	v_mfma_f32_16x16x32_bf16 v[86:89], v[170:173], v[202:205], v[86:89]
	v_mfma_f32_16x16x32_bf16 v[82:85], v[178:181], v[202:205], v[82:85]
	v_mfma_f32_16x16x32_bf16 v[70:73], v[170:173], v[224:227], v[70:73]
	v_mfma_f32_16x16x32_bf16 v[66:69], v[178:181], v[224:227], v[66:69]
	s_setprio 0
	s_barrier
	s_add_i32 s64, s86, s71
	v_lshl_add_u64 v[210:211], v[210:211], 0, s[48:49]
	s_mov_b32 m0, s64
	ds_read_b128 v[182:185], v169 offset:49152
	ds_read_b128 v[186:189], v169 offset:50176
	ds_read_b128 v[190:193], v169 offset:51200
	ds_read_b128 v[194:197], v169 offset:52224
	ds_read_b128 v[198:201], v169 offset:53248
	ds_read_b128 v[202:205], v169 offset:54272
	ds_read_b128 v[206:209], v169 offset:55296
	ds_read_b128 v[224:227], v169 offset:56320
	global_load_lds_dwordx4 v[210:211], off
	s_add_i32 m0, s64, 0x2000
	s_add_u32 s56, s56, 0x40080
	v_lshl_add_u64 v[210:211], v[228:229], 0, s[48:49]
	s_addc_u32 s57, s57, 0
	s_add_i32 s64, s87, s71
	global_load_lds_dwordx4 v[210:211], off
	v_lshl_add_u64 v[210:211], s[56:57], 0, v[142:143]
	s_mov_b32 m0, s64
	s_nop 0
	global_load_lds_dwordx4 v[210:211], off
	v_lshl_add_u64 v[210:211], s[56:57], 0, v[138:139]
	s_add_i32 m0, s64, 0x2000
	s_nop 0
	global_load_lds_dwordx4 v[210:211], off
	v_lshl_add_u64 v[210:211], v[230:231], 0, s[48:49]
	s_mov_b32 m0, s80
	s_nop 0
	global_load_lds_dwordx4 v[210:211], off
	v_lshl_add_u64 v[210:211], v[232:233], 0, s[48:49]
	s_mov_b32 m0, s81
	s_nop 0
	global_load_lds_dwordx4 v[210:211], off
	s_waitcnt vmcnt(8)
	s_waitcnt lgkmcnt(0)
	s_barrier
	s_setprio 3
	s_waitcnt lgkmcnt(0)
	v_mfma_f32_16x16x32_bf16 v[62:65], v[134:137], v[182:185], v[62:65]
	v_mfma_f32_16x16x32_bf16 v[58:61], v[154:157], v[182:185], v[58:61]
	v_mfma_f32_16x16x32_bf16 v[46:49], v[134:137], v[190:193], v[46:49]
	v_mfma_f32_16x16x32_bf16 v[42:45], v[154:157], v[190:193], v[42:45]
	v_mfma_f32_16x16x32_bf16 v[30:33], v[134:137], v[198:201], v[30:33]
	v_mfma_f32_16x16x32_bf16 v[26:29], v[154:157], v[198:201], v[26:29]
	v_mfma_f32_16x16x32_bf16 v[14:17], v[134:137], v[206:209], v[14:17]
	v_mfma_f32_16x16x32_bf16 v[10:13], v[154:157], v[206:209], v[10:13]
	v_mfma_f32_16x16x32_bf16 v[62:65], v[150:153], v[186:189], v[62:65]
	v_mfma_f32_16x16x32_bf16 v[58:61], v[158:161], v[186:189], v[58:61]
	v_mfma_f32_16x16x32_bf16 v[46:49], v[150:153], v[194:197], v[46:49]
	v_mfma_f32_16x16x32_bf16 v[42:45], v[158:161], v[194:197], v[42:45]
	v_mfma_f32_16x16x32_bf16 v[30:33], v[150:153], v[202:205], v[30:33]
	v_mfma_f32_16x16x32_bf16 v[26:29], v[158:161], v[202:205], v[26:29]
	v_mfma_f32_16x16x32_bf16 v[14:17], v[150:153], v[224:227], v[14:17]
	v_mfma_f32_16x16x32_bf16 v[10:13], v[158:161], v[224:227], v[10:13]
	v_mfma_f32_16x16x32_bf16 v[54:57], v[162:165], v[182:185], v[54:57]
	v_mfma_f32_16x16x32_bf16 v[50:53], v[174:177], v[182:185], v[50:53]
	v_mfma_f32_16x16x32_bf16 v[38:41], v[162:165], v[190:193], v[38:41]
	v_mfma_f32_16x16x32_bf16 v[34:37], v[174:177], v[190:193], v[34:37]
	v_mfma_f32_16x16x32_bf16 v[22:25], v[162:165], v[198:201], v[22:25]
	v_mfma_f32_16x16x32_bf16 v[18:21], v[174:177], v[198:201], v[18:21]
	v_mfma_f32_16x16x32_bf16 v[6:9], v[162:165], v[206:209], v[6:9]
	v_mfma_f32_16x16x32_bf16 v[2:5], v[174:177], v[206:209], v[2:5]
	v_mfma_f32_16x16x32_bf16 v[54:57], v[170:173], v[186:189], v[54:57]
	v_mfma_f32_16x16x32_bf16 v[50:53], v[178:181], v[186:189], v[50:53]
	v_mfma_f32_16x16x32_bf16 v[38:41], v[170:173], v[194:197], v[38:41]
	v_mfma_f32_16x16x32_bf16 v[34:37], v[178:181], v[194:197], v[34:37]
	v_mfma_f32_16x16x32_bf16 v[22:25], v[170:173], v[202:205], v[22:25]
	v_mfma_f32_16x16x32_bf16 v[18:21], v[178:181], v[202:205], v[18:21]
	v_mfma_f32_16x16x32_bf16 v[6:9], v[170:173], v[224:227], v[6:9]
	v_mfma_f32_16x16x32_bf16 v[2:5], v[178:181], v[224:227], v[2:5]
	s_setprio 0
	s_barrier
	s_add_i32 s85, s85, 2
	s_add_u32 s52, s52, 0x100
	s_addc_u32 s53, s53, 0
	s_add_u32 s31, s31, 0x100
	s_addc_u32 s84, s84, 0
.LBB0_1459:
	s_add_u32 s56, s52, 0xfffc0080
	s_addc_u32 s57, s53, -1
	s_add_i32 s64, 0, 0x10000
	s_cmp_eq_u32 s85, 12
	s_cselect_b32 s69, s13, s57
	s_cselect_b32 s68, s27, s56
	v_add_u32_e32 v0, s64, v167
	s_cselect_b32 s57, s11, s84
	s_cselect_b32 s56, s30, s31
	s_add_i32 s86, 0, 0x14000
	ds_read_b128 v[134:137], v0
	ds_read_b128 v[150:153], v0 offset:1024
	ds_read_b128 v[154:157], v0 offset:2048
	ds_read_b128 v[158:161], v0 offset:3072
	v_add_u32_e32 v0, s86, v167
	ds_read_b128 v[162:165], v0
	ds_read_b128 v[170:173], v0 offset:1024
	ds_read_b128 v[174:177], v0 offset:2048
	ds_read_b128 v[178:181], v0 offset:3072
	v_lshl_add_u64 v[210:211], s[52:53], 0, v[146:147]
	s_add_i32 m0, s21, 0xc000
	ds_read_b128 v[182:185], v169
	ds_read_b128 v[186:189], v169 offset:1024
	ds_read_b128 v[190:193], v169 offset:2048
	ds_read_b128 v[194:197], v169 offset:3072
	ds_read_b128 v[198:201], v169 offset:4096
	ds_read_b128 v[202:205], v169 offset:5120
	ds_read_b128 v[206:209], v169 offset:6144
	ds_read_b128 v[224:227], v169 offset:7168
	global_load_lds_dwordx4 v[210:211], off
	v_lshl_add_u64 v[210:211], s[52:53], 0, v[148:149]
	s_add_i32 m0, s21, 0xe000
	s_nop 0
	global_load_lds_dwordx4 v[210:211], off
	s_waitcnt vmcnt(8)
	s_waitcnt lgkmcnt(0)
	s_barrier
	s_setprio 3
	s_waitcnt lgkmcnt(0)
	v_mfma_f32_16x16x32_bf16 v[126:129], v[134:137], v[182:185], v[126:129]
	v_mfma_f32_16x16x32_bf16 v[122:125], v[154:157], v[182:185], v[122:125]
	v_mfma_f32_16x16x32_bf16 v[110:113], v[134:137], v[190:193], v[110:113]
	v_mfma_f32_16x16x32_bf16 v[106:109], v[154:157], v[190:193], v[106:109]
	v_mfma_f32_16x16x32_bf16 v[94:97], v[134:137], v[198:201], v[94:97]
	v_mfma_f32_16x16x32_bf16 v[90:93], v[154:157], v[198:201], v[90:93]
	v_mfma_f32_16x16x32_bf16 v[78:81], v[134:137], v[206:209], v[78:81]
	v_mfma_f32_16x16x32_bf16 v[74:77], v[154:157], v[206:209], v[74:77]
	v_mfma_f32_16x16x32_bf16 v[126:129], v[150:153], v[186:189], v[126:129]
	v_mfma_f32_16x16x32_bf16 v[122:125], v[158:161], v[186:189], v[122:125]
	v_mfma_f32_16x16x32_bf16 v[110:113], v[150:153], v[194:197], v[110:113]
	v_mfma_f32_16x16x32_bf16 v[106:109], v[158:161], v[194:197], v[106:109]
	v_mfma_f32_16x16x32_bf16 v[94:97], v[150:153], v[202:205], v[94:97]
	v_mfma_f32_16x16x32_bf16 v[90:93], v[158:161], v[202:205], v[90:93]
	v_mfma_f32_16x16x32_bf16 v[78:81], v[150:153], v[224:227], v[78:81]
	v_mfma_f32_16x16x32_bf16 v[74:77], v[158:161], v[224:227], v[74:77]
	v_mfma_f32_16x16x32_bf16 v[118:121], v[162:165], v[182:185], v[118:121]
	v_mfma_f32_16x16x32_bf16 v[114:117], v[174:177], v[182:185], v[114:117]
	v_mfma_f32_16x16x32_bf16 v[102:105], v[162:165], v[190:193], v[102:105]
	v_mfma_f32_16x16x32_bf16 v[98:101], v[174:177], v[190:193], v[98:101]
	v_mfma_f32_16x16x32_bf16 v[86:89], v[162:165], v[198:201], v[86:89]
	v_mfma_f32_16x16x32_bf16 v[82:85], v[174:177], v[198:201], v[82:85]
	v_mfma_f32_16x16x32_bf16 v[70:73], v[162:165], v[206:209], v[70:73]
	v_mfma_f32_16x16x32_bf16 v[66:69], v[174:177], v[206:209], v[66:69]
	v_mfma_f32_16x16x32_bf16 v[118:121], v[170:173], v[186:189], v[118:121]
	v_mfma_f32_16x16x32_bf16 v[114:117], v[178:181], v[186:189], v[114:117]
	v_mfma_f32_16x16x32_bf16 v[102:105], v[170:173], v[194:197], v[102:105]
	v_mfma_f32_16x16x32_bf16 v[98:101], v[178:181], v[194:197], v[98:101]
	v_mfma_f32_16x16x32_bf16 v[86:89], v[170:173], v[202:205], v[86:89]
	v_mfma_f32_16x16x32_bf16 v[82:85], v[178:181], v[202:205], v[82:85]
	v_mfma_f32_16x16x32_bf16 v[70:73], v[170:173], v[224:227], v[70:73]
	v_mfma_f32_16x16x32_bf16 v[66:69], v[178:181], v[224:227], v[66:69]
	s_setprio 0
	s_barrier
	s_add_i32 s64, s64, s71
	v_lshl_add_u64 v[210:211], s[56:57], 0, v[142:143]
	s_mov_b32 m0, s64
	ds_read_b128 v[182:185], v169 offset:16384
	ds_read_b128 v[186:189], v169 offset:17408
	ds_read_b128 v[190:193], v169 offset:18432
	ds_read_b128 v[194:197], v169 offset:19456
	ds_read_b128 v[198:201], v169 offset:20480
	ds_read_b128 v[202:205], v169 offset:21504
	ds_read_b128 v[206:209], v169 offset:22528
	ds_read_b128 v[224:227], v169 offset:23552
	global_load_lds_dwordx4 v[210:211], off
	s_add_i32 m0, s64, 0x2000
	s_add_u32 s64, s56, 0x40000
	v_lshl_add_u64 v[228:229], s[56:57], 0, v[138:139]
	s_addc_u32 s65, s57, 0
	s_add_i32 s86, s86, s71
	global_load_lds_dwordx4 v[228:229], off
	v_lshl_add_u64 v[230:231], s[64:65], 0, v[142:143]
	s_mov_b32 m0, s86
	v_lshl_add_u64 v[232:233], s[68:69], 0, v[140:141]
	global_load_lds_dwordx4 v[230:231], off
	v_lshl_add_u64 v[230:231], s[64:65], 0, v[138:139]
	s_add_i32 m0, s86, 0x2000
	s_nop 0
	global_load_lds_dwordx4 v[230:231], off
	v_lshl_add_u64 v[230:231], s[68:69], 0, v[144:145]
	s_mov_b32 m0, s21
	s_nop 0
	global_load_lds_dwordx4 v[230:231], off
	s_mov_b32 m0, s73
	s_nop 0
	global_load_lds_dwordx4 v[232:233], off
	s_waitcnt vmcnt(8)
	s_waitcnt lgkmcnt(0)
	s_barrier
	s_setprio 3
	s_waitcnt lgkmcnt(0)
	v_mfma_f32_16x16x32_bf16 v[62:65], v[134:137], v[182:185], v[62:65]
	v_mfma_f32_16x16x32_bf16 v[58:61], v[154:157], v[182:185], v[58:61]
	v_mfma_f32_16x16x32_bf16 v[46:49], v[134:137], v[190:193], v[46:49]
	v_mfma_f32_16x16x32_bf16 v[42:45], v[154:157], v[190:193], v[42:45]
	v_mfma_f32_16x16x32_bf16 v[30:33], v[134:137], v[198:201], v[30:33]
	v_mfma_f32_16x16x32_bf16 v[26:29], v[154:157], v[198:201], v[26:29]
	v_mfma_f32_16x16x32_bf16 v[14:17], v[134:137], v[206:209], v[14:17]
	v_mfma_f32_16x16x32_bf16 v[10:13], v[154:157], v[206:209], v[10:13]
	v_mfma_f32_16x16x32_bf16 v[62:65], v[150:153], v[186:189], v[62:65]
	v_mfma_f32_16x16x32_bf16 v[58:61], v[158:161], v[186:189], v[58:61]
	v_mfma_f32_16x16x32_bf16 v[46:49], v[150:153], v[194:197], v[46:49]
	v_mfma_f32_16x16x32_bf16 v[42:45], v[158:161], v[194:197], v[42:45]
	v_mfma_f32_16x16x32_bf16 v[30:33], v[150:153], v[202:205], v[30:33]
	v_mfma_f32_16x16x32_bf16 v[26:29], v[158:161], v[202:205], v[26:29]
	v_mfma_f32_16x16x32_bf16 v[14:17], v[150:153], v[224:227], v[14:17]
	v_mfma_f32_16x16x32_bf16 v[10:13], v[158:161], v[224:227], v[10:13]
	v_mfma_f32_16x16x32_bf16 v[54:57], v[162:165], v[182:185], v[54:57]
	v_mfma_f32_16x16x32_bf16 v[50:53], v[174:177], v[182:185], v[50:53]
	v_mfma_f32_16x16x32_bf16 v[38:41], v[162:165], v[190:193], v[38:41]
	v_mfma_f32_16x16x32_bf16 v[34:37], v[174:177], v[190:193], v[34:37]
	v_mfma_f32_16x16x32_bf16 v[22:25], v[162:165], v[198:201], v[22:25]
	v_mfma_f32_16x16x32_bf16 v[18:21], v[174:177], v[198:201], v[18:21]
	v_mfma_f32_16x16x32_bf16 v[6:9], v[162:165], v[206:209], v[6:9]
	v_mfma_f32_16x16x32_bf16 v[2:5], v[174:177], v[206:209], v[2:5]
	v_mfma_f32_16x16x32_bf16 v[54:57], v[170:173], v[186:189], v[54:57]
	v_mfma_f32_16x16x32_bf16 v[50:53], v[178:181], v[186:189], v[50:53]
	v_mfma_f32_16x16x32_bf16 v[38:41], v[170:173], v[194:197], v[38:41]
	v_mfma_f32_16x16x32_bf16 v[34:37], v[178:181], v[194:197], v[34:37]
	v_mfma_f32_16x16x32_bf16 v[22:25], v[170:173], v[202:205], v[22:25]
	v_mfma_f32_16x16x32_bf16 v[18:21], v[178:181], v[202:205], v[18:21]
	v_mfma_f32_16x16x32_bf16 v[6:9], v[170:173], v[224:227], v[6:9]
	v_mfma_f32_16x16x32_bf16 v[2:5], v[178:181], v[224:227], v[2:5]
	s_setprio 0
	s_barrier
	s_add_i32 s86, 0, 0x18000
	v_add_u32_e32 v0, s86, v167
	s_add_i32 s87, 0, 0x1c000
	ds_read_b128 v[134:137], v0
	ds_read_b128 v[150:153], v0 offset:1024
	ds_read_b128 v[154:157], v0 offset:2048
	ds_read_b128 v[158:161], v0 offset:3072
	v_add_u32_e32 v0, s87, v167
	ds_read_b128 v[162:165], v0
	ds_read_b128 v[170:173], v0 offset:1024
	ds_read_b128 v[174:177], v0 offset:2048
	ds_read_b128 v[178:181], v0 offset:3072
	s_add_u32 s64, s68, 0x40000
	s_addc_u32 s65, s69, 0
	s_mov_b32 m0, s74
	v_lshl_add_u64 v[234:235], s[64:65], 0, v[144:145]
	ds_read_b128 v[182:185], v169 offset:32768
	ds_read_b128 v[186:189], v169 offset:33792
	ds_read_b128 v[190:193], v169 offset:34816
	ds_read_b128 v[194:197], v169 offset:35840
	ds_read_b128 v[198:201], v169 offset:36864
	ds_read_b128 v[202:205], v169 offset:37888
	ds_read_b128 v[206:209], v169 offset:38912
	ds_read_b128 v[224:227], v169 offset:39936
	global_load_lds_dwordx4 v[234:235], off
	v_lshl_add_u64 v[234:235], s[64:65], 0, v[140:141]
	s_mov_b32 m0, s75
	s_nop 0
	global_load_lds_dwordx4 v[234:235], off
	s_waitcnt vmcnt(8)
	s_waitcnt lgkmcnt(0)
	s_barrier
	s_setprio 3
	s_waitcnt lgkmcnt(0)
	v_mfma_f32_16x16x32_bf16 v[126:129], v[134:137], v[182:185], v[126:129]
	v_mfma_f32_16x16x32_bf16 v[122:125], v[154:157], v[182:185], v[122:125]
	v_mfma_f32_16x16x32_bf16 v[110:113], v[134:137], v[190:193], v[110:113]
	v_mfma_f32_16x16x32_bf16 v[106:109], v[154:157], v[190:193], v[106:109]
	v_mfma_f32_16x16x32_bf16 v[94:97], v[134:137], v[198:201], v[94:97]
	v_mfma_f32_16x16x32_bf16 v[90:93], v[154:157], v[198:201], v[90:93]
	v_mfma_f32_16x16x32_bf16 v[78:81], v[134:137], v[206:209], v[78:81]
	v_mfma_f32_16x16x32_bf16 v[74:77], v[154:157], v[206:209], v[74:77]
	v_mfma_f32_16x16x32_bf16 v[126:129], v[150:153], v[186:189], v[126:129]
	v_mfma_f32_16x16x32_bf16 v[122:125], v[158:161], v[186:189], v[122:125]
	v_mfma_f32_16x16x32_bf16 v[110:113], v[150:153], v[194:197], v[110:113]
	v_mfma_f32_16x16x32_bf16 v[106:109], v[158:161], v[194:197], v[106:109]
	v_mfma_f32_16x16x32_bf16 v[94:97], v[150:153], v[202:205], v[94:97]
	v_mfma_f32_16x16x32_bf16 v[90:93], v[158:161], v[202:205], v[90:93]
	v_mfma_f32_16x16x32_bf16 v[78:81], v[150:153], v[224:227], v[78:81]
	v_mfma_f32_16x16x32_bf16 v[74:77], v[158:161], v[224:227], v[74:77]
	v_mfma_f32_16x16x32_bf16 v[118:121], v[162:165], v[182:185], v[118:121]
	v_mfma_f32_16x16x32_bf16 v[114:117], v[174:177], v[182:185], v[114:117]
	v_mfma_f32_16x16x32_bf16 v[102:105], v[162:165], v[190:193], v[102:105]
	v_mfma_f32_16x16x32_bf16 v[98:101], v[174:177], v[190:193], v[98:101]
	v_mfma_f32_16x16x32_bf16 v[86:89], v[162:165], v[198:201], v[86:89]
	v_mfma_f32_16x16x32_bf16 v[82:85], v[174:177], v[198:201], v[82:85]
	v_mfma_f32_16x16x32_bf16 v[70:73], v[162:165], v[206:209], v[70:73]
	v_mfma_f32_16x16x32_bf16 v[66:69], v[174:177], v[206:209], v[66:69]
	v_mfma_f32_16x16x32_bf16 v[118:121], v[170:173], v[186:189], v[118:121]
	v_mfma_f32_16x16x32_bf16 v[114:117], v[178:181], v[186:189], v[114:117]
	v_mfma_f32_16x16x32_bf16 v[102:105], v[170:173], v[194:197], v[102:105]
	v_mfma_f32_16x16x32_bf16 v[98:101], v[178:181], v[194:197], v[98:101]
	v_mfma_f32_16x16x32_bf16 v[86:89], v[170:173], v[202:205], v[86:89]
	v_mfma_f32_16x16x32_bf16 v[82:85], v[178:181], v[202:205], v[82:85]
	v_mfma_f32_16x16x32_bf16 v[70:73], v[170:173], v[224:227], v[70:73]
	v_mfma_f32_16x16x32_bf16 v[66:69], v[178:181], v[224:227], v[66:69]
	s_setprio 0
	s_barrier
	s_add_i32 s64, s86, s71
	v_lshl_add_u64 v[210:211], v[210:211], 0, s[48:49]
	s_mov_b32 m0, s64
	ds_read_b128 v[182:185], v169 offset:49152
	ds_read_b128 v[186:189], v169 offset:50176
	ds_read_b128 v[190:193], v169 offset:51200
	ds_read_b128 v[194:197], v169 offset:52224
	ds_read_b128 v[198:201], v169 offset:53248
	ds_read_b128 v[202:205], v169 offset:54272
	ds_read_b128 v[206:209], v169 offset:55296
	ds_read_b128 v[224:227], v169 offset:56320
	global_load_lds_dwordx4 v[210:211], off
	s_add_i32 m0, s64, 0x2000
	s_add_u32 s56, s56, 0x40080
	v_lshl_add_u64 v[210:211], v[228:229], 0, s[48:49]
	s_addc_u32 s57, s57, 0
	s_add_i32 s64, s87, s71
	global_load_lds_dwordx4 v[210:211], off
	v_lshl_add_u64 v[210:211], s[56:57], 0, v[142:143]
	s_mov_b32 m0, s64
	s_nop 0
	global_load_lds_dwordx4 v[210:211], off
	v_lshl_add_u64 v[210:211], s[56:57], 0, v[138:139]
	s_add_i32 m0, s64, 0x2000
	s_nop 0
	global_load_lds_dwordx4 v[210:211], off
	v_lshl_add_u64 v[210:211], v[230:231], 0, s[48:49]
	s_mov_b32 m0, s80
	s_nop 0
	global_load_lds_dwordx4 v[210:211], off
	v_lshl_add_u64 v[210:211], v[232:233], 0, s[48:49]
	s_mov_b32 m0, s81
	s_nop 0
	global_load_lds_dwordx4 v[210:211], off
	s_waitcnt vmcnt(8)
	s_waitcnt lgkmcnt(0)
	s_barrier
	s_setprio 3
	s_waitcnt lgkmcnt(0)
	v_mfma_f32_16x16x32_bf16 v[62:65], v[134:137], v[182:185], v[62:65]
	v_mfma_f32_16x16x32_bf16 v[58:61], v[154:157], v[182:185], v[58:61]
	v_mfma_f32_16x16x32_bf16 v[46:49], v[134:137], v[190:193], v[46:49]
	v_mfma_f32_16x16x32_bf16 v[42:45], v[154:157], v[190:193], v[42:45]
	v_mfma_f32_16x16x32_bf16 v[30:33], v[134:137], v[198:201], v[30:33]
	v_mfma_f32_16x16x32_bf16 v[26:29], v[154:157], v[198:201], v[26:29]
	v_mfma_f32_16x16x32_bf16 v[14:17], v[134:137], v[206:209], v[14:17]
	v_mfma_f32_16x16x32_bf16 v[10:13], v[154:157], v[206:209], v[10:13]
	v_mfma_f32_16x16x32_bf16 v[62:65], v[150:153], v[186:189], v[62:65]
	v_mfma_f32_16x16x32_bf16 v[58:61], v[158:161], v[186:189], v[58:61]
	v_mfma_f32_16x16x32_bf16 v[46:49], v[150:153], v[194:197], v[46:49]
	v_mfma_f32_16x16x32_bf16 v[42:45], v[158:161], v[194:197], v[42:45]
	v_mfma_f32_16x16x32_bf16 v[30:33], v[150:153], v[202:205], v[30:33]
	v_mfma_f32_16x16x32_bf16 v[26:29], v[158:161], v[202:205], v[26:29]
	v_mfma_f32_16x16x32_bf16 v[14:17], v[150:153], v[224:227], v[14:17]
	v_mfma_f32_16x16x32_bf16 v[10:13], v[158:161], v[224:227], v[10:13]
	v_mfma_f32_16x16x32_bf16 v[54:57], v[162:165], v[182:185], v[54:57]
	v_mfma_f32_16x16x32_bf16 v[50:53], v[174:177], v[182:185], v[50:53]
	v_mfma_f32_16x16x32_bf16 v[38:41], v[162:165], v[190:193], v[38:41]
	v_mfma_f32_16x16x32_bf16 v[34:37], v[174:177], v[190:193], v[34:37]
	v_mfma_f32_16x16x32_bf16 v[22:25], v[162:165], v[198:201], v[22:25]
	v_mfma_f32_16x16x32_bf16 v[18:21], v[174:177], v[198:201], v[18:21]
	v_mfma_f32_16x16x32_bf16 v[6:9], v[162:165], v[206:209], v[6:9]
	v_mfma_f32_16x16x32_bf16 v[2:5], v[174:177], v[206:209], v[2:5]
	v_mfma_f32_16x16x32_bf16 v[54:57], v[170:173], v[186:189], v[54:57]
	v_mfma_f32_16x16x32_bf16 v[50:53], v[178:181], v[186:189], v[50:53]
	v_mfma_f32_16x16x32_bf16 v[38:41], v[170:173], v[194:197], v[38:41]
	v_mfma_f32_16x16x32_bf16 v[34:37], v[178:181], v[194:197], v[34:37]
	v_mfma_f32_16x16x32_bf16 v[22:25], v[170:173], v[202:205], v[22:25]
	v_mfma_f32_16x16x32_bf16 v[18:21], v[178:181], v[202:205], v[18:21]
	v_mfma_f32_16x16x32_bf16 v[6:9], v[170:173], v[224:227], v[6:9]
	v_mfma_f32_16x16x32_bf16 v[2:5], v[178:181], v[224:227], v[2:5]
	s_setprio 0
	s_barrier
	s_add_i32 s85, s85, 2
	s_add_u32 s52, s52, 0x100
	s_addc_u32 s53, s53, 0
	s_add_u32 s31, s31, 0x100
	s_addc_u32 s84, s84, 0
	s_cmp_gt_u32 s85, 13
	s_cbranch_scc0 .LBB0_1459
	s_and_b64 vcc, exec, s[6:7]
	s_cbranch_vccz .LBB0_1462
	s_barrier

.LBB0_1532:
	s_ashr_i32 s17, s16, 31
	s_lshl_b64 s[56:57], s[16:17], 18
	s_add_u32 s56, s37, s56
	s_addc_u32 s57, s60, s57
	s_and_b64 s[6:7], s[6:7], exec
	s_cselect_b32 s17, s57, s69
	s_cselect_b32 s19, s56, s68
	s_add_u32 s6, s70, 0x20080
	s_addc_u32 s7, s71, 0
	s_add_u32 s80, s68, 0x100
	s_addc_u32 s81, s69, 0
	s_mov_b32 s82, -2
	s_add_u32 s64, s6, 0xfffe0080
	s_addc_u32 s65, s7, -1
	s_add_i32 s83, 0, 0x10000
	s_cmp_eq_u32 s82, 4
	s_cselect_b32 s71, s53, s65
	s_cselect_b32 s70, s52, s64
	v_add_u32_e32 v144, s83, v147
	s_cselect_b32 s69, s17, s81
	s_cselect_b32 s68, s19, s80
	s_add_i32 s84, 0, 0x14000
	ds_read_b128 v[150:153], v144
	ds_read_b128 v[154:157], v144 offset:1024
	ds_read_b128 v[158:161], v144 offset:2048
	ds_read_b128 v[162:165], v144 offset:3072
	v_add_u32_e32 v144, s84, v147
	ds_read_b128 v[166:169], v144
	ds_read_b128 v[170:173], v144 offset:1024
	ds_read_b128 v[174:177], v144 offset:2048
	ds_read_b128 v[178:181], v144 offset:3072
	v_lshl_add_u64 v[144:145], s[6:7], 0, v[140:141]
	s_add_i32 m0, s21, 0xc000
	ds_read_b128 v[182:185], v149
	ds_read_b128 v[186:189], v149 offset:1024
	ds_read_b128 v[190:193], v149 offset:2048
	ds_read_b128 v[194:197], v149 offset:3072
	ds_read_b128 v[198:201], v149 offset:4096
	ds_read_b128 v[202:205], v149 offset:5120
	ds_read_b128 v[206:209], v149 offset:6144
	ds_read_b128 v[224:227], v149 offset:7168
	global_load_lds_dwordx4 v[144:145], off
	v_lshl_add_u64 v[144:145], s[6:7], 0, v[142:143]
	s_add_i32 m0, s21, 0xe000
	s_nop 0
	global_load_lds_dwordx4 v[144:145], off
	s_waitcnt vmcnt(8)
	s_waitcnt lgkmcnt(0)
	s_barrier
	s_setprio 3
	s_waitcnt lgkmcnt(0)
	v_mfma_f32_16x16x32_bf16 v[126:129], v[150:153], v[182:185], 0
	v_mfma_f32_16x16x32_bf16 v[122:125], v[158:161], v[182:185], 0
	v_mfma_f32_16x16x32_bf16 v[118:121], v[150:153], v[190:193], 0
	v_mfma_f32_16x16x32_bf16 v[110:113], v[158:161], v[190:193], 0
	v_mfma_f32_16x16x32_bf16 v[102:105], v[150:153], v[198:201], 0
	v_mfma_f32_16x16x32_bf16 v[94:97], v[158:161], v[198:201], 0
	v_mfma_f32_16x16x32_bf16 v[86:89], v[150:153], v[206:209], 0
	v_mfma_f32_16x16x32_bf16 v[78:81], v[158:161], v[206:209], 0
	v_mfma_f32_16x16x32_bf16 v[126:129], v[154:157], v[186:189], v[126:129]
	v_mfma_f32_16x16x32_bf16 v[122:125], v[162:165], v[186:189], v[122:125]
	v_mfma_f32_16x16x32_bf16 v[118:121], v[154:157], v[194:197], v[118:121]
	v_mfma_f32_16x16x32_bf16 v[110:113], v[162:165], v[194:197], v[110:113]
	v_mfma_f32_16x16x32_bf16 v[102:105], v[154:157], v[202:205], v[102:105]
	v_mfma_f32_16x16x32_bf16 v[94:97], v[162:165], v[202:205], v[94:97]
	v_mfma_f32_16x16x32_bf16 v[86:89], v[154:157], v[224:227], v[86:89]
	v_mfma_f32_16x16x32_bf16 v[78:81], v[162:165], v[224:227], v[78:81]
	v_mfma_f32_16x16x32_bf16 v[114:117], v[166:169], v[182:185], 0
	v_mfma_f32_16x16x32_bf16 v[106:109], v[174:177], v[182:185], 0
	v_mfma_f32_16x16x32_bf16 v[98:101], v[166:169], v[190:193], 0
	v_mfma_f32_16x16x32_bf16 v[90:93], v[174:177], v[190:193], 0
	v_mfma_f32_16x16x32_bf16 v[82:85], v[166:169], v[198:201], 0
	v_mfma_f32_16x16x32_bf16 v[74:77], v[174:177], v[198:201], 0
	v_mfma_f32_16x16x32_bf16 v[70:73], v[166:169], v[206:209], 0
	v_mfma_f32_16x16x32_bf16 v[66:69], v[174:177], v[206:209], 0
	v_mfma_f32_16x16x32_bf16 v[114:117], v[170:173], v[186:189], v[114:117]
	v_mfma_f32_16x16x32_bf16 v[106:109], v[178:181], v[186:189], v[106:109]
	v_mfma_f32_16x16x32_bf16 v[98:101], v[170:173], v[194:197], v[98:101]
	v_mfma_f32_16x16x32_bf16 v[90:93], v[178:181], v[194:197], v[90:93]
	v_mfma_f32_16x16x32_bf16 v[82:85], v[170:173], v[202:205], v[82:85]
	v_mfma_f32_16x16x32_bf16 v[74:77], v[178:181], v[202:205], v[74:77]
	v_mfma_f32_16x16x32_bf16 v[70:73], v[170:173], v[224:227], v[70:73]
	v_mfma_f32_16x16x32_bf16 v[66:69], v[178:181], v[224:227], v[66:69]
	s_setprio 0
	s_barrier
	s_add_i32 s64, s83, s63
	v_lshl_add_u64 v[144:145], s[68:69], 0, v[0:1]
	s_mov_b32 m0, s64
	ds_read_b128 v[182:185], v149 offset:16384
	ds_read_b128 v[186:189], v149 offset:17408
	ds_read_b128 v[190:193], v149 offset:18432
	ds_read_b128 v[194:197], v149 offset:19456
	ds_read_b128 v[198:201], v149 offset:20480
	ds_read_b128 v[202:205], v149 offset:21504
	ds_read_b128 v[206:209], v149 offset:22528
	ds_read_b128 v[224:227], v149 offset:23552
	global_load_lds_dwordx4 v[144:145], off
	s_add_i32 m0, s64, 0x2000
	s_add_u32 s64, s68, 0x20000
	v_lshl_add_u64 v[210:211], s[68:69], 0, v[134:135]
	s_addc_u32 s65, s69, 0
	s_add_i32 s83, s84, s63
	global_load_lds_dwordx4 v[210:211], off
	v_lshl_add_u64 v[220:221], s[64:65], 0, v[0:1]
	s_mov_b32 m0, s83
	v_lshl_add_u64 v[228:229], s[70:71], 0, v[136:137]
	global_load_lds_dwordx4 v[220:221], off
	v_lshl_add_u64 v[220:221], s[64:65], 0, v[134:135]
	s_add_i32 m0, s83, 0x2000
	s_nop 0
	global_load_lds_dwordx4 v[220:221], off
	v_lshl_add_u64 v[220:221], s[70:71], 0, v[138:139]
	s_mov_b32 m0, s21
	s_nop 0
	global_load_lds_dwordx4 v[220:221], off
	s_mov_b32 m0, s27
	s_nop 0
	global_load_lds_dwordx4 v[228:229], off
	s_waitcnt vmcnt(8)
	s_waitcnt lgkmcnt(0)
	s_barrier
	s_setprio 3
	s_waitcnt lgkmcnt(0)
	v_mfma_f32_16x16x32_bf16 v[62:65], v[150:153], v[182:185], 0
	v_mfma_f32_16x16x32_bf16 v[58:61], v[158:161], v[182:185], 0
	v_mfma_f32_16x16x32_bf16 v[54:57], v[150:153], v[190:193], 0
	v_mfma_f32_16x16x32_bf16 v[46:49], v[158:161], v[190:193], 0
	v_mfma_f32_16x16x32_bf16 v[38:41], v[150:153], v[198:201], 0
	v_mfma_f32_16x16x32_bf16 v[30:33], v[158:161], v[198:201], 0
	v_mfma_f32_16x16x32_bf16 v[22:25], v[150:153], v[206:209], 0
	v_mfma_f32_16x16x32_bf16 v[14:17], v[158:161], v[206:209], 0
	v_mfma_f32_16x16x32_bf16 v[62:65], v[154:157], v[186:189], v[62:65]
	v_mfma_f32_16x16x32_bf16 v[58:61], v[162:165], v[186:189], v[58:61]
	v_mfma_f32_16x16x32_bf16 v[54:57], v[154:157], v[194:197], v[54:57]
	v_mfma_f32_16x16x32_bf16 v[46:49], v[162:165], v[194:197], v[46:49]
	v_mfma_f32_16x16x32_bf16 v[38:41], v[154:157], v[202:205], v[38:41]
	v_mfma_f32_16x16x32_bf16 v[30:33], v[162:165], v[202:205], v[30:33]
	v_mfma_f32_16x16x32_bf16 v[22:25], v[154:157], v[224:227], v[22:25]
	v_mfma_f32_16x16x32_bf16 v[14:17], v[162:165], v[224:227], v[14:17]
	v_mfma_f32_16x16x32_bf16 v[50:53], v[166:169], v[182:185], 0
	v_mfma_f32_16x16x32_bf16 v[42:45], v[174:177], v[182:185], 0
	v_mfma_f32_16x16x32_bf16 v[34:37], v[166:169], v[190:193], 0
	v_mfma_f32_16x16x32_bf16 v[26:29], v[174:177], v[190:193], 0
	v_mfma_f32_16x16x32_bf16 v[18:21], v[166:169], v[198:201], 0
	v_mfma_f32_16x16x32_bf16 v[10:13], v[174:177], v[198:201], 0
	v_mfma_f32_16x16x32_bf16 v[6:9], v[166:169], v[206:209], 0
	v_mfma_f32_16x16x32_bf16 v[2:5], v[174:177], v[206:209], 0
	v_mfma_f32_16x16x32_bf16 v[50:53], v[170:173], v[186:189], v[50:53]
	v_mfma_f32_16x16x32_bf16 v[42:45], v[178:181], v[186:189], v[42:45]
	v_mfma_f32_16x16x32_bf16 v[34:37], v[170:173], v[194:197], v[34:37]
	v_mfma_f32_16x16x32_bf16 v[26:29], v[178:181], v[194:197], v[26:29]
	v_mfma_f32_16x16x32_bf16 v[18:21], v[170:173], v[202:205], v[18:21]
	v_mfma_f32_16x16x32_bf16 v[10:13], v[178:181], v[202:205], v[10:13]
	v_mfma_f32_16x16x32_bf16 v[6:9], v[170:173], v[224:227], v[6:9]
	v_mfma_f32_16x16x32_bf16 v[2:5], v[178:181], v[224:227], v[2:5]
	s_setprio 0
	s_barrier
	s_add_i32 s83, 0, 0x18000
	s_add_i32 s84, 0, 0x1c000
	v_add_u32_e32 v162, s83, v147
	v_add_u32_e32 v178, s84, v147
	ds_read_b128 v[150:153], v162
	ds_read_b128 v[154:157], v162 offset:1024
	ds_read_b128 v[158:161], v162 offset:2048
	ds_read_b128 v[162:165], v162 offset:3072
	ds_read_b128 v[166:169], v178
	ds_read_b128 v[170:173], v178 offset:1024
	ds_read_b128 v[174:177], v178 offset:2048
	ds_read_b128 v[178:181], v178 offset:3072
	s_add_u32 s64, s70, 0x20000
	s_addc_u32 s65, s71, 0
	s_mov_b32 m0, s72
	v_lshl_add_u64 v[230:231], s[64:65], 0, v[138:139]
	ds_read_b128 v[182:185], v149 offset:32768
	ds_read_b128 v[186:189], v149 offset:33792
	ds_read_b128 v[190:193], v149 offset:34816
	ds_read_b128 v[194:197], v149 offset:35840
	ds_read_b128 v[198:201], v149 offset:36864
	ds_read_b128 v[202:205], v149 offset:37888
	ds_read_b128 v[206:209], v149 offset:38912
	ds_read_b128 v[224:227], v149 offset:39936
	global_load_lds_dwordx4 v[230:231], off
	v_lshl_add_u64 v[230:231], s[64:65], 0, v[136:137]
	s_mov_b32 m0, s73
	s_nop 0
	global_load_lds_dwordx4 v[230:231], off
	s_waitcnt vmcnt(8)
	s_waitcnt lgkmcnt(0)
	s_barrier
	s_setprio 3
	s_waitcnt lgkmcnt(0)
	v_mfma_f32_16x16x32_bf16 v[126:129], v[150:153], v[182:185], v[126:129]
	v_mfma_f32_16x16x32_bf16 v[122:125], v[158:161], v[182:185], v[122:125]
	v_mfma_f32_16x16x32_bf16 v[118:121], v[150:153], v[190:193], v[118:121]
	v_mfma_f32_16x16x32_bf16 v[110:113], v[158:161], v[190:193], v[110:113]
	v_mfma_f32_16x16x32_bf16 v[102:105], v[150:153], v[198:201], v[102:105]
	v_mfma_f32_16x16x32_bf16 v[94:97], v[158:161], v[198:201], v[94:97]
	v_mfma_f32_16x16x32_bf16 v[86:89], v[150:153], v[206:209], v[86:89]
	v_mfma_f32_16x16x32_bf16 v[78:81], v[158:161], v[206:209], v[78:81]
	v_mfma_f32_16x16x32_bf16 v[126:129], v[154:157], v[186:189], v[126:129]
	v_mfma_f32_16x16x32_bf16 v[122:125], v[162:165], v[186:189], v[122:125]
	v_mfma_f32_16x16x32_bf16 v[118:121], v[154:157], v[194:197], v[118:121]
	v_mfma_f32_16x16x32_bf16 v[110:113], v[162:165], v[194:197], v[110:113]
	v_mfma_f32_16x16x32_bf16 v[102:105], v[154:157], v[202:205], v[102:105]
	v_mfma_f32_16x16x32_bf16 v[94:97], v[162:165], v[202:205], v[94:97]
	v_mfma_f32_16x16x32_bf16 v[86:89], v[154:157], v[224:227], v[86:89]
	v_mfma_f32_16x16x32_bf16 v[78:81], v[162:165], v[224:227], v[78:81]
	v_mfma_f32_16x16x32_bf16 v[114:117], v[166:169], v[182:185], v[114:117]
	v_mfma_f32_16x16x32_bf16 v[106:109], v[174:177], v[182:185], v[106:109]
	v_mfma_f32_16x16x32_bf16 v[98:101], v[166:169], v[190:193], v[98:101]
	v_mfma_f32_16x16x32_bf16 v[90:93], v[174:177], v[190:193], v[90:93]
	v_mfma_f32_16x16x32_bf16 v[82:85], v[166:169], v[198:201], v[82:85]
	v_mfma_f32_16x16x32_bf16 v[74:77], v[174:177], v[198:201], v[74:77]
	v_mfma_f32_16x16x32_bf16 v[70:73], v[166:169], v[206:209], v[70:73]
	v_mfma_f32_16x16x32_bf16 v[66:69], v[174:177], v[206:209], v[66:69]
	v_mfma_f32_16x16x32_bf16 v[114:117], v[170:173], v[186:189], v[114:117]
	v_mfma_f32_16x16x32_bf16 v[106:109], v[178:181], v[186:189], v[106:109]
	v_mfma_f32_16x16x32_bf16 v[98:101], v[170:173], v[194:197], v[98:101]
	v_mfma_f32_16x16x32_bf16 v[90:93], v[178:181], v[194:197], v[90:93]
	v_mfma_f32_16x16x32_bf16 v[82:85], v[170:173], v[202:205], v[82:85]
	v_mfma_f32_16x16x32_bf16 v[74:77], v[178:181], v[202:205], v[74:77]
	v_mfma_f32_16x16x32_bf16 v[70:73], v[170:173], v[224:227], v[70:73]
	v_mfma_f32_16x16x32_bf16 v[66:69], v[178:181], v[224:227], v[66:69]
	s_setprio 0
	s_barrier
	s_add_i32 s64, s83, s63
	v_lshl_add_u64 v[144:145], v[144:145], 0, s[48:49]
	s_mov_b32 m0, s64
	ds_read_b128 v[182:185], v149 offset:49152
	ds_read_b128 v[186:189], v149 offset:50176
	ds_read_b128 v[190:193], v149 offset:51200
	ds_read_b128 v[194:197], v149 offset:52224
	ds_read_b128 v[198:201], v149 offset:53248
	ds_read_b128 v[202:205], v149 offset:54272
	ds_read_b128 v[206:209], v149 offset:55296
	ds_read_b128 v[224:227], v149 offset:56320
	global_load_lds_dwordx4 v[144:145], off
	s_add_i32 m0, s64, 0x2000
	s_add_u32 s64, s68, 0x20080
	v_lshl_add_u64 v[144:145], v[210:211], 0, s[48:49]
	s_addc_u32 s65, s69, 0
	s_add_i32 s68, s84, s63
	global_load_lds_dwordx4 v[144:145], off
	v_lshl_add_u64 v[144:145], s[64:65], 0, v[0:1]
	s_mov_b32 m0, s68
	s_nop 0
	global_load_lds_dwordx4 v[144:145], off
	v_lshl_add_u64 v[144:145], s[64:65], 0, v[134:135]
	s_add_i32 m0, s68, 0x2000
	s_nop 0
	global_load_lds_dwordx4 v[144:145], off
	v_lshl_add_u64 v[144:145], v[220:221], 0, s[48:49]
	s_mov_b32 m0, s74
	s_nop 0
	global_load_lds_dwordx4 v[144:145], off
	v_lshl_add_u64 v[144:145], v[228:229], 0, s[48:49]
	s_mov_b32 m0, s75
	s_nop 0
	global_load_lds_dwordx4 v[144:145], off
	s_waitcnt vmcnt(8)
	s_waitcnt lgkmcnt(0)
	s_barrier
	s_setprio 3
	s_waitcnt lgkmcnt(0)
	v_mfma_f32_16x16x32_bf16 v[62:65], v[150:153], v[182:185], v[62:65]
	v_mfma_f32_16x16x32_bf16 v[58:61], v[158:161], v[182:185], v[58:61]
	v_mfma_f32_16x16x32_bf16 v[54:57], v[150:153], v[190:193], v[54:57]
	v_mfma_f32_16x16x32_bf16 v[46:49], v[158:161], v[190:193], v[46:49]
	v_mfma_f32_16x16x32_bf16 v[38:41], v[150:153], v[198:201], v[38:41]
	v_mfma_f32_16x16x32_bf16 v[30:33], v[158:161], v[198:201], v[30:33]
	v_mfma_f32_16x16x32_bf16 v[22:25], v[150:153], v[206:209], v[22:25]
	v_mfma_f32_16x16x32_bf16 v[14:17], v[158:161], v[206:209], v[14:17]
	v_mfma_f32_16x16x32_bf16 v[62:65], v[154:157], v[186:189], v[62:65]
	v_mfma_f32_16x16x32_bf16 v[58:61], v[162:165], v[186:189], v[58:61]
	v_mfma_f32_16x16x32_bf16 v[54:57], v[154:157], v[194:197], v[54:57]
	v_mfma_f32_16x16x32_bf16 v[46:49], v[162:165], v[194:197], v[46:49]
	v_mfma_f32_16x16x32_bf16 v[38:41], v[154:157], v[202:205], v[38:41]
	v_mfma_f32_16x16x32_bf16 v[30:33], v[162:165], v[202:205], v[30:33]
	v_mfma_f32_16x16x32_bf16 v[22:25], v[154:157], v[224:227], v[22:25]
	v_mfma_f32_16x16x32_bf16 v[14:17], v[162:165], v[224:227], v[14:17]
	v_mfma_f32_16x16x32_bf16 v[50:53], v[166:169], v[182:185], v[50:53]
	v_mfma_f32_16x16x32_bf16 v[42:45], v[174:177], v[182:185], v[42:45]
	v_mfma_f32_16x16x32_bf16 v[34:37], v[166:169], v[190:193], v[34:37]
	v_mfma_f32_16x16x32_bf16 v[26:29], v[174:177], v[190:193], v[26:29]
	v_mfma_f32_16x16x32_bf16 v[18:21], v[166:169], v[198:201], v[18:21]
	v_mfma_f32_16x16x32_bf16 v[10:13], v[174:177], v[198:201], v[10:13]
	v_mfma_f32_16x16x32_bf16 v[6:9], v[166:169], v[206:209], v[6:9]
	v_mfma_f32_16x16x32_bf16 v[2:5], v[174:177], v[206:209], v[2:5]
	v_mfma_f32_16x16x32_bf16 v[50:53], v[170:173], v[186:189], v[50:53]
	v_mfma_f32_16x16x32_bf16 v[42:45], v[178:181], v[186:189], v[42:45]
	v_mfma_f32_16x16x32_bf16 v[34:37], v[170:173], v[194:197], v[34:37]
	v_mfma_f32_16x16x32_bf16 v[26:29], v[178:181], v[194:197], v[26:29]
	v_mfma_f32_16x16x32_bf16 v[18:21], v[170:173], v[202:205], v[18:21]
	v_mfma_f32_16x16x32_bf16 v[10:13], v[178:181], v[202:205], v[10:13]
	v_mfma_f32_16x16x32_bf16 v[6:9], v[170:173], v[224:227], v[6:9]
	v_mfma_f32_16x16x32_bf16 v[2:5], v[178:181], v[224:227], v[2:5]
	s_setprio 0
	s_barrier
	s_add_i32 s82, s82, 2
	s_add_u32 s6, s6, 0x100
	s_addc_u32 s7, s7, 0
	s_add_u32 s80, s80, 0x100
	s_addc_u32 s81, s81, 0
.LBB0_1533:
	s_add_u32 s64, s6, 0xfffe0080
	s_addc_u32 s65, s7, -1
	s_add_i32 s83, 0, 0x10000
	s_cmp_eq_u32 s82, 4
	s_cselect_b32 s71, s53, s65
	s_cselect_b32 s70, s52, s64
	v_add_u32_e32 v144, s83, v147
	s_cselect_b32 s69, s17, s81
	s_cselect_b32 s68, s19, s80
	s_add_i32 s84, 0, 0x14000
	ds_read_b128 v[150:153], v144
	ds_read_b128 v[154:157], v144 offset:1024
	ds_read_b128 v[158:161], v144 offset:2048
	ds_read_b128 v[162:165], v144 offset:3072
	v_add_u32_e32 v144, s84, v147
	ds_read_b128 v[166:169], v144
	ds_read_b128 v[170:173], v144 offset:1024
	ds_read_b128 v[174:177], v144 offset:2048
	ds_read_b128 v[178:181], v144 offset:3072
	v_lshl_add_u64 v[144:145], s[6:7], 0, v[140:141]
	s_add_i32 m0, s21, 0xc000
	ds_read_b128 v[182:185], v149
	ds_read_b128 v[186:189], v149 offset:1024
	ds_read_b128 v[190:193], v149 offset:2048
	ds_read_b128 v[194:197], v149 offset:3072
	ds_read_b128 v[198:201], v149 offset:4096
	ds_read_b128 v[202:205], v149 offset:5120
	ds_read_b128 v[206:209], v149 offset:6144
	ds_read_b128 v[224:227], v149 offset:7168
	global_load_lds_dwordx4 v[144:145], off
	v_lshl_add_u64 v[144:145], s[6:7], 0, v[142:143]
	s_add_i32 m0, s21, 0xe000
	s_nop 0
	global_load_lds_dwordx4 v[144:145], off
	s_waitcnt vmcnt(8)
	s_waitcnt lgkmcnt(0)
	s_barrier
	s_setprio 3
	s_waitcnt lgkmcnt(0)
	v_mfma_f32_16x16x32_bf16 v[126:129], v[150:153], v[182:185], v[126:129]
	v_mfma_f32_16x16x32_bf16 v[122:125], v[158:161], v[182:185], v[122:125]
	v_mfma_f32_16x16x32_bf16 v[118:121], v[150:153], v[190:193], v[118:121]
	v_mfma_f32_16x16x32_bf16 v[110:113], v[158:161], v[190:193], v[110:113]
	v_mfma_f32_16x16x32_bf16 v[102:105], v[150:153], v[198:201], v[102:105]
	v_mfma_f32_16x16x32_bf16 v[94:97], v[158:161], v[198:201], v[94:97]
	v_mfma_f32_16x16x32_bf16 v[86:89], v[150:153], v[206:209], v[86:89]
	v_mfma_f32_16x16x32_bf16 v[78:81], v[158:161], v[206:209], v[78:81]
	v_mfma_f32_16x16x32_bf16 v[126:129], v[154:157], v[186:189], v[126:129]
	v_mfma_f32_16x16x32_bf16 v[122:125], v[162:165], v[186:189], v[122:125]
	v_mfma_f32_16x16x32_bf16 v[118:121], v[154:157], v[194:197], v[118:121]
	v_mfma_f32_16x16x32_bf16 v[110:113], v[162:165], v[194:197], v[110:113]
	v_mfma_f32_16x16x32_bf16 v[102:105], v[154:157], v[202:205], v[102:105]
	v_mfma_f32_16x16x32_bf16 v[94:97], v[162:165], v[202:205], v[94:97]
	v_mfma_f32_16x16x32_bf16 v[86:89], v[154:157], v[224:227], v[86:89]
	v_mfma_f32_16x16x32_bf16 v[78:81], v[162:165], v[224:227], v[78:81]
	v_mfma_f32_16x16x32_bf16 v[114:117], v[166:169], v[182:185], v[114:117]
	v_mfma_f32_16x16x32_bf16 v[106:109], v[174:177], v[182:185], v[106:109]
	v_mfma_f32_16x16x32_bf16 v[98:101], v[166:169], v[190:193], v[98:101]
	v_mfma_f32_16x16x32_bf16 v[90:93], v[174:177], v[190:193], v[90:93]
	v_mfma_f32_16x16x32_bf16 v[82:85], v[166:169], v[198:201], v[82:85]
	v_mfma_f32_16x16x32_bf16 v[74:77], v[174:177], v[198:201], v[74:77]
	v_mfma_f32_16x16x32_bf16 v[70:73], v[166:169], v[206:209], v[70:73]
	v_mfma_f32_16x16x32_bf16 v[66:69], v[174:177], v[206:209], v[66:69]
	v_mfma_f32_16x16x32_bf16 v[114:117], v[170:173], v[186:189], v[114:117]
	v_mfma_f32_16x16x32_bf16 v[106:109], v[178:181], v[186:189], v[106:109]
	v_mfma_f32_16x16x32_bf16 v[98:101], v[170:173], v[194:197], v[98:101]
	v_mfma_f32_16x16x32_bf16 v[90:93], v[178:181], v[194:197], v[90:93]
	v_mfma_f32_16x16x32_bf16 v[82:85], v[170:173], v[202:205], v[82:85]
	v_mfma_f32_16x16x32_bf16 v[74:77], v[178:181], v[202:205], v[74:77]
	v_mfma_f32_16x16x32_bf16 v[70:73], v[170:173], v[224:227], v[70:73]
	v_mfma_f32_16x16x32_bf16 v[66:69], v[178:181], v[224:227], v[66:69]
	s_setprio 0
	s_barrier
	s_add_i32 s64, s83, s63
	v_lshl_add_u64 v[144:145], s[68:69], 0, v[0:1]
	s_mov_b32 m0, s64
	ds_read_b128 v[182:185], v149 offset:16384
	ds_read_b128 v[186:189], v149 offset:17408
	ds_read_b128 v[190:193], v149 offset:18432
	ds_read_b128 v[194:197], v149 offset:19456
	ds_read_b128 v[198:201], v149 offset:20480
	ds_read_b128 v[202:205], v149 offset:21504
	ds_read_b128 v[206:209], v149 offset:22528
	ds_read_b128 v[224:227], v149 offset:23552
	global_load_lds_dwordx4 v[144:145], off
	s_add_i32 m0, s64, 0x2000
	s_add_u32 s64, s68, 0x20000
	v_lshl_add_u64 v[210:211], s[68:69], 0, v[134:135]
	s_addc_u32 s65, s69, 0
	s_add_i32 s83, s84, s63
	global_load_lds_dwordx4 v[210:211], off
	v_lshl_add_u64 v[220:221], s[64:65], 0, v[0:1]
	s_mov_b32 m0, s83
	v_lshl_add_u64 v[228:229], s[70:71], 0, v[136:137]
	global_load_lds_dwordx4 v[220:221], off
	v_lshl_add_u64 v[220:221], s[64:65], 0, v[134:135]
	s_add_i32 m0, s83, 0x2000
	s_nop 0
	global_load_lds_dwordx4 v[220:221], off
	v_lshl_add_u64 v[220:221], s[70:71], 0, v[138:139]
	s_mov_b32 m0, s21
	s_nop 0
	global_load_lds_dwordx4 v[220:221], off
	s_mov_b32 m0, s27
	s_nop 0
	global_load_lds_dwordx4 v[228:229], off
	s_waitcnt vmcnt(8)
	s_waitcnt lgkmcnt(0)
	s_barrier
	s_setprio 3
	s_waitcnt lgkmcnt(0)
	v_mfma_f32_16x16x32_bf16 v[62:65], v[150:153], v[182:185], v[62:65]
	v_mfma_f32_16x16x32_bf16 v[58:61], v[158:161], v[182:185], v[58:61]
	v_mfma_f32_16x16x32_bf16 v[54:57], v[150:153], v[190:193], v[54:57]
	v_mfma_f32_16x16x32_bf16 v[46:49], v[158:161], v[190:193], v[46:49]
	v_mfma_f32_16x16x32_bf16 v[38:41], v[150:153], v[198:201], v[38:41]
	v_mfma_f32_16x16x32_bf16 v[30:33], v[158:161], v[198:201], v[30:33]
	v_mfma_f32_16x16x32_bf16 v[22:25], v[150:153], v[206:209], v[22:25]
	v_mfma_f32_16x16x32_bf16 v[14:17], v[158:161], v[206:209], v[14:17]
	v_mfma_f32_16x16x32_bf16 v[62:65], v[154:157], v[186:189], v[62:65]
	v_mfma_f32_16x16x32_bf16 v[58:61], v[162:165], v[186:189], v[58:61]
	v_mfma_f32_16x16x32_bf16 v[54:57], v[154:157], v[194:197], v[54:57]
	v_mfma_f32_16x16x32_bf16 v[46:49], v[162:165], v[194:197], v[46:49]
	v_mfma_f32_16x16x32_bf16 v[38:41], v[154:157], v[202:205], v[38:41]
	v_mfma_f32_16x16x32_bf16 v[30:33], v[162:165], v[202:205], v[30:33]
	v_mfma_f32_16x16x32_bf16 v[22:25], v[154:157], v[224:227], v[22:25]
	v_mfma_f32_16x16x32_bf16 v[14:17], v[162:165], v[224:227], v[14:17]
	v_mfma_f32_16x16x32_bf16 v[50:53], v[166:169], v[182:185], v[50:53]
	v_mfma_f32_16x16x32_bf16 v[42:45], v[174:177], v[182:185], v[42:45]
	v_mfma_f32_16x16x32_bf16 v[34:37], v[166:169], v[190:193], v[34:37]
	v_mfma_f32_16x16x32_bf16 v[26:29], v[174:177], v[190:193], v[26:29]
	v_mfma_f32_16x16x32_bf16 v[18:21], v[166:169], v[198:201], v[18:21]
	v_mfma_f32_16x16x32_bf16 v[10:13], v[174:177], v[198:201], v[10:13]
	v_mfma_f32_16x16x32_bf16 v[6:9], v[166:169], v[206:209], v[6:9]
	v_mfma_f32_16x16x32_bf16 v[2:5], v[174:177], v[206:209], v[2:5]
	v_mfma_f32_16x16x32_bf16 v[50:53], v[170:173], v[186:189], v[50:53]
	v_mfma_f32_16x16x32_bf16 v[42:45], v[178:181], v[186:189], v[42:45]
	v_mfma_f32_16x16x32_bf16 v[34:37], v[170:173], v[194:197], v[34:37]
	v_mfma_f32_16x16x32_bf16 v[26:29], v[178:181], v[194:197], v[26:29]
	v_mfma_f32_16x16x32_bf16 v[18:21], v[170:173], v[202:205], v[18:21]
	v_mfma_f32_16x16x32_bf16 v[10:13], v[178:181], v[202:205], v[10:13]
	v_mfma_f32_16x16x32_bf16 v[6:9], v[170:173], v[224:227], v[6:9]
	v_mfma_f32_16x16x32_bf16 v[2:5], v[178:181], v[224:227], v[2:5]
	s_setprio 0
	s_barrier
	s_add_i32 s83, 0, 0x18000
	s_add_i32 s84, 0, 0x1c000
	v_add_u32_e32 v162, s83, v147
	v_add_u32_e32 v178, s84, v147
	ds_read_b128 v[150:153], v162
	ds_read_b128 v[154:157], v162 offset:1024
	ds_read_b128 v[158:161], v162 offset:2048
	ds_read_b128 v[162:165], v162 offset:3072
	ds_read_b128 v[166:169], v178
	ds_read_b128 v[170:173], v178 offset:1024
	ds_read_b128 v[174:177], v178 offset:2048
	ds_read_b128 v[178:181], v178 offset:3072
	s_add_u32 s64, s70, 0x20000
	s_addc_u32 s65, s71, 0
	s_mov_b32 m0, s72
	v_lshl_add_u64 v[230:231], s[64:65], 0, v[138:139]
	ds_read_b128 v[182:185], v149 offset:32768
	ds_read_b128 v[186:189], v149 offset:33792
	ds_read_b128 v[190:193], v149 offset:34816
	ds_read_b128 v[194:197], v149 offset:35840
	ds_read_b128 v[198:201], v149 offset:36864
	ds_read_b128 v[202:205], v149 offset:37888
	ds_read_b128 v[206:209], v149 offset:38912
	ds_read_b128 v[224:227], v149 offset:39936
	global_load_lds_dwordx4 v[230:231], off
	v_lshl_add_u64 v[230:231], s[64:65], 0, v[136:137]
	s_mov_b32 m0, s73
	s_nop 0
	global_load_lds_dwordx4 v[230:231], off
	s_waitcnt vmcnt(8)
	s_waitcnt lgkmcnt(0)
	s_barrier
	s_setprio 3
	s_waitcnt lgkmcnt(0)
	v_mfma_f32_16x16x32_bf16 v[126:129], v[150:153], v[182:185], v[126:129]
	v_mfma_f32_16x16x32_bf16 v[122:125], v[158:161], v[182:185], v[122:125]
	v_mfma_f32_16x16x32_bf16 v[118:121], v[150:153], v[190:193], v[118:121]
	v_mfma_f32_16x16x32_bf16 v[110:113], v[158:161], v[190:193], v[110:113]
	v_mfma_f32_16x16x32_bf16 v[102:105], v[150:153], v[198:201], v[102:105]
	v_mfma_f32_16x16x32_bf16 v[94:97], v[158:161], v[198:201], v[94:97]
	v_mfma_f32_16x16x32_bf16 v[86:89], v[150:153], v[206:209], v[86:89]
	v_mfma_f32_16x16x32_bf16 v[78:81], v[158:161], v[206:209], v[78:81]
	v_mfma_f32_16x16x32_bf16 v[126:129], v[154:157], v[186:189], v[126:129]
	v_mfma_f32_16x16x32_bf16 v[122:125], v[162:165], v[186:189], v[122:125]
	v_mfma_f32_16x16x32_bf16 v[118:121], v[154:157], v[194:197], v[118:121]
	v_mfma_f32_16x16x32_bf16 v[110:113], v[162:165], v[194:197], v[110:113]
	v_mfma_f32_16x16x32_bf16 v[102:105], v[154:157], v[202:205], v[102:105]
	v_mfma_f32_16x16x32_bf16 v[94:97], v[162:165], v[202:205], v[94:97]
	v_mfma_f32_16x16x32_bf16 v[86:89], v[154:157], v[224:227], v[86:89]
	v_mfma_f32_16x16x32_bf16 v[78:81], v[162:165], v[224:227], v[78:81]
	v_mfma_f32_16x16x32_bf16 v[114:117], v[166:169], v[182:185], v[114:117]
	v_mfma_f32_16x16x32_bf16 v[106:109], v[174:177], v[182:185], v[106:109]
	v_mfma_f32_16x16x32_bf16 v[98:101], v[166:169], v[190:193], v[98:101]
	v_mfma_f32_16x16x32_bf16 v[90:93], v[174:177], v[190:193], v[90:93]
	v_mfma_f32_16x16x32_bf16 v[82:85], v[166:169], v[198:201], v[82:85]
	v_mfma_f32_16x16x32_bf16 v[74:77], v[174:177], v[198:201], v[74:77]
	v_mfma_f32_16x16x32_bf16 v[70:73], v[166:169], v[206:209], v[70:73]
	v_mfma_f32_16x16x32_bf16 v[66:69], v[174:177], v[206:209], v[66:69]
	v_mfma_f32_16x16x32_bf16 v[114:117], v[170:173], v[186:189], v[114:117]
	v_mfma_f32_16x16x32_bf16 v[106:109], v[178:181], v[186:189], v[106:109]
	v_mfma_f32_16x16x32_bf16 v[98:101], v[170:173], v[194:197], v[98:101]
	v_mfma_f32_16x16x32_bf16 v[90:93], v[178:181], v[194:197], v[90:93]
	v_mfma_f32_16x16x32_bf16 v[82:85], v[170:173], v[202:205], v[82:85]
	v_mfma_f32_16x16x32_bf16 v[74:77], v[178:181], v[202:205], v[74:77]
	v_mfma_f32_16x16x32_bf16 v[70:73], v[170:173], v[224:227], v[70:73]
	v_mfma_f32_16x16x32_bf16 v[66:69], v[178:181], v[224:227], v[66:69]
	s_setprio 0
	s_barrier
	s_add_i32 s64, s83, s63
	v_lshl_add_u64 v[144:145], v[144:145], 0, s[48:49]
	s_mov_b32 m0, s64
	ds_read_b128 v[182:185], v149 offset:49152
	ds_read_b128 v[186:189], v149 offset:50176
	ds_read_b128 v[190:193], v149 offset:51200
	ds_read_b128 v[194:197], v149 offset:52224
	ds_read_b128 v[198:201], v149 offset:53248
	ds_read_b128 v[202:205], v149 offset:54272
	ds_read_b128 v[206:209], v149 offset:55296
	ds_read_b128 v[224:227], v149 offset:56320
	global_load_lds_dwordx4 v[144:145], off
	s_add_i32 m0, s64, 0x2000
	s_add_u32 s64, s68, 0x20080
	v_lshl_add_u64 v[144:145], v[210:211], 0, s[48:49]
	s_addc_u32 s65, s69, 0
	s_add_i32 s68, s84, s63
	global_load_lds_dwordx4 v[144:145], off
	v_lshl_add_u64 v[144:145], s[64:65], 0, v[0:1]
	s_mov_b32 m0, s68
	s_nop 0
	global_load_lds_dwordx4 v[144:145], off
	v_lshl_add_u64 v[144:145], s[64:65], 0, v[134:135]
	s_add_i32 m0, s68, 0x2000
	s_nop 0
	global_load_lds_dwordx4 v[144:145], off
	v_lshl_add_u64 v[144:145], v[220:221], 0, s[48:49]
	s_mov_b32 m0, s74
	s_nop 0
	global_load_lds_dwordx4 v[144:145], off
	v_lshl_add_u64 v[144:145], v[228:229], 0, s[48:49]
	s_mov_b32 m0, s75
	s_nop 0
	global_load_lds_dwordx4 v[144:145], off
	s_waitcnt vmcnt(8)
	s_waitcnt lgkmcnt(0)
	s_barrier
	s_setprio 3
	s_waitcnt lgkmcnt(0)
	v_mfma_f32_16x16x32_bf16 v[62:65], v[150:153], v[182:185], v[62:65]
	v_mfma_f32_16x16x32_bf16 v[58:61], v[158:161], v[182:185], v[58:61]
	v_mfma_f32_16x16x32_bf16 v[54:57], v[150:153], v[190:193], v[54:57]
	v_mfma_f32_16x16x32_bf16 v[46:49], v[158:161], v[190:193], v[46:49]
	v_mfma_f32_16x16x32_bf16 v[38:41], v[150:153], v[198:201], v[38:41]
	v_mfma_f32_16x16x32_bf16 v[30:33], v[158:161], v[198:201], v[30:33]
	v_mfma_f32_16x16x32_bf16 v[22:25], v[150:153], v[206:209], v[22:25]
	v_mfma_f32_16x16x32_bf16 v[14:17], v[158:161], v[206:209], v[14:17]
	v_mfma_f32_16x16x32_bf16 v[62:65], v[154:157], v[186:189], v[62:65]
	v_mfma_f32_16x16x32_bf16 v[58:61], v[162:165], v[186:189], v[58:61]
	v_mfma_f32_16x16x32_bf16 v[54:57], v[154:157], v[194:197], v[54:57]
	v_mfma_f32_16x16x32_bf16 v[46:49], v[162:165], v[194:197], v[46:49]
	v_mfma_f32_16x16x32_bf16 v[38:41], v[154:157], v[202:205], v[38:41]
	v_mfma_f32_16x16x32_bf16 v[30:33], v[162:165], v[202:205], v[30:33]
	v_mfma_f32_16x16x32_bf16 v[22:25], v[154:157], v[224:227], v[22:25]
	v_mfma_f32_16x16x32_bf16 v[14:17], v[162:165], v[224:227], v[14:17]
	v_mfma_f32_16x16x32_bf16 v[50:53], v[166:169], v[182:185], v[50:53]
	v_mfma_f32_16x16x32_bf16 v[42:45], v[174:177], v[182:185], v[42:45]
	v_mfma_f32_16x16x32_bf16 v[34:37], v[166:169], v[190:193], v[34:37]
	v_mfma_f32_16x16x32_bf16 v[26:29], v[174:177], v[190:193], v[26:29]
	v_mfma_f32_16x16x32_bf16 v[18:21], v[166:169], v[198:201], v[18:21]
	v_mfma_f32_16x16x32_bf16 v[10:13], v[174:177], v[198:201], v[10:13]
	v_mfma_f32_16x16x32_bf16 v[6:9], v[166:169], v[206:209], v[6:9]
	v_mfma_f32_16x16x32_bf16 v[2:5], v[174:177], v[206:209], v[2:5]
	v_mfma_f32_16x16x32_bf16 v[50:53], v[170:173], v[186:189], v[50:53]
	v_mfma_f32_16x16x32_bf16 v[42:45], v[178:181], v[186:189], v[42:45]
	v_mfma_f32_16x16x32_bf16 v[34:37], v[170:173], v[194:197], v[34:37]
	v_mfma_f32_16x16x32_bf16 v[26:29], v[178:181], v[194:197], v[26:29]
	v_mfma_f32_16x16x32_bf16 v[18:21], v[170:173], v[202:205], v[18:21]
	v_mfma_f32_16x16x32_bf16 v[10:13], v[178:181], v[202:205], v[10:13]
	v_mfma_f32_16x16x32_bf16 v[6:9], v[170:173], v[224:227], v[6:9]
	v_mfma_f32_16x16x32_bf16 v[2:5], v[178:181], v[224:227], v[2:5]
	s_setprio 0
	s_barrier
	s_add_i32 s82, s82, 2
	s_add_u32 s6, s6, 0x100
	s_addc_u32 s7, s7, 0
	s_add_u32 s80, s80, 0x100
	s_addc_u32 s81, s81, 0
	s_cmp_gt_u32 s82, 5
	s_cbranch_scc0 .LBB0_1533
	s_and_b64 vcc, exec, s[12:13]
	s_cbranch_vccnz .LBB0_1537
	s_cmp_gt_i32 s20, 15
	s_cbranch_scc0 .LBB0_1538

.LBB0_1602:
	s_ashr_i32 s13, s16, 3
	s_add_i32 s13, s16, s13
	s_and_b64 s[18:19], s[66:67], s[4:5]
	s_add_i32 s13, s13, 1
	s_and_b64 s[18:19], s[18:19], exec
	s_cselect_b32 s16, s13, s16
	s_ashr_i32 s17, s16, 31
	s_lshl_b64 s[18:19], s[16:17], 19
	s_add_u32 s18, s37, s18
	s_addc_u32 s19, s60, s19
	s_and_b64 s[20:21], s[4:5], exec
	s_cselect_b32 s17, s19, s57
	s_cselect_b32 s27, s18, s56
	s_ashr_i32 s13, s12, 31
	s_lshl_b64 s[20:21], s[12:13], 19
	s_add_u32 s20, s63, s20
	s_addc_u32 s21, s72, s21
	s_and_b64 s[30:31], s[4:5], exec
	s_cselect_b32 s13, s21, s69
	s_cselect_b32 s30, s20, s68
	s_add_u32 s56, s56, 0x40080
	s_addc_u32 s57, s57, 0
	s_add_u32 s31, s68, 0x100
	s_addc_u32 s85, s69, 0
	s_mov_b32 s86, -2
	s_add_u32 s64, s56, 0xfffc0080
	s_addc_u32 s65, s57, -1
	s_add_i32 s87, 0, 0x10000
	s_cmp_eq_u32 s86, 12
	s_cselect_b32 s71, s17, s65
	s_cselect_b32 s70, s27, s64
	v_add_u32_e32 v144, s87, v147
	s_cselect_b32 s69, s13, s85
	s_cselect_b32 s68, s30, s31
	s_add_i32 s88, 0, 0x14000
	ds_read_b128 v[140:143], v144
	ds_read_b128 v[150:153], v144 offset:1024
	ds_read_b128 v[154:157], v144 offset:2048
	ds_read_b128 v[158:161], v144 offset:3072
	v_add_u32_e32 v144, s88, v147
	ds_read_b128 v[162:165], v144
	ds_read_b128 v[166:169], v144 offset:1024
	ds_read_b128 v[170:173], v144 offset:2048
	ds_read_b128 v[174:177], v144 offset:3072
	v_lshl_add_u64 v[144:145], s[56:57], 0, v[136:137]
	s_add_i32 m0, s53, 0xc000
	ds_read_b128 v[178:181], v149
	ds_read_b128 v[182:185], v149 offset:1024
	ds_read_b128 v[186:189], v149 offset:2048
	ds_read_b128 v[190:193], v149 offset:3072
	ds_read_b128 v[194:197], v149 offset:4096
	ds_read_b128 v[198:201], v149 offset:5120
	ds_read_b128 v[202:205], v149 offset:6144
	ds_read_b128 v[206:209], v149 offset:7168
	global_load_lds_dwordx4 v[144:145], off
	v_lshl_add_u64 v[144:145], s[56:57], 0, v[138:139]
	s_add_i32 m0, s53, 0xe000
	s_nop 0
	global_load_lds_dwordx4 v[144:145], off
	s_waitcnt vmcnt(8)
	s_waitcnt lgkmcnt(0)
	s_barrier
	s_setprio 3
	s_waitcnt lgkmcnt(0)
	v_mfma_f32_16x16x32_bf16 v[126:129], v[140:143], v[178:181], 0
	v_mfma_f32_16x16x32_bf16 v[122:125], v[154:157], v[178:181], 0
	v_mfma_f32_16x16x32_bf16 v[110:113], v[140:143], v[186:189], 0
	v_mfma_f32_16x16x32_bf16 v[106:109], v[154:157], v[186:189], 0
	v_mfma_f32_16x16x32_bf16 v[94:97], v[140:143], v[194:197], 0
	v_mfma_f32_16x16x32_bf16 v[90:93], v[154:157], v[194:197], 0
	v_mfma_f32_16x16x32_bf16 v[78:81], v[140:143], v[202:205], 0
	v_mfma_f32_16x16x32_bf16 v[74:77], v[154:157], v[202:205], 0
	v_mfma_f32_16x16x32_bf16 v[126:129], v[150:153], v[182:185], v[126:129]
	v_mfma_f32_16x16x32_bf16 v[122:125], v[158:161], v[182:185], v[122:125]
	v_mfma_f32_16x16x32_bf16 v[110:113], v[150:153], v[190:193], v[110:113]
	v_mfma_f32_16x16x32_bf16 v[106:109], v[158:161], v[190:193], v[106:109]
	v_mfma_f32_16x16x32_bf16 v[94:97], v[150:153], v[198:201], v[94:97]
	v_mfma_f32_16x16x32_bf16 v[90:93], v[158:161], v[198:201], v[90:93]
	v_mfma_f32_16x16x32_bf16 v[78:81], v[150:153], v[206:209], v[78:81]
	v_mfma_f32_16x16x32_bf16 v[74:77], v[158:161], v[206:209], v[74:77]
	v_mfma_f32_16x16x32_bf16 v[118:121], v[162:165], v[178:181], 0
	v_mfma_f32_16x16x32_bf16 v[114:117], v[170:173], v[178:181], 0
	v_mfma_f32_16x16x32_bf16 v[102:105], v[162:165], v[186:189], 0
	v_mfma_f32_16x16x32_bf16 v[98:101], v[170:173], v[186:189], 0
	v_mfma_f32_16x16x32_bf16 v[86:89], v[162:165], v[194:197], 0
	v_mfma_f32_16x16x32_bf16 v[82:85], v[170:173], v[194:197], 0
	v_mfma_f32_16x16x32_bf16 v[70:73], v[162:165], v[202:205], 0
	v_mfma_f32_16x16x32_bf16 v[66:69], v[170:173], v[202:205], 0
	v_mfma_f32_16x16x32_bf16 v[118:121], v[166:169], v[182:185], v[118:121]
	v_mfma_f32_16x16x32_bf16 v[114:117], v[174:177], v[182:185], v[114:117]
	v_mfma_f32_16x16x32_bf16 v[102:105], v[166:169], v[190:193], v[102:105]
	v_mfma_f32_16x16x32_bf16 v[98:101], v[174:177], v[190:193], v[98:101]
	v_mfma_f32_16x16x32_bf16 v[86:89], v[166:169], v[198:201], v[86:89]
	v_mfma_f32_16x16x32_bf16 v[82:85], v[174:177], v[198:201], v[82:85]
	v_mfma_f32_16x16x32_bf16 v[70:73], v[166:169], v[206:209], v[70:73]
	v_mfma_f32_16x16x32_bf16 v[66:69], v[174:177], v[206:209], v[66:69]
	s_setprio 0
	s_barrier
	s_add_i32 s64, s87, s73
	v_lshl_add_u64 v[144:145], s[68:69], 0, v[0:1]
	s_mov_b32 m0, s64
	ds_read_b128 v[178:181], v149 offset:16384
	ds_read_b128 v[182:185], v149 offset:17408
	ds_read_b128 v[186:189], v149 offset:18432
	ds_read_b128 v[190:193], v149 offset:19456
	ds_read_b128 v[194:197], v149 offset:20480
	ds_read_b128 v[198:201], v149 offset:21504
	ds_read_b128 v[202:205], v149 offset:22528
	ds_read_b128 v[206:209], v149 offset:23552
	global_load_lds_dwordx4 v[144:145], off
	s_add_i32 m0, s64, 0x2000
	s_add_u32 s64, s68, 0x40000
	v_lshl_add_u64 v[210:211], s[68:69], 0, v[134:135]
	s_addc_u32 s65, s69, 0
	s_add_i32 s87, s88, s73
	global_load_lds_dwordx4 v[210:211], off
	v_lshl_add_u64 v[220:221], s[64:65], 0, v[0:1]
	s_mov_b32 m0, s87
	v_lshl_add_u64 v[224:225], s[70:71], 0, v[134:135]
	global_load_lds_dwordx4 v[220:221], off
	v_lshl_add_u64 v[220:221], s[64:65], 0, v[134:135]
	s_add_i32 m0, s87, 0x2000
	s_nop 0
	global_load_lds_dwordx4 v[220:221], off
	v_lshl_add_u64 v[220:221], s[70:71], 0, v[0:1]
	s_mov_b32 m0, s53
	s_nop 0
	global_load_lds_dwordx4 v[220:221], off
	s_mov_b32 m0, s78
	s_nop 0
	global_load_lds_dwordx4 v[224:225], off
	s_waitcnt vmcnt(8)
	s_waitcnt lgkmcnt(0)
	s_barrier
	s_setprio 3
	s_waitcnt lgkmcnt(0)
	v_mfma_f32_16x16x32_bf16 v[62:65], v[140:143], v[178:181], 0
	v_mfma_f32_16x16x32_bf16 v[58:61], v[154:157], v[178:181], 0
	v_mfma_f32_16x16x32_bf16 v[46:49], v[140:143], v[186:189], 0
	v_mfma_f32_16x16x32_bf16 v[42:45], v[154:157], v[186:189], 0
	v_mfma_f32_16x16x32_bf16 v[30:33], v[140:143], v[194:197], 0
	v_mfma_f32_16x16x32_bf16 v[26:29], v[154:157], v[194:197], 0
	v_mfma_f32_16x16x32_bf16 v[14:17], v[140:143], v[202:205], 0
	v_mfma_f32_16x16x32_bf16 v[10:13], v[154:157], v[202:205], 0
	v_mfma_f32_16x16x32_bf16 v[62:65], v[150:153], v[182:185], v[62:65]
	v_mfma_f32_16x16x32_bf16 v[58:61], v[158:161], v[182:185], v[58:61]
	v_mfma_f32_16x16x32_bf16 v[46:49], v[150:153], v[190:193], v[46:49]
	v_mfma_f32_16x16x32_bf16 v[42:45], v[158:161], v[190:193], v[42:45]
	v_mfma_f32_16x16x32_bf16 v[30:33], v[150:153], v[198:201], v[30:33]
	v_mfma_f32_16x16x32_bf16 v[26:29], v[158:161], v[198:201], v[26:29]
	v_mfma_f32_16x16x32_bf16 v[14:17], v[150:153], v[206:209], v[14:17]
	v_mfma_f32_16x16x32_bf16 v[10:13], v[158:161], v[206:209], v[10:13]
	v_mfma_f32_16x16x32_bf16 v[54:57], v[162:165], v[178:181], 0
	v_mfma_f32_16x16x32_bf16 v[50:53], v[170:173], v[178:181], 0
	v_mfma_f32_16x16x32_bf16 v[38:41], v[162:165], v[186:189], 0
	v_mfma_f32_16x16x32_bf16 v[34:37], v[170:173], v[186:189], 0
	v_mfma_f32_16x16x32_bf16 v[22:25], v[162:165], v[194:197], 0
	v_mfma_f32_16x16x32_bf16 v[18:21], v[170:173], v[194:197], 0
	v_mfma_f32_16x16x32_bf16 v[6:9], v[162:165], v[202:205], 0
	v_mfma_f32_16x16x32_bf16 v[2:5], v[170:173], v[202:205], 0
	v_mfma_f32_16x16x32_bf16 v[54:57], v[166:169], v[182:185], v[54:57]
	v_mfma_f32_16x16x32_bf16 v[50:53], v[174:177], v[182:185], v[50:53]
	v_mfma_f32_16x16x32_bf16 v[38:41], v[166:169], v[190:193], v[38:41]
	v_mfma_f32_16x16x32_bf16 v[34:37], v[174:177], v[190:193], v[34:37]
	v_mfma_f32_16x16x32_bf16 v[22:25], v[166:169], v[198:201], v[22:25]
	v_mfma_f32_16x16x32_bf16 v[18:21], v[174:177], v[198:201], v[18:21]
	v_mfma_f32_16x16x32_bf16 v[6:9], v[166:169], v[206:209], v[6:9]
	v_mfma_f32_16x16x32_bf16 v[2:5], v[174:177], v[206:209], v[2:5]
	s_setprio 0
	s_barrier
	s_add_i32 s87, 0, 0x18000
	s_add_i32 s88, 0, 0x1c000
	v_add_u32_e32 v158, s87, v147
	v_add_u32_e32 v174, s88, v147
	ds_read_b128 v[140:143], v158
	ds_read_b128 v[150:153], v158 offset:1024
	ds_read_b128 v[154:157], v158 offset:2048
	ds_read_b128 v[158:161], v158 offset:3072
	ds_read_b128 v[162:165], v174
	ds_read_b128 v[166:169], v174 offset:1024
	ds_read_b128 v[170:173], v174 offset:2048
	ds_read_b128 v[174:177], v174 offset:3072
	s_add_u32 s64, s70, 0x40000
	s_addc_u32 s65, s71, 0
	s_mov_b32 m0, s79
	v_lshl_add_u64 v[226:227], s[64:65], 0, v[0:1]
	ds_read_b128 v[178:181], v149 offset:32768
	ds_read_b128 v[182:185], v149 offset:33792
	ds_read_b128 v[186:189], v149 offset:34816
	ds_read_b128 v[190:193], v149 offset:35840
	ds_read_b128 v[194:197], v149 offset:36864
	ds_read_b128 v[198:201], v149 offset:37888
	ds_read_b128 v[202:205], v149 offset:38912
	ds_read_b128 v[206:209], v149 offset:39936
	global_load_lds_dwordx4 v[226:227], off
	v_lshl_add_u64 v[226:227], s[64:65], 0, v[134:135]
	s_mov_b32 m0, s80
	s_nop 0
	global_load_lds_dwordx4 v[226:227], off
	s_waitcnt vmcnt(8)
	s_waitcnt lgkmcnt(0)
	s_barrier
	s_setprio 3
	s_waitcnt lgkmcnt(0)
	v_mfma_f32_16x16x32_bf16 v[126:129], v[140:143], v[178:181], v[126:129]
	v_mfma_f32_16x16x32_bf16 v[122:125], v[154:157], v[178:181], v[122:125]
	v_mfma_f32_16x16x32_bf16 v[110:113], v[140:143], v[186:189], v[110:113]
	v_mfma_f32_16x16x32_bf16 v[106:109], v[154:157], v[186:189], v[106:109]
	v_mfma_f32_16x16x32_bf16 v[94:97], v[140:143], v[194:197], v[94:97]
	v_mfma_f32_16x16x32_bf16 v[90:93], v[154:157], v[194:197], v[90:93]
	v_mfma_f32_16x16x32_bf16 v[78:81], v[140:143], v[202:205], v[78:81]
	v_mfma_f32_16x16x32_bf16 v[74:77], v[154:157], v[202:205], v[74:77]
	v_mfma_f32_16x16x32_bf16 v[126:129], v[150:153], v[182:185], v[126:129]
	v_mfma_f32_16x16x32_bf16 v[122:125], v[158:161], v[182:185], v[122:125]
	v_mfma_f32_16x16x32_bf16 v[110:113], v[150:153], v[190:193], v[110:113]
	v_mfma_f32_16x16x32_bf16 v[106:109], v[158:161], v[190:193], v[106:109]
	v_mfma_f32_16x16x32_bf16 v[94:97], v[150:153], v[198:201], v[94:97]
	v_mfma_f32_16x16x32_bf16 v[90:93], v[158:161], v[198:201], v[90:93]
	v_mfma_f32_16x16x32_bf16 v[78:81], v[150:153], v[206:209], v[78:81]
	v_mfma_f32_16x16x32_bf16 v[74:77], v[158:161], v[206:209], v[74:77]
	v_mfma_f32_16x16x32_bf16 v[118:121], v[162:165], v[178:181], v[118:121]
	v_mfma_f32_16x16x32_bf16 v[114:117], v[170:173], v[178:181], v[114:117]
	v_mfma_f32_16x16x32_bf16 v[102:105], v[162:165], v[186:189], v[102:105]
	v_mfma_f32_16x16x32_bf16 v[98:101], v[170:173], v[186:189], v[98:101]
	v_mfma_f32_16x16x32_bf16 v[86:89], v[162:165], v[194:197], v[86:89]
	v_mfma_f32_16x16x32_bf16 v[82:85], v[170:173], v[194:197], v[82:85]
	v_mfma_f32_16x16x32_bf16 v[70:73], v[162:165], v[202:205], v[70:73]
	v_mfma_f32_16x16x32_bf16 v[66:69], v[170:173], v[202:205], v[66:69]
	v_mfma_f32_16x16x32_bf16 v[118:121], v[166:169], v[182:185], v[118:121]
	v_mfma_f32_16x16x32_bf16 v[114:117], v[174:177], v[182:185], v[114:117]
	v_mfma_f32_16x16x32_bf16 v[102:105], v[166:169], v[190:193], v[102:105]
	v_mfma_f32_16x16x32_bf16 v[98:101], v[174:177], v[190:193], v[98:101]
	v_mfma_f32_16x16x32_bf16 v[86:89], v[166:169], v[198:201], v[86:89]
	v_mfma_f32_16x16x32_bf16 v[82:85], v[174:177], v[198:201], v[82:85]
	v_mfma_f32_16x16x32_bf16 v[70:73], v[166:169], v[206:209], v[70:73]
	v_mfma_f32_16x16x32_bf16 v[66:69], v[174:177], v[206:209], v[66:69]
	s_setprio 0
	s_barrier
	s_add_i32 s64, s87, s73
	v_lshl_add_u64 v[144:145], v[144:145], 0, s[48:49]
	s_mov_b32 m0, s64
	ds_read_b128 v[178:181], v149 offset:49152
	ds_read_b128 v[182:185], v149 offset:50176
	ds_read_b128 v[186:189], v149 offset:51200
	ds_read_b128 v[190:193], v149 offset:52224
	ds_read_b128 v[194:197], v149 offset:53248
	ds_read_b128 v[198:201], v149 offset:54272
	ds_read_b128 v[202:205], v149 offset:55296
	ds_read_b128 v[206:209], v149 offset:56320
	global_load_lds_dwordx4 v[144:145], off
	s_add_i32 m0, s64, 0x2000
	s_add_u32 s64, s68, 0x40080
	v_lshl_add_u64 v[144:145], v[210:211], 0, s[48:49]
	s_addc_u32 s65, s69, 0
	s_add_i32 s68, s88, s73
	global_load_lds_dwordx4 v[144:145], off
	v_lshl_add_u64 v[144:145], s[64:65], 0, v[0:1]
	s_mov_b32 m0, s68
	s_nop 0
	global_load_lds_dwordx4 v[144:145], off
	v_lshl_add_u64 v[144:145], s[64:65], 0, v[134:135]
	s_add_i32 m0, s68, 0x2000
	s_nop 0
	global_load_lds_dwordx4 v[144:145], off
	v_lshl_add_u64 v[144:145], v[220:221], 0, s[48:49]
	s_mov_b32 m0, s81
	s_nop 0
	global_load_lds_dwordx4 v[144:145], off
	v_lshl_add_u64 v[144:145], v[224:225], 0, s[48:49]
	s_mov_b32 m0, s82
	s_nop 0
	global_load_lds_dwordx4 v[144:145], off
	s_waitcnt vmcnt(8)
	s_waitcnt lgkmcnt(0)
	s_barrier
	s_setprio 3
	s_waitcnt lgkmcnt(0)
	v_mfma_f32_16x16x32_bf16 v[62:65], v[140:143], v[178:181], v[62:65]
	v_mfma_f32_16x16x32_bf16 v[58:61], v[154:157], v[178:181], v[58:61]
	v_mfma_f32_16x16x32_bf16 v[46:49], v[140:143], v[186:189], v[46:49]
	v_mfma_f32_16x16x32_bf16 v[42:45], v[154:157], v[186:189], v[42:45]
	v_mfma_f32_16x16x32_bf16 v[30:33], v[140:143], v[194:197], v[30:33]
	v_mfma_f32_16x16x32_bf16 v[26:29], v[154:157], v[194:197], v[26:29]
	v_mfma_f32_16x16x32_bf16 v[14:17], v[140:143], v[202:205], v[14:17]
	v_mfma_f32_16x16x32_bf16 v[10:13], v[154:157], v[202:205], v[10:13]
	v_mfma_f32_16x16x32_bf16 v[62:65], v[150:153], v[182:185], v[62:65]
	v_mfma_f32_16x16x32_bf16 v[58:61], v[158:161], v[182:185], v[58:61]
	v_mfma_f32_16x16x32_bf16 v[46:49], v[150:153], v[190:193], v[46:49]
	v_mfma_f32_16x16x32_bf16 v[42:45], v[158:161], v[190:193], v[42:45]
	v_mfma_f32_16x16x32_bf16 v[30:33], v[150:153], v[198:201], v[30:33]
	v_mfma_f32_16x16x32_bf16 v[26:29], v[158:161], v[198:201], v[26:29]
	v_mfma_f32_16x16x32_bf16 v[14:17], v[150:153], v[206:209], v[14:17]
	v_mfma_f32_16x16x32_bf16 v[10:13], v[158:161], v[206:209], v[10:13]
	v_mfma_f32_16x16x32_bf16 v[54:57], v[162:165], v[178:181], v[54:57]
	v_mfma_f32_16x16x32_bf16 v[50:53], v[170:173], v[178:181], v[50:53]
	v_mfma_f32_16x16x32_bf16 v[38:41], v[162:165], v[186:189], v[38:41]
	v_mfma_f32_16x16x32_bf16 v[34:37], v[170:173], v[186:189], v[34:37]
	v_mfma_f32_16x16x32_bf16 v[22:25], v[162:165], v[194:197], v[22:25]
	v_mfma_f32_16x16x32_bf16 v[18:21], v[170:173], v[194:197], v[18:21]
	v_mfma_f32_16x16x32_bf16 v[6:9], v[162:165], v[202:205], v[6:9]
	v_mfma_f32_16x16x32_bf16 v[2:5], v[170:173], v[202:205], v[2:5]
	v_mfma_f32_16x16x32_bf16 v[54:57], v[166:169], v[182:185], v[54:57]
	v_mfma_f32_16x16x32_bf16 v[50:53], v[174:177], v[182:185], v[50:53]
	v_mfma_f32_16x16x32_bf16 v[38:41], v[166:169], v[190:193], v[38:41]
	v_mfma_f32_16x16x32_bf16 v[34:37], v[174:177], v[190:193], v[34:37]
	v_mfma_f32_16x16x32_bf16 v[22:25], v[166:169], v[198:201], v[22:25]
	v_mfma_f32_16x16x32_bf16 v[18:21], v[174:177], v[198:201], v[18:21]
	v_mfma_f32_16x16x32_bf16 v[6:9], v[166:169], v[206:209], v[6:9]
	v_mfma_f32_16x16x32_bf16 v[2:5], v[174:177], v[206:209], v[2:5]
	s_setprio 0
	s_barrier
	s_add_i32 s86, s86, 2
	s_add_u32 s56, s56, 0x100
	s_addc_u32 s57, s57, 0
	s_add_u32 s31, s31, 0x100
	s_addc_u32 s85, s85, 0
.LBB0_1603:
	s_add_u32 s64, s56, 0xfffc0080
	s_addc_u32 s65, s57, -1
	s_add_i32 s87, 0, 0x10000
	s_cmp_eq_u32 s86, 12
	s_cselect_b32 s71, s17, s65
	s_cselect_b32 s70, s27, s64
	v_add_u32_e32 v144, s87, v147
	s_cselect_b32 s69, s13, s85
	s_cselect_b32 s68, s30, s31
	s_add_i32 s88, 0, 0x14000
	ds_read_b128 v[140:143], v144
	ds_read_b128 v[150:153], v144 offset:1024
	ds_read_b128 v[154:157], v144 offset:2048
	ds_read_b128 v[158:161], v144 offset:3072
	v_add_u32_e32 v144, s88, v147
	ds_read_b128 v[162:165], v144
	ds_read_b128 v[166:169], v144 offset:1024
	ds_read_b128 v[170:173], v144 offset:2048
	ds_read_b128 v[174:177], v144 offset:3072
	v_lshl_add_u64 v[144:145], s[56:57], 0, v[136:137]
	s_add_i32 m0, s53, 0xc000
	ds_read_b128 v[178:181], v149
	ds_read_b128 v[182:185], v149 offset:1024
	ds_read_b128 v[186:189], v149 offset:2048
	ds_read_b128 v[190:193], v149 offset:3072
	ds_read_b128 v[194:197], v149 offset:4096
	ds_read_b128 v[198:201], v149 offset:5120
	ds_read_b128 v[202:205], v149 offset:6144
	ds_read_b128 v[206:209], v149 offset:7168
	global_load_lds_dwordx4 v[144:145], off
	v_lshl_add_u64 v[144:145], s[56:57], 0, v[138:139]
	s_add_i32 m0, s53, 0xe000
	s_nop 0
	global_load_lds_dwordx4 v[144:145], off
	s_waitcnt vmcnt(8)
	s_waitcnt lgkmcnt(0)
	s_barrier
	s_setprio 3
	s_waitcnt lgkmcnt(0)
	v_mfma_f32_16x16x32_bf16 v[126:129], v[140:143], v[178:181], v[126:129]
	v_mfma_f32_16x16x32_bf16 v[122:125], v[154:157], v[178:181], v[122:125]
	v_mfma_f32_16x16x32_bf16 v[110:113], v[140:143], v[186:189], v[110:113]
	v_mfma_f32_16x16x32_bf16 v[106:109], v[154:157], v[186:189], v[106:109]
	v_mfma_f32_16x16x32_bf16 v[94:97], v[140:143], v[194:197], v[94:97]
	v_mfma_f32_16x16x32_bf16 v[90:93], v[154:157], v[194:197], v[90:93]
	v_mfma_f32_16x16x32_bf16 v[78:81], v[140:143], v[202:205], v[78:81]
	v_mfma_f32_16x16x32_bf16 v[74:77], v[154:157], v[202:205], v[74:77]
	v_mfma_f32_16x16x32_bf16 v[126:129], v[150:153], v[182:185], v[126:129]
	v_mfma_f32_16x16x32_bf16 v[122:125], v[158:161], v[182:185], v[122:125]
	v_mfma_f32_16x16x32_bf16 v[110:113], v[150:153], v[190:193], v[110:113]
	v_mfma_f32_16x16x32_bf16 v[106:109], v[158:161], v[190:193], v[106:109]
	v_mfma_f32_16x16x32_bf16 v[94:97], v[150:153], v[198:201], v[94:97]
	v_mfma_f32_16x16x32_bf16 v[90:93], v[158:161], v[198:201], v[90:93]
	v_mfma_f32_16x16x32_bf16 v[78:81], v[150:153], v[206:209], v[78:81]
	v_mfma_f32_16x16x32_bf16 v[74:77], v[158:161], v[206:209], v[74:77]
	v_mfma_f32_16x16x32_bf16 v[118:121], v[162:165], v[178:181], v[118:121]
	v_mfma_f32_16x16x32_bf16 v[114:117], v[170:173], v[178:181], v[114:117]
	v_mfma_f32_16x16x32_bf16 v[102:105], v[162:165], v[186:189], v[102:105]
	v_mfma_f32_16x16x32_bf16 v[98:101], v[170:173], v[186:189], v[98:101]
	v_mfma_f32_16x16x32_bf16 v[86:89], v[162:165], v[194:197], v[86:89]
	v_mfma_f32_16x16x32_bf16 v[82:85], v[170:173], v[194:197], v[82:85]
	v_mfma_f32_16x16x32_bf16 v[70:73], v[162:165], v[202:205], v[70:73]
	v_mfma_f32_16x16x32_bf16 v[66:69], v[170:173], v[202:205], v[66:69]
	v_mfma_f32_16x16x32_bf16 v[118:121], v[166:169], v[182:185], v[118:121]
	v_mfma_f32_16x16x32_bf16 v[114:117], v[174:177], v[182:185], v[114:117]
	v_mfma_f32_16x16x32_bf16 v[102:105], v[166:169], v[190:193], v[102:105]
	v_mfma_f32_16x16x32_bf16 v[98:101], v[174:177], v[190:193], v[98:101]
	v_mfma_f32_16x16x32_bf16 v[86:89], v[166:169], v[198:201], v[86:89]
	v_mfma_f32_16x16x32_bf16 v[82:85], v[174:177], v[198:201], v[82:85]
	v_mfma_f32_16x16x32_bf16 v[70:73], v[166:169], v[206:209], v[70:73]
	v_mfma_f32_16x16x32_bf16 v[66:69], v[174:177], v[206:209], v[66:69]
	s_setprio 0
	s_barrier
	s_add_i32 s64, s87, s73
	v_lshl_add_u64 v[144:145], s[68:69], 0, v[0:1]
	s_mov_b32 m0, s64
	ds_read_b128 v[178:181], v149 offset:16384
	ds_read_b128 v[182:185], v149 offset:17408
	ds_read_b128 v[186:189], v149 offset:18432
	ds_read_b128 v[190:193], v149 offset:19456
	ds_read_b128 v[194:197], v149 offset:20480
	ds_read_b128 v[198:201], v149 offset:21504
	ds_read_b128 v[202:205], v149 offset:22528
	ds_read_b128 v[206:209], v149 offset:23552
	global_load_lds_dwordx4 v[144:145], off
	s_add_i32 m0, s64, 0x2000
	s_add_u32 s64, s68, 0x40000
	v_lshl_add_u64 v[210:211], s[68:69], 0, v[134:135]
	s_addc_u32 s65, s69, 0
	s_add_i32 s87, s88, s73
	global_load_lds_dwordx4 v[210:211], off
	v_lshl_add_u64 v[220:221], s[64:65], 0, v[0:1]
	s_mov_b32 m0, s87
	v_lshl_add_u64 v[224:225], s[70:71], 0, v[134:135]
	global_load_lds_dwordx4 v[220:221], off
	v_lshl_add_u64 v[220:221], s[64:65], 0, v[134:135]
	s_add_i32 m0, s87, 0x2000
	s_nop 0
	global_load_lds_dwordx4 v[220:221], off
	v_lshl_add_u64 v[220:221], s[70:71], 0, v[0:1]
	s_mov_b32 m0, s53
	s_nop 0
	global_load_lds_dwordx4 v[220:221], off
	s_mov_b32 m0, s78
	s_nop 0
	global_load_lds_dwordx4 v[224:225], off
	s_waitcnt vmcnt(8)
	s_waitcnt lgkmcnt(0)
	s_barrier
	s_setprio 3
	s_waitcnt lgkmcnt(0)
	v_mfma_f32_16x16x32_bf16 v[62:65], v[140:143], v[178:181], v[62:65]
	v_mfma_f32_16x16x32_bf16 v[58:61], v[154:157], v[178:181], v[58:61]
	v_mfma_f32_16x16x32_bf16 v[46:49], v[140:143], v[186:189], v[46:49]
	v_mfma_f32_16x16x32_bf16 v[42:45], v[154:157], v[186:189], v[42:45]
	v_mfma_f32_16x16x32_bf16 v[30:33], v[140:143], v[194:197], v[30:33]
	v_mfma_f32_16x16x32_bf16 v[26:29], v[154:157], v[194:197], v[26:29]
	v_mfma_f32_16x16x32_bf16 v[14:17], v[140:143], v[202:205], v[14:17]
	v_mfma_f32_16x16x32_bf16 v[10:13], v[154:157], v[202:205], v[10:13]
	v_mfma_f32_16x16x32_bf16 v[62:65], v[150:153], v[182:185], v[62:65]
	v_mfma_f32_16x16x32_bf16 v[58:61], v[158:161], v[182:185], v[58:61]
	v_mfma_f32_16x16x32_bf16 v[46:49], v[150:153], v[190:193], v[46:49]
	v_mfma_f32_16x16x32_bf16 v[42:45], v[158:161], v[190:193], v[42:45]
	v_mfma_f32_16x16x32_bf16 v[30:33], v[150:153], v[198:201], v[30:33]
	v_mfma_f32_16x16x32_bf16 v[26:29], v[158:161], v[198:201], v[26:29]
	v_mfma_f32_16x16x32_bf16 v[14:17], v[150:153], v[206:209], v[14:17]
	v_mfma_f32_16x16x32_bf16 v[10:13], v[158:161], v[206:209], v[10:13]
	v_mfma_f32_16x16x32_bf16 v[54:57], v[162:165], v[178:181], v[54:57]
	v_mfma_f32_16x16x32_bf16 v[50:53], v[170:173], v[178:181], v[50:53]
	v_mfma_f32_16x16x32_bf16 v[38:41], v[162:165], v[186:189], v[38:41]
	v_mfma_f32_16x16x32_bf16 v[34:37], v[170:173], v[186:189], v[34:37]
	v_mfma_f32_16x16x32_bf16 v[22:25], v[162:165], v[194:197], v[22:25]
	v_mfma_f32_16x16x32_bf16 v[18:21], v[170:173], v[194:197], v[18:21]
	v_mfma_f32_16x16x32_bf16 v[6:9], v[162:165], v[202:205], v[6:9]
	v_mfma_f32_16x16x32_bf16 v[2:5], v[170:173], v[202:205], v[2:5]
	v_mfma_f32_16x16x32_bf16 v[54:57], v[166:169], v[182:185], v[54:57]
	v_mfma_f32_16x16x32_bf16 v[50:53], v[174:177], v[182:185], v[50:53]
	v_mfma_f32_16x16x32_bf16 v[38:41], v[166:169], v[190:193], v[38:41]
	v_mfma_f32_16x16x32_bf16 v[34:37], v[174:177], v[190:193], v[34:37]
	v_mfma_f32_16x16x32_bf16 v[22:25], v[166:169], v[198:201], v[22:25]
	v_mfma_f32_16x16x32_bf16 v[18:21], v[174:177], v[198:201], v[18:21]
	v_mfma_f32_16x16x32_bf16 v[6:9], v[166:169], v[206:209], v[6:9]
	v_mfma_f32_16x16x32_bf16 v[2:5], v[174:177], v[206:209], v[2:5]
	s_setprio 0
	s_barrier
	s_add_i32 s87, 0, 0x18000
	s_add_i32 s88, 0, 0x1c000
	v_add_u32_e32 v158, s87, v147
	v_add_u32_e32 v174, s88, v147
	ds_read_b128 v[140:143], v158
	ds_read_b128 v[150:153], v158 offset:1024
	ds_read_b128 v[154:157], v158 offset:2048
	ds_read_b128 v[158:161], v158 offset:3072
	ds_read_b128 v[162:165], v174
	ds_read_b128 v[166:169], v174 offset:1024
	ds_read_b128 v[170:173], v174 offset:2048
	ds_read_b128 v[174:177], v174 offset:3072
	s_add_u32 s64, s70, 0x40000
	s_addc_u32 s65, s71, 0
	s_mov_b32 m0, s79
	v_lshl_add_u64 v[226:227], s[64:65], 0, v[0:1]
	ds_read_b128 v[178:181], v149 offset:32768
	ds_read_b128 v[182:185], v149 offset:33792
	ds_read_b128 v[186:189], v149 offset:34816
	ds_read_b128 v[190:193], v149 offset:35840
	ds_read_b128 v[194:197], v149 offset:36864
	ds_read_b128 v[198:201], v149 offset:37888
	ds_read_b128 v[202:205], v149 offset:38912
	ds_read_b128 v[206:209], v149 offset:39936
	global_load_lds_dwordx4 v[226:227], off
	v_lshl_add_u64 v[226:227], s[64:65], 0, v[134:135]
	s_mov_b32 m0, s80
	s_nop 0
	global_load_lds_dwordx4 v[226:227], off
	s_waitcnt vmcnt(8)
	s_waitcnt lgkmcnt(0)
	s_barrier
	s_setprio 3
	s_waitcnt lgkmcnt(0)
	v_mfma_f32_16x16x32_bf16 v[126:129], v[140:143], v[178:181], v[126:129]
	v_mfma_f32_16x16x32_bf16 v[122:125], v[154:157], v[178:181], v[122:125]
	v_mfma_f32_16x16x32_bf16 v[110:113], v[140:143], v[186:189], v[110:113]
	v_mfma_f32_16x16x32_bf16 v[106:109], v[154:157], v[186:189], v[106:109]
	v_mfma_f32_16x16x32_bf16 v[94:97], v[140:143], v[194:197], v[94:97]
	v_mfma_f32_16x16x32_bf16 v[90:93], v[154:157], v[194:197], v[90:93]
	v_mfma_f32_16x16x32_bf16 v[78:81], v[140:143], v[202:205], v[78:81]
	v_mfma_f32_16x16x32_bf16 v[74:77], v[154:157], v[202:205], v[74:77]
	v_mfma_f32_16x16x32_bf16 v[126:129], v[150:153], v[182:185], v[126:129]
	v_mfma_f32_16x16x32_bf16 v[122:125], v[158:161], v[182:185], v[122:125]
	v_mfma_f32_16x16x32_bf16 v[110:113], v[150:153], v[190:193], v[110:113]
	v_mfma_f32_16x16x32_bf16 v[106:109], v[158:161], v[190:193], v[106:109]
	v_mfma_f32_16x16x32_bf16 v[94:97], v[150:153], v[198:201], v[94:97]
	v_mfma_f32_16x16x32_bf16 v[90:93], v[158:161], v[198:201], v[90:93]
	v_mfma_f32_16x16x32_bf16 v[78:81], v[150:153], v[206:209], v[78:81]
	v_mfma_f32_16x16x32_bf16 v[74:77], v[158:161], v[206:209], v[74:77]
	v_mfma_f32_16x16x32_bf16 v[118:121], v[162:165], v[178:181], v[118:121]
	v_mfma_f32_16x16x32_bf16 v[114:117], v[170:173], v[178:181], v[114:117]
	v_mfma_f32_16x16x32_bf16 v[102:105], v[162:165], v[186:189], v[102:105]
	v_mfma_f32_16x16x32_bf16 v[98:101], v[170:173], v[186:189], v[98:101]
	v_mfma_f32_16x16x32_bf16 v[86:89], v[162:165], v[194:197], v[86:89]
	v_mfma_f32_16x16x32_bf16 v[82:85], v[170:173], v[194:197], v[82:85]
	v_mfma_f32_16x16x32_bf16 v[70:73], v[162:165], v[202:205], v[70:73]
	v_mfma_f32_16x16x32_bf16 v[66:69], v[170:173], v[202:205], v[66:69]
	v_mfma_f32_16x16x32_bf16 v[118:121], v[166:169], v[182:185], v[118:121]
	v_mfma_f32_16x16x32_bf16 v[114:117], v[174:177], v[182:185], v[114:117]
	v_mfma_f32_16x16x32_bf16 v[102:105], v[166:169], v[190:193], v[102:105]
	v_mfma_f32_16x16x32_bf16 v[98:101], v[174:177], v[190:193], v[98:101]
	v_mfma_f32_16x16x32_bf16 v[86:89], v[166:169], v[198:201], v[86:89]
	v_mfma_f32_16x16x32_bf16 v[82:85], v[174:177], v[198:201], v[82:85]
	v_mfma_f32_16x16x32_bf16 v[70:73], v[166:169], v[206:209], v[70:73]
	v_mfma_f32_16x16x32_bf16 v[66:69], v[174:177], v[206:209], v[66:69]
	s_setprio 0
	s_barrier
	s_add_i32 s64, s87, s73
	v_lshl_add_u64 v[144:145], v[144:145], 0, s[48:49]
	s_mov_b32 m0, s64
	ds_read_b128 v[178:181], v149 offset:49152
	ds_read_b128 v[182:185], v149 offset:50176
	ds_read_b128 v[186:189], v149 offset:51200
	ds_read_b128 v[190:193], v149 offset:52224
	ds_read_b128 v[194:197], v149 offset:53248
	ds_read_b128 v[198:201], v149 offset:54272
	ds_read_b128 v[202:205], v149 offset:55296
	ds_read_b128 v[206:209], v149 offset:56320
	global_load_lds_dwordx4 v[144:145], off
	s_add_i32 m0, s64, 0x2000
	s_add_u32 s64, s68, 0x40080
	v_lshl_add_u64 v[144:145], v[210:211], 0, s[48:49]
	s_addc_u32 s65, s69, 0
	s_add_i32 s68, s88, s73
	global_load_lds_dwordx4 v[144:145], off
	v_lshl_add_u64 v[144:145], s[64:65], 0, v[0:1]
	s_mov_b32 m0, s68
	s_nop 0
	global_load_lds_dwordx4 v[144:145], off
	v_lshl_add_u64 v[144:145], s[64:65], 0, v[134:135]
	s_add_i32 m0, s68, 0x2000
	s_nop 0
	global_load_lds_dwordx4 v[144:145], off
	v_lshl_add_u64 v[144:145], v[220:221], 0, s[48:49]
	s_mov_b32 m0, s81
	s_nop 0
	global_load_lds_dwordx4 v[144:145], off
	v_lshl_add_u64 v[144:145], v[224:225], 0, s[48:49]
	s_mov_b32 m0, s82
	s_nop 0
	global_load_lds_dwordx4 v[144:145], off
	s_waitcnt vmcnt(8)
	s_waitcnt lgkmcnt(0)
	s_barrier
	s_setprio 3
	s_waitcnt lgkmcnt(0)
	v_mfma_f32_16x16x32_bf16 v[62:65], v[140:143], v[178:181], v[62:65]
	v_mfma_f32_16x16x32_bf16 v[58:61], v[154:157], v[178:181], v[58:61]
	v_mfma_f32_16x16x32_bf16 v[46:49], v[140:143], v[186:189], v[46:49]
	v_mfma_f32_16x16x32_bf16 v[42:45], v[154:157], v[186:189], v[42:45]
	v_mfma_f32_16x16x32_bf16 v[30:33], v[140:143], v[194:197], v[30:33]
	v_mfma_f32_16x16x32_bf16 v[26:29], v[154:157], v[194:197], v[26:29]
	v_mfma_f32_16x16x32_bf16 v[14:17], v[140:143], v[202:205], v[14:17]
	v_mfma_f32_16x16x32_bf16 v[10:13], v[154:157], v[202:205], v[10:13]
	v_mfma_f32_16x16x32_bf16 v[62:65], v[150:153], v[182:185], v[62:65]
	v_mfma_f32_16x16x32_bf16 v[58:61], v[158:161], v[182:185], v[58:61]
	v_mfma_f32_16x16x32_bf16 v[46:49], v[150:153], v[190:193], v[46:49]
	v_mfma_f32_16x16x32_bf16 v[42:45], v[158:161], v[190:193], v[42:45]
	v_mfma_f32_16x16x32_bf16 v[30:33], v[150:153], v[198:201], v[30:33]
	v_mfma_f32_16x16x32_bf16 v[26:29], v[158:161], v[198:201], v[26:29]
	v_mfma_f32_16x16x32_bf16 v[14:17], v[150:153], v[206:209], v[14:17]
	v_mfma_f32_16x16x32_bf16 v[10:13], v[158:161], v[206:209], v[10:13]
	v_mfma_f32_16x16x32_bf16 v[54:57], v[162:165], v[178:181], v[54:57]
	v_mfma_f32_16x16x32_bf16 v[50:53], v[170:173], v[178:181], v[50:53]
	v_mfma_f32_16x16x32_bf16 v[38:41], v[162:165], v[186:189], v[38:41]
	v_mfma_f32_16x16x32_bf16 v[34:37], v[170:173], v[186:189], v[34:37]
	v_mfma_f32_16x16x32_bf16 v[22:25], v[162:165], v[194:197], v[22:25]
	v_mfma_f32_16x16x32_bf16 v[18:21], v[170:173], v[194:197], v[18:21]
	v_mfma_f32_16x16x32_bf16 v[6:9], v[162:165], v[202:205], v[6:9]
	v_mfma_f32_16x16x32_bf16 v[2:5], v[170:173], v[202:205], v[2:5]
	v_mfma_f32_16x16x32_bf16 v[54:57], v[166:169], v[182:185], v[54:57]
	v_mfma_f32_16x16x32_bf16 v[50:53], v[174:177], v[182:185], v[50:53]
	v_mfma_f32_16x16x32_bf16 v[38:41], v[166:169], v[190:193], v[38:41]
	v_mfma_f32_16x16x32_bf16 v[34:37], v[174:177], v[190:193], v[34:37]
	v_mfma_f32_16x16x32_bf16 v[22:25], v[166:169], v[198:201], v[22:25]
	v_mfma_f32_16x16x32_bf16 v[18:21], v[174:177], v[198:201], v[18:21]
	v_mfma_f32_16x16x32_bf16 v[6:9], v[166:169], v[206:209], v[6:9]
	v_mfma_f32_16x16x32_bf16 v[2:5], v[174:177], v[206:209], v[2:5]
	s_setprio 0
	s_barrier
	s_add_i32 s86, s86, 2
	s_add_u32 s56, s56, 0x100
	s_addc_u32 s57, s57, 0
	s_add_u32 s31, s31, 0x100
	s_addc_u32 s85, s85, 0
	s_cmp_gt_u32 s86, 13
	s_cbranch_scc0 .LBB0_1603
	s_and_b64 vcc, exec, s[10:11]
	s_cbranch_vccz .LBB0_1606
	s_barrier

.LBB0_1670:
	s_ashr_i32 s11, s12, 3
	s_add_i32 s11, s12, s11
	s_and_b64 s[16:17], s[66:67], s[4:5]
	s_add_i32 s11, s11, 1
	s_and_b64 s[16:17], s[16:17], exec
	s_cselect_b32 s12, s11, s12
	s_ashr_i32 s13, s12, 31
	s_lshl_b64 s[16:17], s[12:13], 19
	s_add_u32 s16, s31, s16
	s_addc_u32 s17, s36, s17
	s_and_b64 s[26:27], s[4:5], exec
	s_cselect_b32 s13, s17, s53
	s_cselect_b32 s79, s16, s52
	s_ashr_i32 s11, s10, 31
	s_lshl_b64 s[26:27], s[10:11], 19
	s_add_u32 s26, s37, s26
	s_addc_u32 s27, s60, s27
	s_and_b64 s[64:65], s[4:5], exec
	s_cselect_b32 s11, s27, s57
	s_cselect_b32 s80, s26, s56
	s_add_u32 s52, s52, 0x40080
	s_addc_u32 s53, s53, 0
	s_add_u32 s81, s56, 0x100
	s_addc_u32 s82, s57, 0
	s_mov_b32 s83, -2
	s_add_u32 s56, s52, 0xfffc0080
	s_addc_u32 s57, s53, -1
	s_add_i32 s64, 0, 0x10000
	s_cmp_eq_u32 s83, 12
	s_cselect_b32 s69, s13, s57
	s_cselect_b32 s68, s79, s56
	v_add_u32_e32 v144, s64, v147
	s_cselect_b32 s57, s11, s82
	s_cselect_b32 s56, s80, s81
	s_add_i32 s84, 0, 0x14000
	ds_read_b128 v[150:153], v144
	ds_read_b128 v[154:157], v144 offset:1024
	ds_read_b128 v[158:161], v144 offset:2048
	ds_read_b128 v[162:165], v144 offset:3072
	v_add_u32_e32 v144, s84, v147
	ds_read_b128 v[166:169], v144
	ds_read_b128 v[170:173], v144 offset:1024
	ds_read_b128 v[174:177], v144 offset:2048
	ds_read_b128 v[178:181], v144 offset:3072
	v_lshl_add_u64 v[144:145], s[52:53], 0, v[140:141]
	s_add_i32 m0, s19, 0xc000
	ds_read_b128 v[182:185], v149
	ds_read_b128 v[186:189], v149 offset:1024
	ds_read_b128 v[190:193], v149 offset:2048
	ds_read_b128 v[194:197], v149 offset:3072
	ds_read_b128 v[198:201], v149 offset:4096
	ds_read_b128 v[202:205], v149 offset:5120
	ds_read_b128 v[206:209], v149 offset:6144
	ds_read_b128 v[224:227], v149 offset:7168
	global_load_lds_dwordx4 v[144:145], off
	v_lshl_add_u64 v[144:145], s[52:53], 0, v[142:143]
	s_add_i32 m0, s19, 0xe000
	s_nop 0
	global_load_lds_dwordx4 v[144:145], off
	s_waitcnt vmcnt(8)
	s_waitcnt lgkmcnt(0)
	s_barrier
	s_setprio 3
	s_waitcnt lgkmcnt(0)
	v_mfma_f32_16x16x32_bf16 v[126:129], v[150:153], v[182:185], 0
	v_mfma_f32_16x16x32_bf16 v[122:125], v[158:161], v[182:185], 0
	v_mfma_f32_16x16x32_bf16 v[118:121], v[150:153], v[190:193], 0
	v_mfma_f32_16x16x32_bf16 v[110:113], v[158:161], v[190:193], 0
	v_mfma_f32_16x16x32_bf16 v[102:105], v[150:153], v[198:201], 0
	v_mfma_f32_16x16x32_bf16 v[94:97], v[158:161], v[198:201], 0
	v_mfma_f32_16x16x32_bf16 v[86:89], v[150:153], v[206:209], 0
	v_mfma_f32_16x16x32_bf16 v[78:81], v[158:161], v[206:209], 0
	v_mfma_f32_16x16x32_bf16 v[126:129], v[154:157], v[186:189], v[126:129]
	v_mfma_f32_16x16x32_bf16 v[122:125], v[162:165], v[186:189], v[122:125]
	v_mfma_f32_16x16x32_bf16 v[118:121], v[154:157], v[194:197], v[118:121]
	v_mfma_f32_16x16x32_bf16 v[110:113], v[162:165], v[194:197], v[110:113]
	v_mfma_f32_16x16x32_bf16 v[102:105], v[154:157], v[202:205], v[102:105]
	v_mfma_f32_16x16x32_bf16 v[94:97], v[162:165], v[202:205], v[94:97]
	v_mfma_f32_16x16x32_bf16 v[86:89], v[154:157], v[224:227], v[86:89]
	v_mfma_f32_16x16x32_bf16 v[78:81], v[162:165], v[224:227], v[78:81]
	v_mfma_f32_16x16x32_bf16 v[114:117], v[166:169], v[182:185], 0
	v_mfma_f32_16x16x32_bf16 v[106:109], v[174:177], v[182:185], 0
	v_mfma_f32_16x16x32_bf16 v[98:101], v[166:169], v[190:193], 0
	v_mfma_f32_16x16x32_bf16 v[90:93], v[174:177], v[190:193], 0
	v_mfma_f32_16x16x32_bf16 v[82:85], v[166:169], v[198:201], 0
	v_mfma_f32_16x16x32_bf16 v[74:77], v[174:177], v[198:201], 0
	v_mfma_f32_16x16x32_bf16 v[70:73], v[166:169], v[206:209], 0
	v_mfma_f32_16x16x32_bf16 v[66:69], v[174:177], v[206:209], 0
	v_mfma_f32_16x16x32_bf16 v[114:117], v[170:173], v[186:189], v[114:117]
	v_mfma_f32_16x16x32_bf16 v[106:109], v[178:181], v[186:189], v[106:109]
	v_mfma_f32_16x16x32_bf16 v[98:101], v[170:173], v[194:197], v[98:101]
	v_mfma_f32_16x16x32_bf16 v[90:93], v[178:181], v[194:197], v[90:93]
	v_mfma_f32_16x16x32_bf16 v[82:85], v[170:173], v[202:205], v[82:85]
	v_mfma_f32_16x16x32_bf16 v[74:77], v[178:181], v[202:205], v[74:77]
	v_mfma_f32_16x16x32_bf16 v[70:73], v[170:173], v[224:227], v[70:73]
	v_mfma_f32_16x16x32_bf16 v[66:69], v[178:181], v[224:227], v[66:69]
	s_setprio 0
	s_barrier
	s_add_i32 s64, s64, s63
	v_lshl_add_u64 v[144:145], s[56:57], 0, v[0:1]
	s_mov_b32 m0, s64
	ds_read_b128 v[182:185], v149 offset:16384
	ds_read_b128 v[186:189], v149 offset:17408
	ds_read_b128 v[190:193], v149 offset:18432
	ds_read_b128 v[194:197], v149 offset:19456
	ds_read_b128 v[198:201], v149 offset:20480
	ds_read_b128 v[202:205], v149 offset:21504
	ds_read_b128 v[206:209], v149 offset:22528
	ds_read_b128 v[224:227], v149 offset:23552
	global_load_lds_dwordx4 v[144:145], off
	s_add_i32 m0, s64, 0x2000
	s_add_u32 s64, s56, 0x40000
	v_lshl_add_u64 v[210:211], s[56:57], 0, v[134:135]
	s_addc_u32 s65, s57, 0
	s_add_i32 s84, s84, s63
	global_load_lds_dwordx4 v[210:211], off
	v_lshl_add_u64 v[220:221], s[64:65], 0, v[0:1]
	s_mov_b32 m0, s84
	v_lshl_add_u64 v[228:229], s[68:69], 0, v[136:137]
	global_load_lds_dwordx4 v[220:221], off
	v_lshl_add_u64 v[220:221], s[64:65], 0, v[134:135]
	s_add_i32 m0, s84, 0x2000
	s_nop 0
	global_load_lds_dwordx4 v[220:221], off
	v_lshl_add_u64 v[220:221], s[68:69], 0, v[138:139]
	s_mov_b32 m0, s19
	s_nop 0
	global_load_lds_dwordx4 v[220:221], off
	s_mov_b32 m0, s21
	s_nop 0
	global_load_lds_dwordx4 v[228:229], off
	s_waitcnt vmcnt(8)
	s_waitcnt lgkmcnt(0)
	s_barrier
	s_setprio 3
	s_waitcnt lgkmcnt(0)
	v_mfma_f32_16x16x32_bf16 v[62:65], v[150:153], v[182:185], 0
	v_mfma_f32_16x16x32_bf16 v[58:61], v[158:161], v[182:185], 0
	v_mfma_f32_16x16x32_bf16 v[54:57], v[150:153], v[190:193], 0
	v_mfma_f32_16x16x32_bf16 v[46:49], v[158:161], v[190:193], 0
	v_mfma_f32_16x16x32_bf16 v[38:41], v[150:153], v[198:201], 0
	v_mfma_f32_16x16x32_bf16 v[30:33], v[158:161], v[198:201], 0
	v_mfma_f32_16x16x32_bf16 v[22:25], v[150:153], v[206:209], 0
	v_mfma_f32_16x16x32_bf16 v[14:17], v[158:161], v[206:209], 0
	v_mfma_f32_16x16x32_bf16 v[62:65], v[154:157], v[186:189], v[62:65]
	v_mfma_f32_16x16x32_bf16 v[58:61], v[162:165], v[186:189], v[58:61]
	v_mfma_f32_16x16x32_bf16 v[54:57], v[154:157], v[194:197], v[54:57]
	v_mfma_f32_16x16x32_bf16 v[46:49], v[162:165], v[194:197], v[46:49]
	v_mfma_f32_16x16x32_bf16 v[38:41], v[154:157], v[202:205], v[38:41]
	v_mfma_f32_16x16x32_bf16 v[30:33], v[162:165], v[202:205], v[30:33]
	v_mfma_f32_16x16x32_bf16 v[22:25], v[154:157], v[224:227], v[22:25]
	v_mfma_f32_16x16x32_bf16 v[14:17], v[162:165], v[224:227], v[14:17]
	v_mfma_f32_16x16x32_bf16 v[50:53], v[166:169], v[182:185], 0
	v_mfma_f32_16x16x32_bf16 v[42:45], v[174:177], v[182:185], 0
	v_mfma_f32_16x16x32_bf16 v[34:37], v[166:169], v[190:193], 0
	v_mfma_f32_16x16x32_bf16 v[26:29], v[174:177], v[190:193], 0
	v_mfma_f32_16x16x32_bf16 v[18:21], v[166:169], v[198:201], 0
	v_mfma_f32_16x16x32_bf16 v[10:13], v[174:177], v[198:201], 0
	v_mfma_f32_16x16x32_bf16 v[6:9], v[166:169], v[206:209], 0
	v_mfma_f32_16x16x32_bf16 v[2:5], v[174:177], v[206:209], 0
	v_mfma_f32_16x16x32_bf16 v[50:53], v[170:173], v[186:189], v[50:53]
	v_mfma_f32_16x16x32_bf16 v[42:45], v[178:181], v[186:189], v[42:45]
	v_mfma_f32_16x16x32_bf16 v[34:37], v[170:173], v[194:197], v[34:37]
	v_mfma_f32_16x16x32_bf16 v[26:29], v[178:181], v[194:197], v[26:29]
	v_mfma_f32_16x16x32_bf16 v[18:21], v[170:173], v[202:205], v[18:21]
	v_mfma_f32_16x16x32_bf16 v[10:13], v[178:181], v[202:205], v[10:13]
	v_mfma_f32_16x16x32_bf16 v[6:9], v[170:173], v[224:227], v[6:9]
	v_mfma_f32_16x16x32_bf16 v[2:5], v[178:181], v[224:227], v[2:5]
	s_setprio 0
	s_barrier
	s_add_i32 s84, 0, 0x18000
	s_add_i32 s85, 0, 0x1c000
	v_add_u32_e32 v162, s84, v147
	v_add_u32_e32 v178, s85, v147
	ds_read_b128 v[150:153], v162
	ds_read_b128 v[154:157], v162 offset:1024
	ds_read_b128 v[158:161], v162 offset:2048
	ds_read_b128 v[162:165], v162 offset:3072
	ds_read_b128 v[166:169], v178
	ds_read_b128 v[170:173], v178 offset:1024
	ds_read_b128 v[174:177], v178 offset:2048
	ds_read_b128 v[178:181], v178 offset:3072
	s_add_u32 s64, s68, 0x40000
	s_addc_u32 s65, s69, 0
	s_mov_b32 m0, s71
	v_lshl_add_u64 v[230:231], s[64:65], 0, v[138:139]
	ds_read_b128 v[182:185], v149 offset:32768
	ds_read_b128 v[186:189], v149 offset:33792
	ds_read_b128 v[190:193], v149 offset:34816
	ds_read_b128 v[194:197], v149 offset:35840
	ds_read_b128 v[198:201], v149 offset:36864
	ds_read_b128 v[202:205], v149 offset:37888
	ds_read_b128 v[206:209], v149 offset:38912
	ds_read_b128 v[224:227], v149 offset:39936
	global_load_lds_dwordx4 v[230:231], off
	v_lshl_add_u64 v[230:231], s[64:65], 0, v[136:137]
	s_mov_b32 m0, s72
	s_nop 0
	global_load_lds_dwordx4 v[230:231], off
	s_waitcnt vmcnt(8)
	s_waitcnt lgkmcnt(0)
	s_barrier
	s_setprio 3
	s_waitcnt lgkmcnt(0)
	v_mfma_f32_16x16x32_bf16 v[126:129], v[150:153], v[182:185], v[126:129]
	v_mfma_f32_16x16x32_bf16 v[122:125], v[158:161], v[182:185], v[122:125]
	v_mfma_f32_16x16x32_bf16 v[118:121], v[150:153], v[190:193], v[118:121]
	v_mfma_f32_16x16x32_bf16 v[110:113], v[158:161], v[190:193], v[110:113]
	v_mfma_f32_16x16x32_bf16 v[102:105], v[150:153], v[198:201], v[102:105]
	v_mfma_f32_16x16x32_bf16 v[94:97], v[158:161], v[198:201], v[94:97]
	v_mfma_f32_16x16x32_bf16 v[86:89], v[150:153], v[206:209], v[86:89]
	v_mfma_f32_16x16x32_bf16 v[78:81], v[158:161], v[206:209], v[78:81]
	v_mfma_f32_16x16x32_bf16 v[126:129], v[154:157], v[186:189], v[126:129]
	v_mfma_f32_16x16x32_bf16 v[122:125], v[162:165], v[186:189], v[122:125]
	v_mfma_f32_16x16x32_bf16 v[118:121], v[154:157], v[194:197], v[118:121]
	v_mfma_f32_16x16x32_bf16 v[110:113], v[162:165], v[194:197], v[110:113]
	v_mfma_f32_16x16x32_bf16 v[102:105], v[154:157], v[202:205], v[102:105]
	v_mfma_f32_16x16x32_bf16 v[94:97], v[162:165], v[202:205], v[94:97]
	v_mfma_f32_16x16x32_bf16 v[86:89], v[154:157], v[224:227], v[86:89]
	v_mfma_f32_16x16x32_bf16 v[78:81], v[162:165], v[224:227], v[78:81]
	v_mfma_f32_16x16x32_bf16 v[114:117], v[166:169], v[182:185], v[114:117]
	v_mfma_f32_16x16x32_bf16 v[106:109], v[174:177], v[182:185], v[106:109]
	v_mfma_f32_16x16x32_bf16 v[98:101], v[166:169], v[190:193], v[98:101]
	v_mfma_f32_16x16x32_bf16 v[90:93], v[174:177], v[190:193], v[90:93]
	v_mfma_f32_16x16x32_bf16 v[82:85], v[166:169], v[198:201], v[82:85]
	v_mfma_f32_16x16x32_bf16 v[74:77], v[174:177], v[198:201], v[74:77]
	v_mfma_f32_16x16x32_bf16 v[70:73], v[166:169], v[206:209], v[70:73]
	v_mfma_f32_16x16x32_bf16 v[66:69], v[174:177], v[206:209], v[66:69]
	v_mfma_f32_16x16x32_bf16 v[114:117], v[170:173], v[186:189], v[114:117]
	v_mfma_f32_16x16x32_bf16 v[106:109], v[178:181], v[186:189], v[106:109]
	v_mfma_f32_16x16x32_bf16 v[98:101], v[170:173], v[194:197], v[98:101]
	v_mfma_f32_16x16x32_bf16 v[90:93], v[178:181], v[194:197], v[90:93]
	v_mfma_f32_16x16x32_bf16 v[82:85], v[170:173], v[202:205], v[82:85]
	v_mfma_f32_16x16x32_bf16 v[74:77], v[178:181], v[202:205], v[74:77]
	v_mfma_f32_16x16x32_bf16 v[70:73], v[170:173], v[224:227], v[70:73]
	v_mfma_f32_16x16x32_bf16 v[66:69], v[178:181], v[224:227], v[66:69]
	s_setprio 0
	s_barrier
	s_add_i32 s64, s84, s63
	v_lshl_add_u64 v[144:145], v[144:145], 0, s[48:49]
	s_mov_b32 m0, s64
	ds_read_b128 v[182:185], v149 offset:49152
	ds_read_b128 v[186:189], v149 offset:50176
	ds_read_b128 v[190:193], v149 offset:51200
	ds_read_b128 v[194:197], v149 offset:52224
	ds_read_b128 v[198:201], v149 offset:53248
	ds_read_b128 v[202:205], v149 offset:54272
	ds_read_b128 v[206:209], v149 offset:55296
	ds_read_b128 v[224:227], v149 offset:56320
	global_load_lds_dwordx4 v[144:145], off
	s_add_i32 m0, s64, 0x2000
	s_add_u32 s56, s56, 0x40080
	v_lshl_add_u64 v[144:145], v[210:211], 0, s[48:49]
	s_addc_u32 s57, s57, 0
	s_add_i32 s64, s85, s63
	global_load_lds_dwordx4 v[144:145], off
	v_lshl_add_u64 v[144:145], s[56:57], 0, v[0:1]
	s_mov_b32 m0, s64
	s_nop 0
	global_load_lds_dwordx4 v[144:145], off
	v_lshl_add_u64 v[144:145], s[56:57], 0, v[134:135]
	s_add_i32 m0, s64, 0x2000
	s_nop 0
	global_load_lds_dwordx4 v[144:145], off
	v_lshl_add_u64 v[144:145], v[220:221], 0, s[48:49]
	s_mov_b32 m0, s73
	s_nop 0
	global_load_lds_dwordx4 v[144:145], off
	v_lshl_add_u64 v[144:145], v[228:229], 0, s[48:49]
	s_mov_b32 m0, s74
	s_nop 0
	global_load_lds_dwordx4 v[144:145], off
	s_waitcnt vmcnt(8)
	s_waitcnt lgkmcnt(0)
	s_barrier
	s_setprio 3
	s_waitcnt lgkmcnt(0)
	v_mfma_f32_16x16x32_bf16 v[62:65], v[150:153], v[182:185], v[62:65]
	v_mfma_f32_16x16x32_bf16 v[58:61], v[158:161], v[182:185], v[58:61]
	v_mfma_f32_16x16x32_bf16 v[54:57], v[150:153], v[190:193], v[54:57]
	v_mfma_f32_16x16x32_bf16 v[46:49], v[158:161], v[190:193], v[46:49]
	v_mfma_f32_16x16x32_bf16 v[38:41], v[150:153], v[198:201], v[38:41]
	v_mfma_f32_16x16x32_bf16 v[30:33], v[158:161], v[198:201], v[30:33]
	v_mfma_f32_16x16x32_bf16 v[22:25], v[150:153], v[206:209], v[22:25]
	v_mfma_f32_16x16x32_bf16 v[14:17], v[158:161], v[206:209], v[14:17]
	v_mfma_f32_16x16x32_bf16 v[62:65], v[154:157], v[186:189], v[62:65]
	v_mfma_f32_16x16x32_bf16 v[58:61], v[162:165], v[186:189], v[58:61]
	v_mfma_f32_16x16x32_bf16 v[54:57], v[154:157], v[194:197], v[54:57]
	v_mfma_f32_16x16x32_bf16 v[46:49], v[162:165], v[194:197], v[46:49]
	v_mfma_f32_16x16x32_bf16 v[38:41], v[154:157], v[202:205], v[38:41]
	v_mfma_f32_16x16x32_bf16 v[30:33], v[162:165], v[202:205], v[30:33]
	v_mfma_f32_16x16x32_bf16 v[22:25], v[154:157], v[224:227], v[22:25]
	v_mfma_f32_16x16x32_bf16 v[14:17], v[162:165], v[224:227], v[14:17]
	v_mfma_f32_16x16x32_bf16 v[50:53], v[166:169], v[182:185], v[50:53]
	v_mfma_f32_16x16x32_bf16 v[42:45], v[174:177], v[182:185], v[42:45]
	v_mfma_f32_16x16x32_bf16 v[34:37], v[166:169], v[190:193], v[34:37]
	v_mfma_f32_16x16x32_bf16 v[26:29], v[174:177], v[190:193], v[26:29]
	v_mfma_f32_16x16x32_bf16 v[18:21], v[166:169], v[198:201], v[18:21]
	v_mfma_f32_16x16x32_bf16 v[10:13], v[174:177], v[198:201], v[10:13]
	v_mfma_f32_16x16x32_bf16 v[6:9], v[166:169], v[206:209], v[6:9]
	v_mfma_f32_16x16x32_bf16 v[2:5], v[174:177], v[206:209], v[2:5]
	v_mfma_f32_16x16x32_bf16 v[50:53], v[170:173], v[186:189], v[50:53]
	v_mfma_f32_16x16x32_bf16 v[42:45], v[178:181], v[186:189], v[42:45]
	v_mfma_f32_16x16x32_bf16 v[34:37], v[170:173], v[194:197], v[34:37]
	v_mfma_f32_16x16x32_bf16 v[26:29], v[178:181], v[194:197], v[26:29]
	v_mfma_f32_16x16x32_bf16 v[18:21], v[170:173], v[202:205], v[18:21]
	v_mfma_f32_16x16x32_bf16 v[10:13], v[178:181], v[202:205], v[10:13]
	v_mfma_f32_16x16x32_bf16 v[6:9], v[170:173], v[224:227], v[6:9]
	v_mfma_f32_16x16x32_bf16 v[2:5], v[178:181], v[224:227], v[2:5]
	s_setprio 0
	s_barrier
	s_add_i32 s83, s83, 2
	s_add_u32 s52, s52, 0x100
	s_addc_u32 s53, s53, 0
	s_add_u32 s81, s81, 0x100
	s_addc_u32 s82, s82, 0
.LBB0_1671:
	s_add_u32 s56, s52, 0xfffc0080
	s_addc_u32 s57, s53, -1
	s_add_i32 s64, 0, 0x10000
	s_cmp_eq_u32 s83, 12
	s_cselect_b32 s69, s13, s57
	s_cselect_b32 s68, s79, s56
	v_add_u32_e32 v144, s64, v147
	s_cselect_b32 s57, s11, s82
	s_cselect_b32 s56, s80, s81
	s_add_i32 s84, 0, 0x14000
	ds_read_b128 v[150:153], v144
	ds_read_b128 v[154:157], v144 offset:1024
	ds_read_b128 v[158:161], v144 offset:2048
	ds_read_b128 v[162:165], v144 offset:3072
	v_add_u32_e32 v144, s84, v147
	ds_read_b128 v[166:169], v144
	ds_read_b128 v[170:173], v144 offset:1024
	ds_read_b128 v[174:177], v144 offset:2048
	ds_read_b128 v[178:181], v144 offset:3072
	v_lshl_add_u64 v[144:145], s[52:53], 0, v[140:141]
	s_add_i32 m0, s19, 0xc000
	ds_read_b128 v[182:185], v149
	ds_read_b128 v[186:189], v149 offset:1024
	ds_read_b128 v[190:193], v149 offset:2048
	ds_read_b128 v[194:197], v149 offset:3072
	ds_read_b128 v[198:201], v149 offset:4096
	ds_read_b128 v[202:205], v149 offset:5120
	ds_read_b128 v[206:209], v149 offset:6144
	ds_read_b128 v[224:227], v149 offset:7168
	global_load_lds_dwordx4 v[144:145], off
	v_lshl_add_u64 v[144:145], s[52:53], 0, v[142:143]
	s_add_i32 m0, s19, 0xe000
	s_nop 0
	global_load_lds_dwordx4 v[144:145], off
	s_waitcnt vmcnt(8)
	s_waitcnt lgkmcnt(0)
	s_barrier
	s_setprio 3
	s_waitcnt lgkmcnt(0)
	v_mfma_f32_16x16x32_bf16 v[126:129], v[150:153], v[182:185], v[126:129]
	v_mfma_f32_16x16x32_bf16 v[122:125], v[158:161], v[182:185], v[122:125]
	v_mfma_f32_16x16x32_bf16 v[118:121], v[150:153], v[190:193], v[118:121]
	v_mfma_f32_16x16x32_bf16 v[110:113], v[158:161], v[190:193], v[110:113]
	v_mfma_f32_16x16x32_bf16 v[102:105], v[150:153], v[198:201], v[102:105]
	v_mfma_f32_16x16x32_bf16 v[94:97], v[158:161], v[198:201], v[94:97]
	v_mfma_f32_16x16x32_bf16 v[86:89], v[150:153], v[206:209], v[86:89]
	v_mfma_f32_16x16x32_bf16 v[78:81], v[158:161], v[206:209], v[78:81]
	v_mfma_f32_16x16x32_bf16 v[126:129], v[154:157], v[186:189], v[126:129]
	v_mfma_f32_16x16x32_bf16 v[122:125], v[162:165], v[186:189], v[122:125]
	v_mfma_f32_16x16x32_bf16 v[118:121], v[154:157], v[194:197], v[118:121]
	v_mfma_f32_16x16x32_bf16 v[110:113], v[162:165], v[194:197], v[110:113]
	v_mfma_f32_16x16x32_bf16 v[102:105], v[154:157], v[202:205], v[102:105]
	v_mfma_f32_16x16x32_bf16 v[94:97], v[162:165], v[202:205], v[94:97]
	v_mfma_f32_16x16x32_bf16 v[86:89], v[154:157], v[224:227], v[86:89]
	v_mfma_f32_16x16x32_bf16 v[78:81], v[162:165], v[224:227], v[78:81]
	v_mfma_f32_16x16x32_bf16 v[114:117], v[166:169], v[182:185], v[114:117]
	v_mfma_f32_16x16x32_bf16 v[106:109], v[174:177], v[182:185], v[106:109]
	v_mfma_f32_16x16x32_bf16 v[98:101], v[166:169], v[190:193], v[98:101]
	v_mfma_f32_16x16x32_bf16 v[90:93], v[174:177], v[190:193], v[90:93]
	v_mfma_f32_16x16x32_bf16 v[82:85], v[166:169], v[198:201], v[82:85]
	v_mfma_f32_16x16x32_bf16 v[74:77], v[174:177], v[198:201], v[74:77]
	v_mfma_f32_16x16x32_bf16 v[70:73], v[166:169], v[206:209], v[70:73]
	v_mfma_f32_16x16x32_bf16 v[66:69], v[174:177], v[206:209], v[66:69]
	v_mfma_f32_16x16x32_bf16 v[114:117], v[170:173], v[186:189], v[114:117]
	v_mfma_f32_16x16x32_bf16 v[106:109], v[178:181], v[186:189], v[106:109]
	v_mfma_f32_16x16x32_bf16 v[98:101], v[170:173], v[194:197], v[98:101]
	v_mfma_f32_16x16x32_bf16 v[90:93], v[178:181], v[194:197], v[90:93]
	v_mfma_f32_16x16x32_bf16 v[82:85], v[170:173], v[202:205], v[82:85]
	v_mfma_f32_16x16x32_bf16 v[74:77], v[178:181], v[202:205], v[74:77]
	v_mfma_f32_16x16x32_bf16 v[70:73], v[170:173], v[224:227], v[70:73]
	v_mfma_f32_16x16x32_bf16 v[66:69], v[178:181], v[224:227], v[66:69]
	s_setprio 0
	s_barrier
	s_add_i32 s64, s64, s63
	v_lshl_add_u64 v[144:145], s[56:57], 0, v[0:1]
	s_mov_b32 m0, s64
	ds_read_b128 v[182:185], v149 offset:16384
	ds_read_b128 v[186:189], v149 offset:17408
	ds_read_b128 v[190:193], v149 offset:18432
	ds_read_b128 v[194:197], v149 offset:19456
	ds_read_b128 v[198:201], v149 offset:20480
	ds_read_b128 v[202:205], v149 offset:21504
	ds_read_b128 v[206:209], v149 offset:22528
	ds_read_b128 v[224:227], v149 offset:23552
	global_load_lds_dwordx4 v[144:145], off
	s_add_i32 m0, s64, 0x2000
	s_add_u32 s64, s56, 0x40000
	v_lshl_add_u64 v[210:211], s[56:57], 0, v[134:135]
	s_addc_u32 s65, s57, 0
	s_add_i32 s84, s84, s63
	global_load_lds_dwordx4 v[210:211], off
	v_lshl_add_u64 v[220:221], s[64:65], 0, v[0:1]
	s_mov_b32 m0, s84
	v_lshl_add_u64 v[228:229], s[68:69], 0, v[136:137]
	global_load_lds_dwordx4 v[220:221], off
	v_lshl_add_u64 v[220:221], s[64:65], 0, v[134:135]
	s_add_i32 m0, s84, 0x2000
	s_nop 0
	global_load_lds_dwordx4 v[220:221], off
	v_lshl_add_u64 v[220:221], s[68:69], 0, v[138:139]
	s_mov_b32 m0, s19
	s_nop 0
	global_load_lds_dwordx4 v[220:221], off
	s_mov_b32 m0, s21
	s_nop 0
	global_load_lds_dwordx4 v[228:229], off
	s_waitcnt vmcnt(8)
	s_waitcnt lgkmcnt(0)
	s_barrier
	s_setprio 3
	s_waitcnt lgkmcnt(0)
	v_mfma_f32_16x16x32_bf16 v[62:65], v[150:153], v[182:185], v[62:65]
	v_mfma_f32_16x16x32_bf16 v[58:61], v[158:161], v[182:185], v[58:61]
	v_mfma_f32_16x16x32_bf16 v[54:57], v[150:153], v[190:193], v[54:57]
	v_mfma_f32_16x16x32_bf16 v[46:49], v[158:161], v[190:193], v[46:49]
	v_mfma_f32_16x16x32_bf16 v[38:41], v[150:153], v[198:201], v[38:41]
	v_mfma_f32_16x16x32_bf16 v[30:33], v[158:161], v[198:201], v[30:33]
	v_mfma_f32_16x16x32_bf16 v[22:25], v[150:153], v[206:209], v[22:25]
	v_mfma_f32_16x16x32_bf16 v[14:17], v[158:161], v[206:209], v[14:17]
	v_mfma_f32_16x16x32_bf16 v[62:65], v[154:157], v[186:189], v[62:65]
	v_mfma_f32_16x16x32_bf16 v[58:61], v[162:165], v[186:189], v[58:61]
	v_mfma_f32_16x16x32_bf16 v[54:57], v[154:157], v[194:197], v[54:57]
	v_mfma_f32_16x16x32_bf16 v[46:49], v[162:165], v[194:197], v[46:49]
	v_mfma_f32_16x16x32_bf16 v[38:41], v[154:157], v[202:205], v[38:41]
	v_mfma_f32_16x16x32_bf16 v[30:33], v[162:165], v[202:205], v[30:33]
	v_mfma_f32_16x16x32_bf16 v[22:25], v[154:157], v[224:227], v[22:25]
	v_mfma_f32_16x16x32_bf16 v[14:17], v[162:165], v[224:227], v[14:17]
	v_mfma_f32_16x16x32_bf16 v[50:53], v[166:169], v[182:185], v[50:53]
	v_mfma_f32_16x16x32_bf16 v[42:45], v[174:177], v[182:185], v[42:45]
	v_mfma_f32_16x16x32_bf16 v[34:37], v[166:169], v[190:193], v[34:37]
	v_mfma_f32_16x16x32_bf16 v[26:29], v[174:177], v[190:193], v[26:29]
	v_mfma_f32_16x16x32_bf16 v[18:21], v[166:169], v[198:201], v[18:21]
	v_mfma_f32_16x16x32_bf16 v[10:13], v[174:177], v[198:201], v[10:13]
	v_mfma_f32_16x16x32_bf16 v[6:9], v[166:169], v[206:209], v[6:9]
	v_mfma_f32_16x16x32_bf16 v[2:5], v[174:177], v[206:209], v[2:5]
	v_mfma_f32_16x16x32_bf16 v[50:53], v[170:173], v[186:189], v[50:53]
	v_mfma_f32_16x16x32_bf16 v[42:45], v[178:181], v[186:189], v[42:45]
	v_mfma_f32_16x16x32_bf16 v[34:37], v[170:173], v[194:197], v[34:37]
	v_mfma_f32_16x16x32_bf16 v[26:29], v[178:181], v[194:197], v[26:29]
	v_mfma_f32_16x16x32_bf16 v[18:21], v[170:173], v[202:205], v[18:21]
	v_mfma_f32_16x16x32_bf16 v[10:13], v[178:181], v[202:205], v[10:13]
	v_mfma_f32_16x16x32_bf16 v[6:9], v[170:173], v[224:227], v[6:9]
	v_mfma_f32_16x16x32_bf16 v[2:5], v[178:181], v[224:227], v[2:5]
	s_setprio 0
	s_barrier
	s_add_i32 s84, 0, 0x18000
	s_add_i32 s85, 0, 0x1c000
	v_add_u32_e32 v162, s84, v147
	v_add_u32_e32 v178, s85, v147
	ds_read_b128 v[150:153], v162
	ds_read_b128 v[154:157], v162 offset:1024
	ds_read_b128 v[158:161], v162 offset:2048
	ds_read_b128 v[162:165], v162 offset:3072
	ds_read_b128 v[166:169], v178
	ds_read_b128 v[170:173], v178 offset:1024
	ds_read_b128 v[174:177], v178 offset:2048
	ds_read_b128 v[178:181], v178 offset:3072
	s_add_u32 s64, s68, 0x40000
	s_addc_u32 s65, s69, 0
	s_mov_b32 m0, s71
	v_lshl_add_u64 v[230:231], s[64:65], 0, v[138:139]
	ds_read_b128 v[182:185], v149 offset:32768
	ds_read_b128 v[186:189], v149 offset:33792
	ds_read_b128 v[190:193], v149 offset:34816
	ds_read_b128 v[194:197], v149 offset:35840
	ds_read_b128 v[198:201], v149 offset:36864
	ds_read_b128 v[202:205], v149 offset:37888
	ds_read_b128 v[206:209], v149 offset:38912
	ds_read_b128 v[224:227], v149 offset:39936
	global_load_lds_dwordx4 v[230:231], off
	v_lshl_add_u64 v[230:231], s[64:65], 0, v[136:137]
	s_mov_b32 m0, s72
	s_nop 0
	global_load_lds_dwordx4 v[230:231], off
	s_waitcnt vmcnt(8)
	s_waitcnt lgkmcnt(0)
	s_barrier
	s_setprio 3
	s_waitcnt lgkmcnt(0)
	v_mfma_f32_16x16x32_bf16 v[126:129], v[150:153], v[182:185], v[126:129]
	v_mfma_f32_16x16x32_bf16 v[122:125], v[158:161], v[182:185], v[122:125]
	v_mfma_f32_16x16x32_bf16 v[118:121], v[150:153], v[190:193], v[118:121]
	v_mfma_f32_16x16x32_bf16 v[110:113], v[158:161], v[190:193], v[110:113]
	v_mfma_f32_16x16x32_bf16 v[102:105], v[150:153], v[198:201], v[102:105]
	v_mfma_f32_16x16x32_bf16 v[94:97], v[158:161], v[198:201], v[94:97]
	v_mfma_f32_16x16x32_bf16 v[86:89], v[150:153], v[206:209], v[86:89]
	v_mfma_f32_16x16x32_bf16 v[78:81], v[158:161], v[206:209], v[78:81]
	v_mfma_f32_16x16x32_bf16 v[126:129], v[154:157], v[186:189], v[126:129]
	v_mfma_f32_16x16x32_bf16 v[122:125], v[162:165], v[186:189], v[122:125]
	v_mfma_f32_16x16x32_bf16 v[118:121], v[154:157], v[194:197], v[118:121]
	v_mfma_f32_16x16x32_bf16 v[110:113], v[162:165], v[194:197], v[110:113]
	v_mfma_f32_16x16x32_bf16 v[102:105], v[154:157], v[202:205], v[102:105]
	v_mfma_f32_16x16x32_bf16 v[94:97], v[162:165], v[202:205], v[94:97]
	v_mfma_f32_16x16x32_bf16 v[86:89], v[154:157], v[224:227], v[86:89]
	v_mfma_f32_16x16x32_bf16 v[78:81], v[162:165], v[224:227], v[78:81]
	v_mfma_f32_16x16x32_bf16 v[114:117], v[166:169], v[182:185], v[114:117]
	v_mfma_f32_16x16x32_bf16 v[106:109], v[174:177], v[182:185], v[106:109]
	v_mfma_f32_16x16x32_bf16 v[98:101], v[166:169], v[190:193], v[98:101]
	v_mfma_f32_16x16x32_bf16 v[90:93], v[174:177], v[190:193], v[90:93]
	v_mfma_f32_16x16x32_bf16 v[82:85], v[166:169], v[198:201], v[82:85]
	v_mfma_f32_16x16x32_bf16 v[74:77], v[174:177], v[198:201], v[74:77]
	v_mfma_f32_16x16x32_bf16 v[70:73], v[166:169], v[206:209], v[70:73]
	v_mfma_f32_16x16x32_bf16 v[66:69], v[174:177], v[206:209], v[66:69]
	v_mfma_f32_16x16x32_bf16 v[114:117], v[170:173], v[186:189], v[114:117]
	v_mfma_f32_16x16x32_bf16 v[106:109], v[178:181], v[186:189], v[106:109]
	v_mfma_f32_16x16x32_bf16 v[98:101], v[170:173], v[194:197], v[98:101]
	v_mfma_f32_16x16x32_bf16 v[90:93], v[178:181], v[194:197], v[90:93]
	v_mfma_f32_16x16x32_bf16 v[82:85], v[170:173], v[202:205], v[82:85]
	v_mfma_f32_16x16x32_bf16 v[74:77], v[178:181], v[202:205], v[74:77]
	v_mfma_f32_16x16x32_bf16 v[70:73], v[170:173], v[224:227], v[70:73]
	v_mfma_f32_16x16x32_bf16 v[66:69], v[178:181], v[224:227], v[66:69]
	s_setprio 0
	s_barrier
	s_add_i32 s64, s84, s63
	v_lshl_add_u64 v[144:145], v[144:145], 0, s[48:49]
	s_mov_b32 m0, s64
	ds_read_b128 v[182:185], v149 offset:49152
	ds_read_b128 v[186:189], v149 offset:50176
	ds_read_b128 v[190:193], v149 offset:51200
	ds_read_b128 v[194:197], v149 offset:52224
	ds_read_b128 v[198:201], v149 offset:53248
	ds_read_b128 v[202:205], v149 offset:54272
	ds_read_b128 v[206:209], v149 offset:55296
	ds_read_b128 v[224:227], v149 offset:56320
	global_load_lds_dwordx4 v[144:145], off
	s_add_i32 m0, s64, 0x2000
	s_add_u32 s56, s56, 0x40080
	v_lshl_add_u64 v[144:145], v[210:211], 0, s[48:49]
	s_addc_u32 s57, s57, 0
	s_add_i32 s64, s85, s63
	global_load_lds_dwordx4 v[144:145], off
	v_lshl_add_u64 v[144:145], s[56:57], 0, v[0:1]
	s_mov_b32 m0, s64
	s_nop 0
	global_load_lds_dwordx4 v[144:145], off
	v_lshl_add_u64 v[144:145], s[56:57], 0, v[134:135]
	s_add_i32 m0, s64, 0x2000
	s_nop 0
	global_load_lds_dwordx4 v[144:145], off
	v_lshl_add_u64 v[144:145], v[220:221], 0, s[48:49]
	s_mov_b32 m0, s73
	s_nop 0
	global_load_lds_dwordx4 v[144:145], off
	v_lshl_add_u64 v[144:145], v[228:229], 0, s[48:49]
	s_mov_b32 m0, s74
	s_nop 0
	global_load_lds_dwordx4 v[144:145], off
	s_waitcnt vmcnt(8)
	s_waitcnt lgkmcnt(0)
	s_barrier
	s_setprio 3
	s_waitcnt lgkmcnt(0)
	v_mfma_f32_16x16x32_bf16 v[62:65], v[150:153], v[182:185], v[62:65]
	v_mfma_f32_16x16x32_bf16 v[58:61], v[158:161], v[182:185], v[58:61]
	v_mfma_f32_16x16x32_bf16 v[54:57], v[150:153], v[190:193], v[54:57]
	v_mfma_f32_16x16x32_bf16 v[46:49], v[158:161], v[190:193], v[46:49]
	v_mfma_f32_16x16x32_bf16 v[38:41], v[150:153], v[198:201], v[38:41]
	v_mfma_f32_16x16x32_bf16 v[30:33], v[158:161], v[198:201], v[30:33]
	v_mfma_f32_16x16x32_bf16 v[22:25], v[150:153], v[206:209], v[22:25]
	v_mfma_f32_16x16x32_bf16 v[14:17], v[158:161], v[206:209], v[14:17]
	v_mfma_f32_16x16x32_bf16 v[62:65], v[154:157], v[186:189], v[62:65]
	v_mfma_f32_16x16x32_bf16 v[58:61], v[162:165], v[186:189], v[58:61]
	v_mfma_f32_16x16x32_bf16 v[54:57], v[154:157], v[194:197], v[54:57]
	v_mfma_f32_16x16x32_bf16 v[46:49], v[162:165], v[194:197], v[46:49]
	v_mfma_f32_16x16x32_bf16 v[38:41], v[154:157], v[202:205], v[38:41]
	v_mfma_f32_16x16x32_bf16 v[30:33], v[162:165], v[202:205], v[30:33]
	v_mfma_f32_16x16x32_bf16 v[22:25], v[154:157], v[224:227], v[22:25]
	v_mfma_f32_16x16x32_bf16 v[14:17], v[162:165], v[224:227], v[14:17]
	v_mfma_f32_16x16x32_bf16 v[50:53], v[166:169], v[182:185], v[50:53]
	v_mfma_f32_16x16x32_bf16 v[42:45], v[174:177], v[182:185], v[42:45]
	v_mfma_f32_16x16x32_bf16 v[34:37], v[166:169], v[190:193], v[34:37]
	v_mfma_f32_16x16x32_bf16 v[26:29], v[174:177], v[190:193], v[26:29]
	v_mfma_f32_16x16x32_bf16 v[18:21], v[166:169], v[198:201], v[18:21]
	v_mfma_f32_16x16x32_bf16 v[10:13], v[174:177], v[198:201], v[10:13]
	v_mfma_f32_16x16x32_bf16 v[6:9], v[166:169], v[206:209], v[6:9]
	v_mfma_f32_16x16x32_bf16 v[2:5], v[174:177], v[206:209], v[2:5]
	v_mfma_f32_16x16x32_bf16 v[50:53], v[170:173], v[186:189], v[50:53]
	v_mfma_f32_16x16x32_bf16 v[42:45], v[178:181], v[186:189], v[42:45]
	v_mfma_f32_16x16x32_bf16 v[34:37], v[170:173], v[194:197], v[34:37]
	v_mfma_f32_16x16x32_bf16 v[26:29], v[178:181], v[194:197], v[26:29]
	v_mfma_f32_16x16x32_bf16 v[18:21], v[170:173], v[202:205], v[18:21]
	v_mfma_f32_16x16x32_bf16 v[10:13], v[178:181], v[202:205], v[10:13]
	v_mfma_f32_16x16x32_bf16 v[6:9], v[170:173], v[224:227], v[6:9]
	v_mfma_f32_16x16x32_bf16 v[2:5], v[178:181], v[224:227], v[2:5]
	s_setprio 0
	s_barrier
	s_add_i32 s83, s83, 2
	s_add_u32 s52, s52, 0x100
	s_addc_u32 s53, s53, 0
	s_add_u32 s81, s81, 0x100
	s_addc_u32 s82, s82, 0
	s_cmp_gt_u32 s83, 13
	s_cbranch_scc0 .LBB0_1671
	s_and_b64 vcc, exec, s[8:9]
	s_cbranch_vccnz .LBB0_1675
	s_cmp_gt_i32 s18, 15
	s_cbranch_scc0 .LBB0_1676
